# trailing half's per-unit re-offset barrier taken after the next-unit scheduling arithmetic and accumulator zeroing, right in front of the K-loop
# baseline (speedup 1.0000x reference)
.LBB0_132:
	s_ashr_i32 s25, s24, 31
	s_lshl_b64 s[28:29], s[24:25], 20
	v_readlane_b32 s25, v254, 62
	s_add_u32 s28, s25, s28
	v_readlane_b32 s25, v254, 63
	s_addc_u32 s29, s25, s29
	s_and_b64 s[4:5], s[4:5], exec
	s_cselect_b32 s25, s29, s31
	s_cselect_b32 s37, s28, s30
	s_add_u32 s50, s30, 0x100
	v_mov_b64_e32 v[8:9], v[4:5]
	v_mov_b64_e32 v[20:21], v[4:5]
	v_mov_b64_e32 v[24:25], v[4:5]
	v_mov_b64_e32 v[36:37], v[4:5]
	v_mov_b64_e32 v[40:41], v[4:5]
	v_mov_b64_e32 v[52:53], v[4:5]
	v_mov_b64_e32 v[56:57], v[4:5]
	v_mov_b64_e32 v[12:13], v[4:5]
	v_mov_b64_e32 v[16:17], v[4:5]
	v_mov_b64_e32 v[28:29], v[4:5]
	v_mov_b64_e32 v[32:33], v[4:5]
	v_mov_b64_e32 v[44:45], v[4:5]
	v_mov_b64_e32 v[48:49], v[4:5]
	v_mov_b64_e32 v[60:61], v[4:5]
	v_mov_b64_e32 v[64:65], v[4:5]
	v_mov_b64_e32 v[68:69], v[4:5]
	v_mov_b64_e32 v[72:73], v[4:5]
	v_mov_b64_e32 v[84:85], v[4:5]
	v_mov_b64_e32 v[88:89], v[4:5]
	v_mov_b64_e32 v[100:101], v[4:5]
	v_mov_b64_e32 v[104:105], v[4:5]
	v_mov_b64_e32 v[116:117], v[4:5]
	v_mov_b64_e32 v[120:121], v[4:5]
	v_mov_b64_e32 v[76:77], v[4:5]
	v_mov_b64_e32 v[80:81], v[4:5]
	v_mov_b64_e32 v[92:93], v[4:5]
	v_mov_b64_e32 v[96:97], v[4:5]
	v_mov_b64_e32 v[108:109], v[4:5]
	v_mov_b64_e32 v[112:113], v[4:5]
	v_mov_b64_e32 v[124:125], v[4:5]
	v_mov_b64_e32 v[128:129], v[4:5]
	s_addc_u32 s51, s31, 0
	s_mov_b32 s57, -2
	v_mov_b64_e32 v[6:7], v[2:3]
	v_mov_b64_e32 v[18:19], v[2:3]
	v_mov_b64_e32 v[22:23], v[2:3]
	v_mov_b64_e32 v[34:35], v[2:3]
	v_mov_b64_e32 v[38:39], v[2:3]
	v_mov_b64_e32 v[50:51], v[2:3]
	v_mov_b64_e32 v[54:55], v[2:3]
	v_mov_b64_e32 v[10:11], v[2:3]
	v_mov_b64_e32 v[14:15], v[2:3]
	v_mov_b64_e32 v[26:27], v[2:3]
	v_mov_b64_e32 v[30:31], v[2:3]
	v_mov_b64_e32 v[42:43], v[2:3]
	v_mov_b64_e32 v[46:47], v[2:3]
	v_mov_b64_e32 v[58:59], v[2:3]
	v_mov_b64_e32 v[62:63], v[2:3]
	v_mov_b64_e32 v[66:67], v[2:3]
	v_mov_b64_e32 v[70:71], v[2:3]
	v_mov_b64_e32 v[82:83], v[2:3]
	v_mov_b64_e32 v[86:87], v[2:3]
	v_mov_b64_e32 v[98:99], v[2:3]
	v_mov_b64_e32 v[102:103], v[2:3]
	v_mov_b64_e32 v[114:115], v[2:3]
	v_mov_b64_e32 v[118:119], v[2:3]
	v_mov_b64_e32 v[74:75], v[2:3]
	v_mov_b64_e32 v[78:79], v[2:3]
	v_mov_b64_e32 v[90:91], v[2:3]
	v_mov_b64_e32 v[94:95], v[2:3]
	v_mov_b64_e32 v[106:107], v[2:3]
	v_mov_b64_e32 v[110:111], v[2:3]
	v_mov_b64_e32 v[122:123], v[2:3]
	v_mov_b64_e32 v[126:127], v[2:3]
	s_cmp_eq_u32 s33, 0
	s_cbranch_scc1 .Lrealign_0
	s_andn2_b64 vcc, exec, s[12:13]
	s_cbranch_vccnz .Lrealign_0
	s_barrier
.Lrealign_0:
.LBB0_133:
	s_add_u32 vcc_lo, s0, 0xffffc000
	s_addc_u32 vcc_hi, s1, -1
	s_mov_b32 m0, s52
	s_nop 0
	global_load_lds_dwordx4 v158, vcc
	s_mov_b32 m0, s53
	s_nop 0
	global_load_lds_dwordx4 v160, vcc
	ds_read_b128 v[130:133], v224
	ds_read_b128 v[134:137], v224 offset:1024
	ds_read_b128 v[138:141], v224 offset:2048
	ds_read_b128 v[142:145], v224 offset:3072
	ds_read_b128 v[146:149], v224 offset:16384
	ds_read_b128 v[162:165], v224 offset:17408
	ds_read_b128 v[166:169], v224 offset:18432
	ds_read_b128 v[170:173], v224 offset:19456
	ds_read_b128 v[174:177], v225
	ds_read_b128 v[178:181], v225 offset:1024
	ds_read_b128 v[182:185], v225 offset:2048
	ds_read_b128 v[186:189], v225 offset:3072
	ds_read_b128 v[190:193], v225 offset:4096
	ds_read_b128 v[204:207], v225 offset:5120
	ds_read_b128 v[208:211], v225 offset:6144
	ds_read_b128 v[212:215], v225 offset:7168
	s_add_u32 s4, s0, 0x100
	s_addc_u32 s5, s1, 0
	s_add_i32 s58, 0, 0x10000
	s_cmp_eq_u32 s57, 28
	s_cselect_b32 s35, s27, s5
	s_cselect_b32 s34, s26, s4
	s_cselect_b32 s31, s25, s51
	s_cselect_b32 s30, s37, s50
	s_add_i32 s59, 0, 0x14000
	s_add_i32 m0, s38, 0xc000
	s_nop 0
	global_load_lds_dwordx4 v158, s[0:1]
	s_add_i32 m0, s38, 0xe000
	s_nop 0
	global_load_lds_dwordx4 v160, s[0:1]
	s_waitcnt vmcnt(8)
	s_waitcnt lgkmcnt(0)
	v_mfma_f32_16x16x32_bf16 v[126:129], v[130:133], v[174:177], v[126:129]
	v_mfma_f32_16x16x32_bf16 v[126:129], v[134:137], v[178:181], v[126:129]
	s_barrier
	s_setprio 1
	v_mfma_f32_16x16x32_bf16 v[122:125], v[142:145], v[178:181], v[122:125]
	v_mfma_f32_16x16x32_bf16 v[122:125], v[138:141], v[174:177], v[122:125]
	v_mfma_f32_16x16x32_bf16 v[106:109], v[138:141], v[182:185], v[106:109]
	v_mfma_f32_16x16x32_bf16 v[106:109], v[142:145], v[186:189], v[106:109]
	v_mfma_f32_16x16x32_bf16 v[110:113], v[134:137], v[186:189], v[110:113]
	v_mfma_f32_16x16x32_bf16 v[110:113], v[130:133], v[182:185], v[110:113]
	v_mfma_f32_16x16x32_bf16 v[94:97], v[130:133], v[190:193], v[94:97]
	v_mfma_f32_16x16x32_bf16 v[94:97], v[134:137], v[204:207], v[94:97]
	v_mfma_f32_16x16x32_bf16 v[90:93], v[142:145], v[204:207], v[90:93]
	v_mfma_f32_16x16x32_bf16 v[90:93], v[138:141], v[190:193], v[90:93]
	v_mfma_f32_16x16x32_bf16 v[74:77], v[138:141], v[208:211], v[74:77]
	v_mfma_f32_16x16x32_bf16 v[74:77], v[142:145], v[212:215], v[74:77]
	v_mfma_f32_16x16x32_bf16 v[78:81], v[134:137], v[212:215], v[78:81]
	v_mfma_f32_16x16x32_bf16 v[78:81], v[130:133], v[208:211], v[78:81]
	v_mfma_f32_16x16x32_bf16 v[118:121], v[146:149], v[174:177], v[118:121]
	v_mfma_f32_16x16x32_bf16 v[118:121], v[162:165], v[178:181], v[118:121]
	v_mfma_f32_16x16x32_bf16 v[114:117], v[170:173], v[178:181], v[114:117]
	v_mfma_f32_16x16x32_bf16 v[114:117], v[166:169], v[174:177], v[114:117]
	v_mfma_f32_16x16x32_bf16 v[98:101], v[166:169], v[182:185], v[98:101]
	v_mfma_f32_16x16x32_bf16 v[98:101], v[170:173], v[186:189], v[98:101]
	v_mfma_f32_16x16x32_bf16 v[102:105], v[162:165], v[186:189], v[102:105]
	v_mfma_f32_16x16x32_bf16 v[102:105], v[146:149], v[182:185], v[102:105]
	v_mfma_f32_16x16x32_bf16 v[86:89], v[146:149], v[190:193], v[86:89]
	v_mfma_f32_16x16x32_bf16 v[86:89], v[162:165], v[204:207], v[86:89]
	v_mfma_f32_16x16x32_bf16 v[82:85], v[170:173], v[204:207], v[82:85]
	v_mfma_f32_16x16x32_bf16 v[82:85], v[166:169], v[190:193], v[82:85]
	v_mfma_f32_16x16x32_bf16 v[66:69], v[166:169], v[208:211], v[66:69]
	v_mfma_f32_16x16x32_bf16 v[66:69], v[170:173], v[212:215], v[66:69]
	v_mfma_f32_16x16x32_bf16 v[70:73], v[162:165], v[212:215], v[70:73]
	v_mfma_f32_16x16x32_bf16 v[70:73], v[146:149], v[208:211], v[70:73]
	s_setprio 0
	s_barrier
	ds_read_b128 v[174:177], v225 offset:16384
	ds_read_b128 v[178:181], v225 offset:17408
	ds_read_b128 v[182:185], v225 offset:18432
	ds_read_b128 v[186:189], v225 offset:19456
	ds_read_b128 v[190:193], v225 offset:20480
	ds_read_b128 v[204:207], v225 offset:21504
	ds_read_b128 v[208:211], v225 offset:22528
	ds_read_b128 v[212:215], v225 offset:23552
	s_add_i32 s0, s58, s15
	s_mov_b32 m0, s0
	s_nop 0
	global_load_lds_dwordx4 v152, s[30:31]
	s_add_i32 m0, s0, 0x2000
	s_add_u32 s0, s30, 0x80000
	s_addc_u32 s1, s31, 0
	s_add_i32 s58, s59, s15
	global_load_lds_dwordx4 v156, s[30:31]
	s_mov_b32 m0, s58
	s_nop 0
	global_load_lds_dwordx4 v152, s[0:1]
	s_add_i32 m0, s58, 0x2000
	s_nop 0
	global_load_lds_dwordx4 v156, s[0:1]
	s_waitcnt vmcnt(6)
	s_waitcnt lgkmcnt(0)
	v_mfma_f32_16x16x32_bf16 v[62:65], v[130:133], v[174:177], v[62:65]
	v_mfma_f32_16x16x32_bf16 v[62:65], v[134:137], v[178:181], v[62:65]
	s_barrier
	s_setprio 1
	v_mfma_f32_16x16x32_bf16 v[58:61], v[142:145], v[178:181], v[58:61]
	v_mfma_f32_16x16x32_bf16 v[58:61], v[138:141], v[174:177], v[58:61]
	v_mfma_f32_16x16x32_bf16 v[42:45], v[138:141], v[182:185], v[42:45]
	v_mfma_f32_16x16x32_bf16 v[42:45], v[142:145], v[186:189], v[42:45]
	v_mfma_f32_16x16x32_bf16 v[46:49], v[134:137], v[186:189], v[46:49]
	v_mfma_f32_16x16x32_bf16 v[46:49], v[130:133], v[182:185], v[46:49]
	v_mfma_f32_16x16x32_bf16 v[30:33], v[130:133], v[190:193], v[30:33]
	v_mfma_f32_16x16x32_bf16 v[30:33], v[134:137], v[204:207], v[30:33]
	v_mfma_f32_16x16x32_bf16 v[26:29], v[142:145], v[204:207], v[26:29]
	v_mfma_f32_16x16x32_bf16 v[26:29], v[138:141], v[190:193], v[26:29]
	v_mfma_f32_16x16x32_bf16 v[10:13], v[138:141], v[208:211], v[10:13]
	v_mfma_f32_16x16x32_bf16 v[10:13], v[142:145], v[212:215], v[10:13]
	v_mfma_f32_16x16x32_bf16 v[14:17], v[134:137], v[212:215], v[14:17]
	v_mfma_f32_16x16x32_bf16 v[14:17], v[130:133], v[208:211], v[14:17]
	v_mfma_f32_16x16x32_bf16 v[54:57], v[146:149], v[174:177], v[54:57]
	v_mfma_f32_16x16x32_bf16 v[54:57], v[162:165], v[178:181], v[54:57]
	v_mfma_f32_16x16x32_bf16 v[50:53], v[170:173], v[178:181], v[50:53]
	v_mfma_f32_16x16x32_bf16 v[50:53], v[166:169], v[174:177], v[50:53]
	v_mfma_f32_16x16x32_bf16 v[34:37], v[166:169], v[182:185], v[34:37]
	v_mfma_f32_16x16x32_bf16 v[34:37], v[170:173], v[186:189], v[34:37]
	v_mfma_f32_16x16x32_bf16 v[38:41], v[162:165], v[186:189], v[38:41]
	v_mfma_f32_16x16x32_bf16 v[38:41], v[146:149], v[182:185], v[38:41]
	v_mfma_f32_16x16x32_bf16 v[22:25], v[146:149], v[190:193], v[22:25]
	v_mfma_f32_16x16x32_bf16 v[22:25], v[162:165], v[204:207], v[22:25]
	v_mfma_f32_16x16x32_bf16 v[18:21], v[170:173], v[204:207], v[18:21]
	v_mfma_f32_16x16x32_bf16 v[18:21], v[166:169], v[190:193], v[18:21]
	v_mfma_f32_16x16x32_bf16 v[2:5], v[166:169], v[208:211], v[2:5]
	v_mfma_f32_16x16x32_bf16 v[2:5], v[170:173], v[212:215], v[2:5]
	v_mfma_f32_16x16x32_bf16 v[6:9], v[162:165], v[212:215], v[6:9]
	v_mfma_f32_16x16x32_bf16 v[6:9], v[146:149], v[208:211], v[6:9]
	s_setprio 0
	s_barrier
	s_mov_b32 m0, s38
	s_nop 0
	global_load_lds_dwordx4 v150, s[34:35]
	s_mov_b32 m0, s39
	s_nop 0
	global_load_lds_dwordx4 v154, s[34:35]
	ds_read_b128 v[130:133], v224 offset:32768
	ds_read_b128 v[134:137], v224 offset:33792
	ds_read_b128 v[138:141], v224 offset:34816
	ds_read_b128 v[142:145], v224 offset:35840
	ds_read_b128 v[146:149], v224 offset:49152
	ds_read_b128 v[162:165], v224 offset:50176
	ds_read_b128 v[166:169], v224 offset:51200
	ds_read_b128 v[170:173], v224 offset:52224
	ds_read_b128 v[174:177], v225 offset:32768
	ds_read_b128 v[178:181], v225 offset:33792
	ds_read_b128 v[182:185], v225 offset:34816
	ds_read_b128 v[186:189], v225 offset:35840
	ds_read_b128 v[190:193], v225 offset:36864
	ds_read_b128 v[204:207], v225 offset:37888
	ds_read_b128 v[208:211], v225 offset:38912
	ds_read_b128 v[212:215], v225 offset:39936
	s_add_i32 s58, 0, 0x18000
	s_add_i32 s59, 0, 0x1c000
	s_add_u32 s0, s34, 0x4000
	s_addc_u32 s1, s35, 0
	s_mov_b32 m0, s40
	s_nop 0
	global_load_lds_dwordx4 v150, s[0:1]
	s_mov_b32 m0, s41
	s_nop 0
	global_load_lds_dwordx4 v154, s[0:1]
	s_waitcnt vmcnt(8)
	s_waitcnt lgkmcnt(0)
	v_mfma_f32_16x16x32_bf16 v[126:129], v[130:133], v[174:177], v[126:129]
	v_mfma_f32_16x16x32_bf16 v[126:129], v[134:137], v[178:181], v[126:129]
	s_barrier
	s_setprio 1
	v_mfma_f32_16x16x32_bf16 v[122:125], v[142:145], v[178:181], v[122:125]
	v_mfma_f32_16x16x32_bf16 v[122:125], v[138:141], v[174:177], v[122:125]
	v_mfma_f32_16x16x32_bf16 v[106:109], v[138:141], v[182:185], v[106:109]
	v_mfma_f32_16x16x32_bf16 v[106:109], v[142:145], v[186:189], v[106:109]
	v_mfma_f32_16x16x32_bf16 v[110:113], v[134:137], v[186:189], v[110:113]
	v_mfma_f32_16x16x32_bf16 v[110:113], v[130:133], v[182:185], v[110:113]
	v_mfma_f32_16x16x32_bf16 v[94:97], v[130:133], v[190:193], v[94:97]
	v_mfma_f32_16x16x32_bf16 v[94:97], v[134:137], v[204:207], v[94:97]
	v_mfma_f32_16x16x32_bf16 v[90:93], v[142:145], v[204:207], v[90:93]
	v_mfma_f32_16x16x32_bf16 v[90:93], v[138:141], v[190:193], v[90:93]
	v_mfma_f32_16x16x32_bf16 v[74:77], v[138:141], v[208:211], v[74:77]
	v_mfma_f32_16x16x32_bf16 v[74:77], v[142:145], v[212:215], v[74:77]
	v_mfma_f32_16x16x32_bf16 v[78:81], v[134:137], v[212:215], v[78:81]
	v_mfma_f32_16x16x32_bf16 v[78:81], v[130:133], v[208:211], v[78:81]
	v_mfma_f32_16x16x32_bf16 v[118:121], v[146:149], v[174:177], v[118:121]
	v_mfma_f32_16x16x32_bf16 v[118:121], v[162:165], v[178:181], v[118:121]
	v_mfma_f32_16x16x32_bf16 v[114:117], v[170:173], v[178:181], v[114:117]
	v_mfma_f32_16x16x32_bf16 v[114:117], v[166:169], v[174:177], v[114:117]
	v_mfma_f32_16x16x32_bf16 v[98:101], v[166:169], v[182:185], v[98:101]
	v_mfma_f32_16x16x32_bf16 v[98:101], v[170:173], v[186:189], v[98:101]
	v_mfma_f32_16x16x32_bf16 v[102:105], v[162:165], v[186:189], v[102:105]
	v_mfma_f32_16x16x32_bf16 v[102:105], v[146:149], v[182:185], v[102:105]
	v_mfma_f32_16x16x32_bf16 v[86:89], v[146:149], v[190:193], v[86:89]
	v_mfma_f32_16x16x32_bf16 v[86:89], v[162:165], v[204:207], v[86:89]
	v_mfma_f32_16x16x32_bf16 v[82:85], v[170:173], v[204:207], v[82:85]
	v_mfma_f32_16x16x32_bf16 v[82:85], v[166:169], v[190:193], v[82:85]
	v_mfma_f32_16x16x32_bf16 v[66:69], v[166:169], v[208:211], v[66:69]
	v_mfma_f32_16x16x32_bf16 v[66:69], v[170:173], v[212:215], v[66:69]
	v_mfma_f32_16x16x32_bf16 v[70:73], v[162:165], v[212:215], v[70:73]
	v_mfma_f32_16x16x32_bf16 v[70:73], v[146:149], v[208:211], v[70:73]
	s_setprio 0
	s_barrier
	ds_read_b128 v[174:177], v225 offset:49152
	ds_read_b128 v[178:181], v225 offset:50176
	ds_read_b128 v[182:185], v225 offset:51200
	ds_read_b128 v[186:189], v225 offset:52224
	ds_read_b128 v[190:193], v225 offset:53248
	ds_read_b128 v[204:207], v225 offset:54272
	ds_read_b128 v[208:211], v225 offset:55296
	ds_read_b128 v[212:215], v225 offset:56320
	s_add_i32 s0, s58, s15
	s_add_u32 vcc_lo, s30, s94
	s_addc_u32 vcc_hi, s31, s95
	s_mov_b32 m0, s0
	s_nop 0
	global_load_lds_dwordx4 v152, vcc
	s_add_i32 m0, s0, 0x2000
	s_add_u32 s0, s30, 0x80080
	s_addc_u32 s1, s31, 0
	s_add_i32 s30, s59, s15
	global_load_lds_dwordx4 v156, vcc
	s_mov_b32 m0, s30
	s_nop 0
	global_load_lds_dwordx4 v152, s[0:1]
	s_add_i32 m0, s30, 0x2000
	s_nop 0
	global_load_lds_dwordx4 v156, s[0:1]
	s_waitcnt vmcnt(6)
	s_waitcnt lgkmcnt(0)
	v_mfma_f32_16x16x32_bf16 v[62:65], v[130:133], v[174:177], v[62:65]
	v_mfma_f32_16x16x32_bf16 v[62:65], v[134:137], v[178:181], v[62:65]
	s_barrier
	s_setprio 1
	v_mfma_f32_16x16x32_bf16 v[58:61], v[142:145], v[178:181], v[58:61]
	v_mfma_f32_16x16x32_bf16 v[58:61], v[138:141], v[174:177], v[58:61]
	v_mfma_f32_16x16x32_bf16 v[42:45], v[138:141], v[182:185], v[42:45]
	v_mfma_f32_16x16x32_bf16 v[42:45], v[142:145], v[186:189], v[42:45]
	v_mfma_f32_16x16x32_bf16 v[46:49], v[134:137], v[186:189], v[46:49]
	v_mfma_f32_16x16x32_bf16 v[46:49], v[130:133], v[182:185], v[46:49]
	v_mfma_f32_16x16x32_bf16 v[30:33], v[130:133], v[190:193], v[30:33]
	v_mfma_f32_16x16x32_bf16 v[30:33], v[134:137], v[204:207], v[30:33]
	v_mfma_f32_16x16x32_bf16 v[26:29], v[142:145], v[204:207], v[26:29]
	v_mfma_f32_16x16x32_bf16 v[26:29], v[138:141], v[190:193], v[26:29]
	v_mfma_f32_16x16x32_bf16 v[10:13], v[138:141], v[208:211], v[10:13]
	v_mfma_f32_16x16x32_bf16 v[10:13], v[142:145], v[212:215], v[10:13]
	s_add_i32 s57, s57, 2
	v_mfma_f32_16x16x32_bf16 v[14:17], v[134:137], v[212:215], v[14:17]
	v_mfma_f32_16x16x32_bf16 v[14:17], v[130:133], v[208:211], v[14:17]
	s_add_u32 s50, s50, 0x100
	v_mfma_f32_16x16x32_bf16 v[54:57], v[146:149], v[174:177], v[54:57]
	v_mfma_f32_16x16x32_bf16 v[54:57], v[162:165], v[178:181], v[54:57]
	s_addc_u32 s51, s51, 0
	v_mfma_f32_16x16x32_bf16 v[50:53], v[170:173], v[178:181], v[50:53]
	v_mfma_f32_16x16x32_bf16 v[50:53], v[166:169], v[174:177], v[50:53]
	s_cmp_gt_u32 s57, 29
	v_mfma_f32_16x16x32_bf16 v[34:37], v[166:169], v[182:185], v[34:37]
	v_mfma_f32_16x16x32_bf16 v[34:37], v[170:173], v[186:189], v[34:37]
	s_mov_b64 s[0:1], s[4:5]
	v_mfma_f32_16x16x32_bf16 v[38:41], v[162:165], v[186:189], v[38:41]
	v_mfma_f32_16x16x32_bf16 v[38:41], v[146:149], v[182:185], v[38:41]
	v_mfma_f32_16x16x32_bf16 v[22:25], v[146:149], v[190:193], v[22:25]
	v_mfma_f32_16x16x32_bf16 v[22:25], v[162:165], v[204:207], v[22:25]
	v_mfma_f32_16x16x32_bf16 v[18:21], v[170:173], v[204:207], v[18:21]
	v_mfma_f32_16x16x32_bf16 v[18:21], v[166:169], v[190:193], v[18:21]
	v_mfma_f32_16x16x32_bf16 v[2:5], v[166:169], v[208:211], v[2:5]
	v_mfma_f32_16x16x32_bf16 v[2:5], v[170:173], v[212:215], v[2:5]
	v_mfma_f32_16x16x32_bf16 v[6:9], v[162:165], v[212:215], v[6:9]
	v_mfma_f32_16x16x32_bf16 v[6:9], v[146:149], v[208:211], v[6:9]
	s_setprio 0
	s_barrier
	s_cbranch_scc0 .LBB0_133

.LBB0_244:
	v_mov_b32_e32 v2, v195
	s_andn2_b64 vcc, exec, s[12:13]
	s_cbranch_vccnz .LBB0_122
	s_branch .LBB0_122

.LBB0_303:
	s_ashr_i32 s25, s24, 31
	s_lshl_b64 s[28:29], s[24:25], 20
	v_readlane_b32 s25, v254, 62
	s_add_u32 s25, s25, s28
	v_readlane_b32 s27, v254, 63
	s_addc_u32 s27, s27, s29
	s_and_b64 s[28:29], s[4:5], exec
	s_cselect_b32 s29, s27, s39
	s_cselect_b32 s25, s25, s38
	s_ashr_i32 s27, s26, 31
	s_lshl_b64 s[40:41], s[26:27], 7
	s_add_u32 s28, s25, s40
	s_addc_u32 s29, s29, s41
	s_and_b64 s[70:71], s[4:5], exec
	s_cselect_b32 s27, s40, 0
	s_cselect_b32 s25, s41, 0
	s_add_u32 s30, s30, s27
	s_addc_u32 s31, s31, s25
	s_cmp_lt_i32 s35, 1
	s_cbranch_scc1 .LBB0_331
	s_and_b64 s[4:5], s[4:5], exec
	s_cselect_b32 s25, s29, s39
	s_cselect_b32 s27, s28, s38
	s_add_i32 s37, s35, -2
	s_add_u32 s51, s38, 0x100
	v_mov_b64_e32 v[8:9], v[4:5]
	v_mov_b64_e32 v[20:21], v[4:5]
	v_mov_b64_e32 v[24:25], v[4:5]
	v_mov_b64_e32 v[36:37], v[4:5]
	v_mov_b64_e32 v[40:41], v[4:5]
	v_mov_b64_e32 v[52:53], v[4:5]
	v_mov_b64_e32 v[56:57], v[4:5]
	v_mov_b64_e32 v[12:13], v[4:5]
	v_mov_b64_e32 v[16:17], v[4:5]
	v_mov_b64_e32 v[28:29], v[4:5]
	v_mov_b64_e32 v[32:33], v[4:5]
	v_mov_b64_e32 v[44:45], v[4:5]
	v_mov_b64_e32 v[48:49], v[4:5]
	v_mov_b64_e32 v[60:61], v[4:5]
	v_mov_b64_e32 v[64:65], v[4:5]
	v_mov_b64_e32 v[68:69], v[4:5]
	v_mov_b64_e32 v[72:73], v[4:5]
	v_mov_b64_e32 v[84:85], v[4:5]
	v_mov_b64_e32 v[88:89], v[4:5]
	v_mov_b64_e32 v[100:101], v[4:5]
	v_mov_b64_e32 v[104:105], v[4:5]
	v_mov_b64_e32 v[116:117], v[4:5]
	v_mov_b64_e32 v[120:121], v[4:5]
	v_mov_b64_e32 v[76:77], v[4:5]
	v_mov_b64_e32 v[80:81], v[4:5]
	v_mov_b64_e32 v[92:93], v[4:5]
	v_mov_b64_e32 v[96:97], v[4:5]
	v_mov_b64_e32 v[108:109], v[4:5]
	v_mov_b64_e32 v[112:113], v[4:5]
	v_mov_b64_e32 v[124:125], v[4:5]
	v_mov_b64_e32 v[128:129], v[4:5]
	s_addc_u32 s70, s39, 0
	s_mov_b32 s38, 0
	v_mov_b64_e32 v[6:7], v[2:3]
	v_mov_b64_e32 v[18:19], v[2:3]
	v_mov_b64_e32 v[22:23], v[2:3]
	v_mov_b64_e32 v[34:35], v[2:3]
	v_mov_b64_e32 v[38:39], v[2:3]
	v_mov_b64_e32 v[50:51], v[2:3]
	v_mov_b64_e32 v[54:55], v[2:3]
	v_mov_b64_e32 v[10:11], v[2:3]
	v_mov_b64_e32 v[14:15], v[2:3]
	v_mov_b64_e32 v[26:27], v[2:3]
	v_mov_b64_e32 v[30:31], v[2:3]
	v_mov_b64_e32 v[42:43], v[2:3]
	v_mov_b64_e32 v[46:47], v[2:3]
	v_mov_b64_e32 v[58:59], v[2:3]
	v_mov_b64_e32 v[62:63], v[2:3]
	v_mov_b64_e32 v[66:67], v[2:3]
	v_mov_b64_e32 v[70:71], v[2:3]
	v_mov_b64_e32 v[82:83], v[2:3]
	v_mov_b64_e32 v[86:87], v[2:3]
	v_mov_b64_e32 v[98:99], v[2:3]
	v_mov_b64_e32 v[102:103], v[2:3]
	v_mov_b64_e32 v[114:115], v[2:3]
	v_mov_b64_e32 v[118:119], v[2:3]
	v_mov_b64_e32 v[74:75], v[2:3]
	v_mov_b64_e32 v[78:79], v[2:3]
	v_mov_b64_e32 v[90:91], v[2:3]
	v_mov_b64_e32 v[94:95], v[2:3]
	v_mov_b64_e32 v[106:107], v[2:3]
	v_mov_b64_e32 v[110:111], v[2:3]
	v_mov_b64_e32 v[122:123], v[2:3]
	v_mov_b64_e32 v[126:127], v[2:3]
	s_cmp_eq_u32 s33, 0
	s_cbranch_scc1 .Lrealign_1
	s_andn2_b64 vcc, exec, s[12:13]
	s_cbranch_vccnz .Lrealign_1
	s_barrier
.Lrealign_1:
.LBB0_305:
	s_add_u32 vcc_lo, s0, 0xffffc000
	s_addc_u32 vcc_hi, s1, -1
	s_mov_b32 m0, s62
	s_nop 0
	global_load_lds_dwordx4 v178, vcc
	s_mov_b32 m0, s63
	s_nop 0
	global_load_lds_dwordx4 v180, vcc
	ds_read_b128 v[130:133], v226
	ds_read_b128 v[134:137], v226 offset:1024
	ds_read_b128 v[138:141], v226 offset:2048
	ds_read_b128 v[142:145], v226 offset:3072
	ds_read_b128 v[146:149], v226 offset:16384
	ds_read_b128 v[150:153], v226 offset:17408
	ds_read_b128 v[154:157], v226 offset:18432
	ds_read_b128 v[158:161], v226 offset:19456
	ds_read_b128 v[162:165], v227
	ds_read_b128 v[166:169], v227 offset:1024
	ds_read_b128 v[182:185], v227 offset:2048
	ds_read_b128 v[186:189], v227 offset:3072
	ds_read_b128 v[190:193], v227 offset:4096
	ds_read_b128 v[204:207], v227 offset:5120
	ds_read_b128 v[208:211], v227 offset:6144
	ds_read_b128 v[212:215], v227 offset:7168
	s_add_i32 s71, s38, 2
	s_add_u32 s4, s0, 0x100
	s_addc_u32 s5, s1, 0
	s_add_i32 s73, 0, 0x10000
	s_cmp_eq_u32 s37, s38
	s_cselect_b32 s41, s31, s5
	s_cselect_b32 s40, s30, s4
	s_cselect_b32 s39, s25, s70
	s_cselect_b32 s38, s27, s51
	s_add_i32 s75, 0, 0x14000
	s_add_i32 m0, s56, 0xc000
	s_nop 0
	global_load_lds_dwordx4 v178, s[0:1]
	s_add_i32 m0, s56, 0xe000
	s_nop 0
	global_load_lds_dwordx4 v180, s[0:1]
	s_waitcnt vmcnt(8)
	s_waitcnt lgkmcnt(0)
	v_mfma_f32_16x16x32_bf16 v[126:129], v[130:133], v[162:165], v[126:129]
	v_mfma_f32_16x16x32_bf16 v[126:129], v[134:137], v[166:169], v[126:129]
	s_barrier
	s_setprio 1
	v_mfma_f32_16x16x32_bf16 v[122:125], v[142:145], v[166:169], v[122:125]
	v_mfma_f32_16x16x32_bf16 v[122:125], v[138:141], v[162:165], v[122:125]
	v_mfma_f32_16x16x32_bf16 v[106:109], v[138:141], v[182:185], v[106:109]
	v_mfma_f32_16x16x32_bf16 v[106:109], v[142:145], v[186:189], v[106:109]
	v_mfma_f32_16x16x32_bf16 v[110:113], v[134:137], v[186:189], v[110:113]
	v_mfma_f32_16x16x32_bf16 v[110:113], v[130:133], v[182:185], v[110:113]
	v_mfma_f32_16x16x32_bf16 v[94:97], v[130:133], v[190:193], v[94:97]
	v_mfma_f32_16x16x32_bf16 v[94:97], v[134:137], v[204:207], v[94:97]
	v_mfma_f32_16x16x32_bf16 v[90:93], v[142:145], v[204:207], v[90:93]
	v_mfma_f32_16x16x32_bf16 v[90:93], v[138:141], v[190:193], v[90:93]
	v_mfma_f32_16x16x32_bf16 v[74:77], v[138:141], v[208:211], v[74:77]
	v_mfma_f32_16x16x32_bf16 v[74:77], v[142:145], v[212:215], v[74:77]
	v_mfma_f32_16x16x32_bf16 v[78:81], v[134:137], v[212:215], v[78:81]
	v_mfma_f32_16x16x32_bf16 v[78:81], v[130:133], v[208:211], v[78:81]
	v_mfma_f32_16x16x32_bf16 v[118:121], v[146:149], v[162:165], v[118:121]
	v_mfma_f32_16x16x32_bf16 v[118:121], v[150:153], v[166:169], v[118:121]
	v_mfma_f32_16x16x32_bf16 v[114:117], v[158:161], v[166:169], v[114:117]
	v_mfma_f32_16x16x32_bf16 v[114:117], v[154:157], v[162:165], v[114:117]
	v_mfma_f32_16x16x32_bf16 v[98:101], v[154:157], v[182:185], v[98:101]
	v_mfma_f32_16x16x32_bf16 v[98:101], v[158:161], v[186:189], v[98:101]
	v_mfma_f32_16x16x32_bf16 v[102:105], v[150:153], v[186:189], v[102:105]
	v_mfma_f32_16x16x32_bf16 v[102:105], v[146:149], v[182:185], v[102:105]
	v_mfma_f32_16x16x32_bf16 v[86:89], v[146:149], v[190:193], v[86:89]
	v_mfma_f32_16x16x32_bf16 v[86:89], v[150:153], v[204:207], v[86:89]
	v_mfma_f32_16x16x32_bf16 v[82:85], v[158:161], v[204:207], v[82:85]
	v_mfma_f32_16x16x32_bf16 v[82:85], v[154:157], v[190:193], v[82:85]
	v_mfma_f32_16x16x32_bf16 v[66:69], v[154:157], v[208:211], v[66:69]
	v_mfma_f32_16x16x32_bf16 v[66:69], v[158:161], v[212:215], v[66:69]
	v_mfma_f32_16x16x32_bf16 v[70:73], v[150:153], v[212:215], v[70:73]
	v_mfma_f32_16x16x32_bf16 v[70:73], v[146:149], v[208:211], v[70:73]
	s_setprio 0
	s_barrier
	ds_read_b128 v[162:165], v227 offset:16384
	ds_read_b128 v[166:169], v227 offset:17408
	ds_read_b128 v[182:185], v227 offset:18432
	ds_read_b128 v[186:189], v227 offset:19456
	ds_read_b128 v[190:193], v227 offset:20480
	ds_read_b128 v[204:207], v227 offset:21504
	ds_read_b128 v[208:211], v227 offset:22528
	ds_read_b128 v[212:215], v227 offset:23552
	s_add_i32 s0, s73, s15
	s_mov_b32 m0, s0
	s_nop 0
	global_load_lds_dwordx4 v172, s[38:39]
	s_add_i32 m0, s0, 0x2000
	s_add_u32 s0, s38, 0x80000
	s_addc_u32 s1, s39, 0
	s_add_i32 s73, s75, s15
	global_load_lds_dwordx4 v176, s[38:39]
	s_mov_b32 m0, s73
	s_nop 0
	global_load_lds_dwordx4 v172, s[0:1]
	s_add_i32 m0, s73, 0x2000
	s_nop 0
	global_load_lds_dwordx4 v176, s[0:1]
	s_waitcnt vmcnt(6)
	s_waitcnt lgkmcnt(0)
	v_mfma_f32_16x16x32_bf16 v[62:65], v[130:133], v[162:165], v[62:65]
	v_mfma_f32_16x16x32_bf16 v[62:65], v[134:137], v[166:169], v[62:65]
	s_barrier
	s_setprio 1
	v_mfma_f32_16x16x32_bf16 v[58:61], v[142:145], v[166:169], v[58:61]
	v_mfma_f32_16x16x32_bf16 v[58:61], v[138:141], v[162:165], v[58:61]
	v_mfma_f32_16x16x32_bf16 v[42:45], v[138:141], v[182:185], v[42:45]
	v_mfma_f32_16x16x32_bf16 v[42:45], v[142:145], v[186:189], v[42:45]
	v_mfma_f32_16x16x32_bf16 v[46:49], v[134:137], v[186:189], v[46:49]
	v_mfma_f32_16x16x32_bf16 v[46:49], v[130:133], v[182:185], v[46:49]
	v_mfma_f32_16x16x32_bf16 v[30:33], v[130:133], v[190:193], v[30:33]
	v_mfma_f32_16x16x32_bf16 v[30:33], v[134:137], v[204:207], v[30:33]
	v_mfma_f32_16x16x32_bf16 v[26:29], v[142:145], v[204:207], v[26:29]
	v_mfma_f32_16x16x32_bf16 v[26:29], v[138:141], v[190:193], v[26:29]
	v_mfma_f32_16x16x32_bf16 v[10:13], v[138:141], v[208:211], v[10:13]
	v_mfma_f32_16x16x32_bf16 v[10:13], v[142:145], v[212:215], v[10:13]
	v_mfma_f32_16x16x32_bf16 v[14:17], v[134:137], v[212:215], v[14:17]
	v_mfma_f32_16x16x32_bf16 v[14:17], v[130:133], v[208:211], v[14:17]
	v_mfma_f32_16x16x32_bf16 v[54:57], v[146:149], v[162:165], v[54:57]
	v_mfma_f32_16x16x32_bf16 v[54:57], v[150:153], v[166:169], v[54:57]
	v_mfma_f32_16x16x32_bf16 v[50:53], v[158:161], v[166:169], v[50:53]
	v_mfma_f32_16x16x32_bf16 v[50:53], v[154:157], v[162:165], v[50:53]
	v_mfma_f32_16x16x32_bf16 v[34:37], v[154:157], v[182:185], v[34:37]
	v_mfma_f32_16x16x32_bf16 v[34:37], v[158:161], v[186:189], v[34:37]
	v_mfma_f32_16x16x32_bf16 v[38:41], v[150:153], v[186:189], v[38:41]
	v_mfma_f32_16x16x32_bf16 v[38:41], v[146:149], v[182:185], v[38:41]
	v_mfma_f32_16x16x32_bf16 v[22:25], v[146:149], v[190:193], v[22:25]
	v_mfma_f32_16x16x32_bf16 v[22:25], v[150:153], v[204:207], v[22:25]
	v_mfma_f32_16x16x32_bf16 v[18:21], v[158:161], v[204:207], v[18:21]
	v_mfma_f32_16x16x32_bf16 v[18:21], v[154:157], v[190:193], v[18:21]
	v_mfma_f32_16x16x32_bf16 v[2:5], v[154:157], v[208:211], v[2:5]
	v_mfma_f32_16x16x32_bf16 v[2:5], v[158:161], v[212:215], v[2:5]
	v_mfma_f32_16x16x32_bf16 v[6:9], v[150:153], v[212:215], v[6:9]
	v_mfma_f32_16x16x32_bf16 v[6:9], v[146:149], v[208:211], v[6:9]
	s_setprio 0
	s_barrier
	s_mov_b32 m0, s56
	s_nop 0
	global_load_lds_dwordx4 v170, s[40:41]
	s_mov_b32 m0, s57
	s_nop 0
	global_load_lds_dwordx4 v174, s[40:41]
	ds_read_b128 v[130:133], v226 offset:32768
	ds_read_b128 v[134:137], v226 offset:33792
	ds_read_b128 v[138:141], v226 offset:34816
	ds_read_b128 v[142:145], v226 offset:35840
	ds_read_b128 v[146:149], v226 offset:49152
	ds_read_b128 v[150:153], v226 offset:50176
	ds_read_b128 v[154:157], v226 offset:51200
	ds_read_b128 v[158:161], v226 offset:52224
	ds_read_b128 v[162:165], v227 offset:32768
	ds_read_b128 v[166:169], v227 offset:33792
	ds_read_b128 v[182:185], v227 offset:34816
	ds_read_b128 v[186:189], v227 offset:35840
	ds_read_b128 v[190:193], v227 offset:36864
	ds_read_b128 v[204:207], v227 offset:37888
	ds_read_b128 v[208:211], v227 offset:38912
	ds_read_b128 v[212:215], v227 offset:39936
	s_add_i32 s73, 0, 0x18000
	s_add_i32 s75, 0, 0x1c000
	s_add_u32 s0, s40, 0x4000
	s_addc_u32 s1, s41, 0
	s_mov_b32 m0, s58
	s_nop 0
	global_load_lds_dwordx4 v170, s[0:1]
	s_mov_b32 m0, s59
	s_nop 0
	global_load_lds_dwordx4 v174, s[0:1]
	s_waitcnt vmcnt(8)
	s_waitcnt lgkmcnt(0)
	v_mfma_f32_16x16x32_bf16 v[126:129], v[130:133], v[162:165], v[126:129]
	v_mfma_f32_16x16x32_bf16 v[126:129], v[134:137], v[166:169], v[126:129]
	s_barrier
	s_setprio 1
	v_mfma_f32_16x16x32_bf16 v[122:125], v[142:145], v[166:169], v[122:125]
	v_mfma_f32_16x16x32_bf16 v[122:125], v[138:141], v[162:165], v[122:125]
	v_mfma_f32_16x16x32_bf16 v[106:109], v[138:141], v[182:185], v[106:109]
	v_mfma_f32_16x16x32_bf16 v[106:109], v[142:145], v[186:189], v[106:109]
	v_mfma_f32_16x16x32_bf16 v[110:113], v[134:137], v[186:189], v[110:113]
	v_mfma_f32_16x16x32_bf16 v[110:113], v[130:133], v[182:185], v[110:113]
	v_mfma_f32_16x16x32_bf16 v[94:97], v[130:133], v[190:193], v[94:97]
	v_mfma_f32_16x16x32_bf16 v[94:97], v[134:137], v[204:207], v[94:97]
	v_mfma_f32_16x16x32_bf16 v[90:93], v[142:145], v[204:207], v[90:93]
	v_mfma_f32_16x16x32_bf16 v[90:93], v[138:141], v[190:193], v[90:93]
	v_mfma_f32_16x16x32_bf16 v[74:77], v[138:141], v[208:211], v[74:77]
	v_mfma_f32_16x16x32_bf16 v[74:77], v[142:145], v[212:215], v[74:77]
	v_mfma_f32_16x16x32_bf16 v[78:81], v[134:137], v[212:215], v[78:81]
	v_mfma_f32_16x16x32_bf16 v[78:81], v[130:133], v[208:211], v[78:81]
	v_mfma_f32_16x16x32_bf16 v[118:121], v[146:149], v[162:165], v[118:121]
	v_mfma_f32_16x16x32_bf16 v[118:121], v[150:153], v[166:169], v[118:121]
	v_mfma_f32_16x16x32_bf16 v[114:117], v[158:161], v[166:169], v[114:117]
	v_mfma_f32_16x16x32_bf16 v[114:117], v[154:157], v[162:165], v[114:117]
	v_mfma_f32_16x16x32_bf16 v[98:101], v[154:157], v[182:185], v[98:101]
	v_mfma_f32_16x16x32_bf16 v[98:101], v[158:161], v[186:189], v[98:101]
	v_mfma_f32_16x16x32_bf16 v[102:105], v[150:153], v[186:189], v[102:105]
	v_mfma_f32_16x16x32_bf16 v[102:105], v[146:149], v[182:185], v[102:105]
	v_mfma_f32_16x16x32_bf16 v[86:89], v[146:149], v[190:193], v[86:89]
	v_mfma_f32_16x16x32_bf16 v[86:89], v[150:153], v[204:207], v[86:89]
	v_mfma_f32_16x16x32_bf16 v[82:85], v[158:161], v[204:207], v[82:85]
	v_mfma_f32_16x16x32_bf16 v[82:85], v[154:157], v[190:193], v[82:85]
	v_mfma_f32_16x16x32_bf16 v[66:69], v[154:157], v[208:211], v[66:69]
	v_mfma_f32_16x16x32_bf16 v[66:69], v[158:161], v[212:215], v[66:69]
	v_mfma_f32_16x16x32_bf16 v[70:73], v[150:153], v[212:215], v[70:73]
	v_mfma_f32_16x16x32_bf16 v[70:73], v[146:149], v[208:211], v[70:73]
	s_setprio 0
	s_barrier
	ds_read_b128 v[162:165], v227 offset:49152
	ds_read_b128 v[166:169], v227 offset:50176
	ds_read_b128 v[182:185], v227 offset:51200
	ds_read_b128 v[186:189], v227 offset:52224
	ds_read_b128 v[190:193], v227 offset:53248
	ds_read_b128 v[204:207], v227 offset:54272
	ds_read_b128 v[208:211], v227 offset:55296
	ds_read_b128 v[212:215], v227 offset:56320
	s_add_i32 s0, s73, s15
	s_add_u32 vcc_lo, s38, s94
	s_addc_u32 vcc_hi, s39, s95
	s_mov_b32 m0, s0
	s_nop 0
	global_load_lds_dwordx4 v172, vcc
	s_add_i32 m0, s0, 0x2000
	s_add_u32 s0, s38, 0x80080
	s_addc_u32 s1, s39, 0
	s_add_i32 s38, s75, s15
	global_load_lds_dwordx4 v176, vcc
	s_mov_b32 m0, s38
	s_nop 0
	global_load_lds_dwordx4 v172, s[0:1]
	s_add_i32 m0, s38, 0x2000
	s_nop 0
	global_load_lds_dwordx4 v176, s[0:1]
	s_waitcnt vmcnt(6)
	s_waitcnt lgkmcnt(0)
	v_mfma_f32_16x16x32_bf16 v[62:65], v[130:133], v[162:165], v[62:65]
	v_mfma_f32_16x16x32_bf16 v[62:65], v[134:137], v[166:169], v[62:65]
	s_barrier
	s_setprio 1
	v_mfma_f32_16x16x32_bf16 v[58:61], v[142:145], v[166:169], v[58:61]
	v_mfma_f32_16x16x32_bf16 v[58:61], v[138:141], v[162:165], v[58:61]
	v_mfma_f32_16x16x32_bf16 v[42:45], v[138:141], v[182:185], v[42:45]
	v_mfma_f32_16x16x32_bf16 v[42:45], v[142:145], v[186:189], v[42:45]
	v_mfma_f32_16x16x32_bf16 v[46:49], v[134:137], v[186:189], v[46:49]
	v_mfma_f32_16x16x32_bf16 v[46:49], v[130:133], v[182:185], v[46:49]
	v_mfma_f32_16x16x32_bf16 v[30:33], v[130:133], v[190:193], v[30:33]
	v_mfma_f32_16x16x32_bf16 v[30:33], v[134:137], v[204:207], v[30:33]
	v_mfma_f32_16x16x32_bf16 v[26:29], v[142:145], v[204:207], v[26:29]
	v_mfma_f32_16x16x32_bf16 v[26:29], v[138:141], v[190:193], v[26:29]
	v_mfma_f32_16x16x32_bf16 v[10:13], v[138:141], v[208:211], v[10:13]
	v_mfma_f32_16x16x32_bf16 v[10:13], v[142:145], v[212:215], v[10:13]
	s_add_u32 s51, s51, 0x100
	v_mfma_f32_16x16x32_bf16 v[14:17], v[134:137], v[212:215], v[14:17]
	v_mfma_f32_16x16x32_bf16 v[14:17], v[130:133], v[208:211], v[14:17]
	s_addc_u32 s70, s70, 0
	v_mfma_f32_16x16x32_bf16 v[54:57], v[146:149], v[162:165], v[54:57]
	v_mfma_f32_16x16x32_bf16 v[54:57], v[150:153], v[166:169], v[54:57]
	s_cmp_ge_i32 s71, s35
	v_mfma_f32_16x16x32_bf16 v[50:53], v[158:161], v[166:169], v[50:53]
	v_mfma_f32_16x16x32_bf16 v[50:53], v[154:157], v[162:165], v[50:53]
	s_mov_b64 s[0:1], s[4:5]
	v_mfma_f32_16x16x32_bf16 v[34:37], v[154:157], v[182:185], v[34:37]
	v_mfma_f32_16x16x32_bf16 v[34:37], v[158:161], v[186:189], v[34:37]
	s_mov_b32 s38, s71
	v_mfma_f32_16x16x32_bf16 v[38:41], v[150:153], v[186:189], v[38:41]
	v_mfma_f32_16x16x32_bf16 v[38:41], v[146:149], v[182:185], v[38:41]
	v_mfma_f32_16x16x32_bf16 v[22:25], v[146:149], v[190:193], v[22:25]
	v_mfma_f32_16x16x32_bf16 v[22:25], v[150:153], v[204:207], v[22:25]
	v_mfma_f32_16x16x32_bf16 v[18:21], v[158:161], v[204:207], v[18:21]
	v_mfma_f32_16x16x32_bf16 v[18:21], v[154:157], v[190:193], v[18:21]
	v_mfma_f32_16x16x32_bf16 v[2:5], v[154:157], v[208:211], v[2:5]
	v_mfma_f32_16x16x32_bf16 v[2:5], v[158:161], v[212:215], v[2:5]
	v_mfma_f32_16x16x32_bf16 v[6:9], v[150:153], v[212:215], v[6:9]
	v_mfma_f32_16x16x32_bf16 v[6:9], v[146:149], v[208:211], v[6:9]
	s_setprio 0
	s_barrier
	s_cbranch_scc0 .LBB0_305
	s_movk_i32 s51, 0x2000
	s_mov_b32 s73, 0x10000
	s_mov_b32 s75, 0x12000
	s_and_b64 vcc, exec, s[16:17]
	s_cbranch_vccz .LBB0_308

.LBB0_439:
	s_and_b64 vcc, exec, s[2:3]
	s_mov_b64 s[0:1], -1
	s_cbranch_vccnz .LBB0_294
	v_mov_b32_e32 v2, v195
	s_andn2_b64 vcc, exec, s[12:13]
	s_cbranch_vccnz .LBB0_293
	s_branch .LBB0_293

.LBB0_529:
	s_lshl_b32 s10, s30, 8
	s_ashr_i32 s11, s10, 31
	s_lshl_b64 s[10:11], s[10:11], 12
	s_add_u32 s10, s86, s10
	s_addc_u32 s11, s87, s11
	s_and_b64 s[12:13], s[2:3], exec
	s_cselect_b32 s34, s11, s15
	s_cselect_b32 s35, s10, s14
	s_ashr_i32 s9, s8, 31
	s_lshl_b64 s[12:13], s[8:9], 20
	v_readlane_b32 s9, v254, 62
	s_add_u32 s12, s9, s12
	v_readlane_b32 s9, v254, 63
	s_addc_u32 s13, s9, s13
	s_and_b64 s[18:19], s[2:3], exec
	s_cselect_b32 s9, s13, s17
	s_cselect_b32 s36, s12, s16
	s_add_u32 s14, s14, 0x80080
	s_addc_u32 s15, s15, 0
	s_add_u32 s37, s16, 0x100
	v_mov_b64_e32 v[8:9], v[4:5]
	v_mov_b64_e32 v[20:21], v[4:5]
	v_mov_b64_e32 v[24:25], v[4:5]
	v_mov_b64_e32 v[36:37], v[4:5]
	v_mov_b64_e32 v[40:41], v[4:5]
	v_mov_b64_e32 v[52:53], v[4:5]
	v_mov_b64_e32 v[56:57], v[4:5]
	v_mov_b64_e32 v[12:13], v[4:5]
	v_mov_b64_e32 v[16:17], v[4:5]
	v_mov_b64_e32 v[28:29], v[4:5]
	v_mov_b64_e32 v[32:33], v[4:5]
	v_mov_b64_e32 v[44:45], v[4:5]
	v_mov_b64_e32 v[48:49], v[4:5]
	v_mov_b64_e32 v[60:61], v[4:5]
	v_mov_b64_e32 v[64:65], v[4:5]
	v_mov_b64_e32 v[68:69], v[4:5]
	v_mov_b64_e32 v[72:73], v[4:5]
	v_mov_b64_e32 v[84:85], v[4:5]
	v_mov_b64_e32 v[88:89], v[4:5]
	v_mov_b64_e32 v[100:101], v[4:5]
	v_mov_b64_e32 v[104:105], v[4:5]
	v_mov_b64_e32 v[116:117], v[4:5]
	v_mov_b64_e32 v[120:121], v[4:5]
	v_mov_b64_e32 v[76:77], v[4:5]
	v_mov_b64_e32 v[80:81], v[4:5]
	v_mov_b64_e32 v[92:93], v[4:5]
	v_mov_b64_e32 v[96:97], v[4:5]
	v_mov_b64_e32 v[108:109], v[4:5]
	v_mov_b64_e32 v[112:113], v[4:5]
	v_mov_b64_e32 v[124:125], v[4:5]
	v_mov_b64_e32 v[128:129], v[4:5]
	s_addc_u32 s38, s17, 0
	s_mov_b32 s39, -2
	v_mov_b64_e32 v[6:7], v[2:3]
	v_mov_b64_e32 v[18:19], v[2:3]
	v_mov_b64_e32 v[22:23], v[2:3]
	v_mov_b64_e32 v[34:35], v[2:3]
	v_mov_b64_e32 v[38:39], v[2:3]
	v_mov_b64_e32 v[50:51], v[2:3]
	v_mov_b64_e32 v[54:55], v[2:3]
	v_mov_b64_e32 v[10:11], v[2:3]
	v_mov_b64_e32 v[14:15], v[2:3]
	v_mov_b64_e32 v[26:27], v[2:3]
	v_mov_b64_e32 v[30:31], v[2:3]
	v_mov_b64_e32 v[42:43], v[2:3]
	v_mov_b64_e32 v[46:47], v[2:3]
	v_mov_b64_e32 v[58:59], v[2:3]
	v_mov_b64_e32 v[62:63], v[2:3]
	v_mov_b64_e32 v[66:67], v[2:3]
	v_mov_b64_e32 v[70:71], v[2:3]
	v_mov_b64_e32 v[82:83], v[2:3]
	v_mov_b64_e32 v[86:87], v[2:3]
	v_mov_b64_e32 v[98:99], v[2:3]
	v_mov_b64_e32 v[102:103], v[2:3]
	v_mov_b64_e32 v[114:115], v[2:3]
	v_mov_b64_e32 v[118:119], v[2:3]
	v_mov_b64_e32 v[74:75], v[2:3]
	v_mov_b64_e32 v[78:79], v[2:3]
	v_mov_b64_e32 v[90:91], v[2:3]
	v_mov_b64_e32 v[94:95], v[2:3]
	v_mov_b64_e32 v[106:107], v[2:3]
	v_mov_b64_e32 v[110:111], v[2:3]
	v_mov_b64_e32 v[122:123], v[2:3]
	v_mov_b64_e32 v[126:127], v[2:3]
	s_cmp_eq_u32 s29, 1
	s_cbranch_scc1 .Lrealign_2
	s_andn2_b64 vcc, exec, s[0:1]
	s_cbranch_vccnz .Lrealign_2
	s_barrier
.Lrealign_2:
.LBB0_530:
	s_add_u32 vcc_lo, s14, 0xfff80000
	s_addc_u32 vcc_hi, s15, -1
	s_mov_b32 m0, s27
	s_nop 0
	global_load_lds_dwordx4 v138, vcc
	s_mov_b32 m0, s28
	s_nop 0
	global_load_lds_dwordx4 v140, vcc
	ds_read_b128 v[152:155], v145
	ds_read_b128 v[156:159], v145 offset:1024
	ds_read_b128 v[160:163], v145 offset:2048
	ds_read_b128 v[164:167], v145 offset:3072
	ds_read_b128 v[168:171], v145 offset:16384
	ds_read_b128 v[172:175], v145 offset:17408
	ds_read_b128 v[176:179], v145 offset:18432
	ds_read_b128 v[180:183], v145 offset:19456
	ds_read_b128 v[184:187], v151
	ds_read_b128 v[188:191], v151 offset:1024
	ds_read_b128 v[204:207], v151 offset:2048
	ds_read_b128 v[208:211], v151 offset:3072
	ds_read_b128 v[212:215], v151 offset:4096
	ds_read_b128 v[216:219], v151 offset:5120
	ds_read_b128 v[220:223], v151 offset:6144
	ds_read_b128 v[224:227], v151 offset:7168
	s_add_u32 s16, s14, 0xfff80080
	s_addc_u32 s17, s15, -1
	s_add_i32 s40, 0, 0x10000
	s_cmp_eq_u32 s39, 28
	s_cselect_b32 s19, s34, s17
	s_cselect_b32 s18, s35, s16
	s_cselect_b32 s17, s9, s38
	s_cselect_b32 s16, s36, s37
	s_add_i32 s42, 0, 0x14000
	s_add_i32 m0, s23, 0xc000
	s_nop 0
	global_load_lds_dwordx4 v138, s[14:15]
	s_add_i32 m0, s23, 0xe000
	s_nop 0
	global_load_lds_dwordx4 v140, s[14:15]
	s_waitcnt vmcnt(8)
	s_waitcnt lgkmcnt(0)
	v_mfma_f32_16x16x32_bf16 v[126:129], v[152:155], v[184:187], v[126:129]
	v_mfma_f32_16x16x32_bf16 v[126:129], v[156:159], v[188:191], v[126:129]
	s_barrier
	s_setprio 1
	v_mfma_f32_16x16x32_bf16 v[122:125], v[164:167], v[188:191], v[122:125]
	v_mfma_f32_16x16x32_bf16 v[122:125], v[160:163], v[184:187], v[122:125]
	v_mfma_f32_16x16x32_bf16 v[106:109], v[160:163], v[204:207], v[106:109]
	v_mfma_f32_16x16x32_bf16 v[106:109], v[164:167], v[208:211], v[106:109]
	v_mfma_f32_16x16x32_bf16 v[110:113], v[156:159], v[208:211], v[110:113]
	v_mfma_f32_16x16x32_bf16 v[110:113], v[152:155], v[204:207], v[110:113]
	v_mfma_f32_16x16x32_bf16 v[94:97], v[152:155], v[212:215], v[94:97]
	v_mfma_f32_16x16x32_bf16 v[94:97], v[156:159], v[216:219], v[94:97]
	v_mfma_f32_16x16x32_bf16 v[90:93], v[164:167], v[216:219], v[90:93]
	v_mfma_f32_16x16x32_bf16 v[90:93], v[160:163], v[212:215], v[90:93]
	v_mfma_f32_16x16x32_bf16 v[74:77], v[160:163], v[220:223], v[74:77]
	v_mfma_f32_16x16x32_bf16 v[74:77], v[164:167], v[224:227], v[74:77]
	v_mfma_f32_16x16x32_bf16 v[78:81], v[156:159], v[224:227], v[78:81]
	v_mfma_f32_16x16x32_bf16 v[78:81], v[152:155], v[220:223], v[78:81]
	v_mfma_f32_16x16x32_bf16 v[118:121], v[168:171], v[184:187], v[118:121]
	v_mfma_f32_16x16x32_bf16 v[118:121], v[172:175], v[188:191], v[118:121]
	v_mfma_f32_16x16x32_bf16 v[114:117], v[180:183], v[188:191], v[114:117]
	v_mfma_f32_16x16x32_bf16 v[114:117], v[176:179], v[184:187], v[114:117]
	v_mfma_f32_16x16x32_bf16 v[98:101], v[176:179], v[204:207], v[98:101]
	v_mfma_f32_16x16x32_bf16 v[98:101], v[180:183], v[208:211], v[98:101]
	v_mfma_f32_16x16x32_bf16 v[102:105], v[172:175], v[208:211], v[102:105]
	v_mfma_f32_16x16x32_bf16 v[102:105], v[168:171], v[204:207], v[102:105]
	v_mfma_f32_16x16x32_bf16 v[86:89], v[168:171], v[212:215], v[86:89]
	v_mfma_f32_16x16x32_bf16 v[86:89], v[172:175], v[216:219], v[86:89]
	v_mfma_f32_16x16x32_bf16 v[82:85], v[180:183], v[216:219], v[82:85]
	v_mfma_f32_16x16x32_bf16 v[82:85], v[176:179], v[212:215], v[82:85]
	v_mfma_f32_16x16x32_bf16 v[66:69], v[176:179], v[220:223], v[66:69]
	v_mfma_f32_16x16x32_bf16 v[66:69], v[180:183], v[224:227], v[66:69]
	v_mfma_f32_16x16x32_bf16 v[70:73], v[172:175], v[224:227], v[70:73]
	v_mfma_f32_16x16x32_bf16 v[70:73], v[168:171], v[220:223], v[70:73]
	s_setprio 0
	s_barrier
	ds_read_b128 v[184:187], v151 offset:16384
	ds_read_b128 v[188:191], v151 offset:17408
	ds_read_b128 v[204:207], v151 offset:18432
	ds_read_b128 v[208:211], v151 offset:19456
	ds_read_b128 v[212:215], v151 offset:20480
	ds_read_b128 v[216:219], v151 offset:21504
	ds_read_b128 v[220:223], v151 offset:22528
	ds_read_b128 v[224:227], v151 offset:23552
	s_add_i32 s40, s40, s22
	s_mov_b32 m0, s40
	s_nop 0
	global_load_lds_dwordx4 v134, s[16:17]
	s_add_i32 m0, s40, 0x2000
	s_add_u32 s40, s16, 0x80000
	s_addc_u32 s41, s17, 0
	s_add_i32 s42, s42, s22
	global_load_lds_dwordx4 v130, s[16:17]
	s_mov_b32 m0, s42
	s_nop 0
	global_load_lds_dwordx4 v134, s[40:41]
	s_add_i32 m0, s42, 0x2000
	s_nop 0
	global_load_lds_dwordx4 v130, s[40:41]
	s_waitcnt vmcnt(6)
	s_waitcnt lgkmcnt(0)
	v_mfma_f32_16x16x32_bf16 v[62:65], v[152:155], v[184:187], v[62:65]
	v_mfma_f32_16x16x32_bf16 v[62:65], v[156:159], v[188:191], v[62:65]
	s_barrier
	s_setprio 1
	v_mfma_f32_16x16x32_bf16 v[58:61], v[164:167], v[188:191], v[58:61]
	v_mfma_f32_16x16x32_bf16 v[58:61], v[160:163], v[184:187], v[58:61]
	v_mfma_f32_16x16x32_bf16 v[42:45], v[160:163], v[204:207], v[42:45]
	v_mfma_f32_16x16x32_bf16 v[42:45], v[164:167], v[208:211], v[42:45]
	v_mfma_f32_16x16x32_bf16 v[46:49], v[156:159], v[208:211], v[46:49]
	v_mfma_f32_16x16x32_bf16 v[46:49], v[152:155], v[204:207], v[46:49]
	v_mfma_f32_16x16x32_bf16 v[30:33], v[152:155], v[212:215], v[30:33]
	v_mfma_f32_16x16x32_bf16 v[30:33], v[156:159], v[216:219], v[30:33]
	v_mfma_f32_16x16x32_bf16 v[26:29], v[164:167], v[216:219], v[26:29]
	v_mfma_f32_16x16x32_bf16 v[26:29], v[160:163], v[212:215], v[26:29]
	v_mfma_f32_16x16x32_bf16 v[10:13], v[160:163], v[220:223], v[10:13]
	v_mfma_f32_16x16x32_bf16 v[10:13], v[164:167], v[224:227], v[10:13]
	v_mfma_f32_16x16x32_bf16 v[14:17], v[156:159], v[224:227], v[14:17]
	v_mfma_f32_16x16x32_bf16 v[14:17], v[152:155], v[220:223], v[14:17]
	v_mfma_f32_16x16x32_bf16 v[54:57], v[168:171], v[184:187], v[54:57]
	v_mfma_f32_16x16x32_bf16 v[54:57], v[172:175], v[188:191], v[54:57]
	v_mfma_f32_16x16x32_bf16 v[50:53], v[180:183], v[188:191], v[50:53]
	v_mfma_f32_16x16x32_bf16 v[50:53], v[176:179], v[184:187], v[50:53]
	v_mfma_f32_16x16x32_bf16 v[34:37], v[176:179], v[204:207], v[34:37]
	v_mfma_f32_16x16x32_bf16 v[34:37], v[180:183], v[208:211], v[34:37]
	v_mfma_f32_16x16x32_bf16 v[38:41], v[172:175], v[208:211], v[38:41]
	v_mfma_f32_16x16x32_bf16 v[38:41], v[168:171], v[204:207], v[38:41]
	v_mfma_f32_16x16x32_bf16 v[22:25], v[168:171], v[212:215], v[22:25]
	v_mfma_f32_16x16x32_bf16 v[22:25], v[172:175], v[216:219], v[22:25]
	v_mfma_f32_16x16x32_bf16 v[18:21], v[180:183], v[216:219], v[18:21]
	v_mfma_f32_16x16x32_bf16 v[18:21], v[176:179], v[212:215], v[18:21]
	v_mfma_f32_16x16x32_bf16 v[2:5], v[176:179], v[220:223], v[2:5]
	v_mfma_f32_16x16x32_bf16 v[2:5], v[180:183], v[224:227], v[2:5]
	v_mfma_f32_16x16x32_bf16 v[6:9], v[172:175], v[224:227], v[6:9]
	v_mfma_f32_16x16x32_bf16 v[6:9], v[168:171], v[220:223], v[6:9]
	s_setprio 0
	s_barrier
	s_mov_b32 m0, s23
	s_nop 0
	global_load_lds_dwordx4 v136, s[18:19]
	s_mov_b32 m0, s24
	s_nop 0
	global_load_lds_dwordx4 v132, s[18:19]
	ds_read_b128 v[152:155], v145 offset:32768
	ds_read_b128 v[156:159], v145 offset:33792
	ds_read_b128 v[160:163], v145 offset:34816
	ds_read_b128 v[164:167], v145 offset:35840
	ds_read_b128 v[168:171], v145 offset:49152
	ds_read_b128 v[172:175], v145 offset:50176
	ds_read_b128 v[176:179], v145 offset:51200
	ds_read_b128 v[180:183], v145 offset:52224
	ds_read_b128 v[184:187], v151 offset:32768
	ds_read_b128 v[188:191], v151 offset:33792
	ds_read_b128 v[204:207], v151 offset:34816
	ds_read_b128 v[208:211], v151 offset:35840
	ds_read_b128 v[212:215], v151 offset:36864
	ds_read_b128 v[216:219], v151 offset:37888
	ds_read_b128 v[220:223], v151 offset:38912
	ds_read_b128 v[224:227], v151 offset:39936
	s_add_i32 s40, 0, 0x18000
	s_add_i32 s41, 0, 0x1c000
	s_add_u32 s18, s18, 0x80000
	s_addc_u32 s19, s19, 0
	s_mov_b32 m0, s25
	s_nop 0
	global_load_lds_dwordx4 v136, s[18:19]
	s_mov_b32 m0, s26
	s_nop 0
	global_load_lds_dwordx4 v132, s[18:19]
	s_waitcnt vmcnt(8)
	s_waitcnt lgkmcnt(0)
	v_mfma_f32_16x16x32_bf16 v[126:129], v[152:155], v[184:187], v[126:129]
	v_mfma_f32_16x16x32_bf16 v[126:129], v[156:159], v[188:191], v[126:129]
	s_barrier
	s_setprio 1
	v_mfma_f32_16x16x32_bf16 v[122:125], v[164:167], v[188:191], v[122:125]
	v_mfma_f32_16x16x32_bf16 v[122:125], v[160:163], v[184:187], v[122:125]
	v_mfma_f32_16x16x32_bf16 v[106:109], v[160:163], v[204:207], v[106:109]
	v_mfma_f32_16x16x32_bf16 v[106:109], v[164:167], v[208:211], v[106:109]
	v_mfma_f32_16x16x32_bf16 v[110:113], v[156:159], v[208:211], v[110:113]
	v_mfma_f32_16x16x32_bf16 v[110:113], v[152:155], v[204:207], v[110:113]
	v_mfma_f32_16x16x32_bf16 v[94:97], v[152:155], v[212:215], v[94:97]
	v_mfma_f32_16x16x32_bf16 v[94:97], v[156:159], v[216:219], v[94:97]
	v_mfma_f32_16x16x32_bf16 v[90:93], v[164:167], v[216:219], v[90:93]
	v_mfma_f32_16x16x32_bf16 v[90:93], v[160:163], v[212:215], v[90:93]
	v_mfma_f32_16x16x32_bf16 v[74:77], v[160:163], v[220:223], v[74:77]
	v_mfma_f32_16x16x32_bf16 v[74:77], v[164:167], v[224:227], v[74:77]
	v_mfma_f32_16x16x32_bf16 v[78:81], v[156:159], v[224:227], v[78:81]
	v_mfma_f32_16x16x32_bf16 v[78:81], v[152:155], v[220:223], v[78:81]
	v_mfma_f32_16x16x32_bf16 v[118:121], v[168:171], v[184:187], v[118:121]
	v_mfma_f32_16x16x32_bf16 v[118:121], v[172:175], v[188:191], v[118:121]
	v_mfma_f32_16x16x32_bf16 v[114:117], v[180:183], v[188:191], v[114:117]
	v_mfma_f32_16x16x32_bf16 v[114:117], v[176:179], v[184:187], v[114:117]
	v_mfma_f32_16x16x32_bf16 v[98:101], v[176:179], v[204:207], v[98:101]
	v_mfma_f32_16x16x32_bf16 v[98:101], v[180:183], v[208:211], v[98:101]
	v_mfma_f32_16x16x32_bf16 v[102:105], v[172:175], v[208:211], v[102:105]
	v_mfma_f32_16x16x32_bf16 v[102:105], v[168:171], v[204:207], v[102:105]
	v_mfma_f32_16x16x32_bf16 v[86:89], v[168:171], v[212:215], v[86:89]
	v_mfma_f32_16x16x32_bf16 v[86:89], v[172:175], v[216:219], v[86:89]
	v_mfma_f32_16x16x32_bf16 v[82:85], v[180:183], v[216:219], v[82:85]
	v_mfma_f32_16x16x32_bf16 v[82:85], v[176:179], v[212:215], v[82:85]
	v_mfma_f32_16x16x32_bf16 v[66:69], v[176:179], v[220:223], v[66:69]
	v_mfma_f32_16x16x32_bf16 v[66:69], v[180:183], v[224:227], v[66:69]
	v_mfma_f32_16x16x32_bf16 v[70:73], v[172:175], v[224:227], v[70:73]
	v_mfma_f32_16x16x32_bf16 v[70:73], v[168:171], v[220:223], v[70:73]
	s_setprio 0
	s_barrier
	ds_read_b128 v[184:187], v151 offset:49152
	ds_read_b128 v[188:191], v151 offset:50176
	ds_read_b128 v[204:207], v151 offset:51200
	ds_read_b128 v[208:211], v151 offset:52224
	ds_read_b128 v[212:215], v151 offset:53248
	ds_read_b128 v[216:219], v151 offset:54272
	ds_read_b128 v[220:223], v151 offset:55296
	ds_read_b128 v[224:227], v151 offset:56320
	s_add_i32 s18, s40, s22
	s_add_u32 vcc_lo, s16, s94
	s_addc_u32 vcc_hi, s17, s95
	s_mov_b32 m0, s18
	s_nop 0
	global_load_lds_dwordx4 v134, vcc
	s_add_i32 m0, s18, 0x2000
	s_add_u32 s16, s16, 0x80080
	s_addc_u32 s17, s17, 0
	s_add_i32 s18, s41, s22
	global_load_lds_dwordx4 v130, vcc
	s_mov_b32 m0, s18
	s_nop 0
	global_load_lds_dwordx4 v134, s[16:17]
	s_add_i32 m0, s18, 0x2000
	s_nop 0
	global_load_lds_dwordx4 v130, s[16:17]
	s_waitcnt vmcnt(6)
	s_waitcnt lgkmcnt(0)
	v_mfma_f32_16x16x32_bf16 v[62:65], v[152:155], v[184:187], v[62:65]
	v_mfma_f32_16x16x32_bf16 v[62:65], v[156:159], v[188:191], v[62:65]
	s_barrier
	s_setprio 1
	v_mfma_f32_16x16x32_bf16 v[58:61], v[164:167], v[188:191], v[58:61]
	v_mfma_f32_16x16x32_bf16 v[58:61], v[160:163], v[184:187], v[58:61]
	v_mfma_f32_16x16x32_bf16 v[42:45], v[160:163], v[204:207], v[42:45]
	v_mfma_f32_16x16x32_bf16 v[42:45], v[164:167], v[208:211], v[42:45]
	v_mfma_f32_16x16x32_bf16 v[46:49], v[156:159], v[208:211], v[46:49]
	v_mfma_f32_16x16x32_bf16 v[46:49], v[152:155], v[204:207], v[46:49]
	v_mfma_f32_16x16x32_bf16 v[30:33], v[152:155], v[212:215], v[30:33]
	v_mfma_f32_16x16x32_bf16 v[30:33], v[156:159], v[216:219], v[30:33]
	v_mfma_f32_16x16x32_bf16 v[26:29], v[164:167], v[216:219], v[26:29]
	v_mfma_f32_16x16x32_bf16 v[26:29], v[160:163], v[212:215], v[26:29]
	v_mfma_f32_16x16x32_bf16 v[10:13], v[160:163], v[220:223], v[10:13]
	v_mfma_f32_16x16x32_bf16 v[10:13], v[164:167], v[224:227], v[10:13]
	s_add_i32 s39, s39, 2
	v_mfma_f32_16x16x32_bf16 v[14:17], v[156:159], v[224:227], v[14:17]
	v_mfma_f32_16x16x32_bf16 v[14:17], v[152:155], v[220:223], v[14:17]
	s_add_u32 s14, s14, 0x100
	v_mfma_f32_16x16x32_bf16 v[54:57], v[168:171], v[184:187], v[54:57]
	v_mfma_f32_16x16x32_bf16 v[54:57], v[172:175], v[188:191], v[54:57]
	s_addc_u32 s15, s15, 0
	v_mfma_f32_16x16x32_bf16 v[50:53], v[180:183], v[188:191], v[50:53]
	v_mfma_f32_16x16x32_bf16 v[50:53], v[176:179], v[184:187], v[50:53]
	s_add_u32 s37, s37, 0x100
	v_mfma_f32_16x16x32_bf16 v[34:37], v[176:179], v[204:207], v[34:37]
	v_mfma_f32_16x16x32_bf16 v[34:37], v[180:183], v[208:211], v[34:37]
	s_addc_u32 s38, s38, 0
	v_mfma_f32_16x16x32_bf16 v[38:41], v[172:175], v[208:211], v[38:41]
	v_mfma_f32_16x16x32_bf16 v[38:41], v[168:171], v[204:207], v[38:41]
	s_cmp_gt_u32 s39, 29
	v_mfma_f32_16x16x32_bf16 v[22:25], v[168:171], v[212:215], v[22:25]
	v_mfma_f32_16x16x32_bf16 v[22:25], v[172:175], v[216:219], v[22:25]
	v_mfma_f32_16x16x32_bf16 v[18:21], v[180:183], v[216:219], v[18:21]
	v_mfma_f32_16x16x32_bf16 v[18:21], v[176:179], v[212:215], v[18:21]
	v_mfma_f32_16x16x32_bf16 v[2:5], v[176:179], v[220:223], v[2:5]
	v_mfma_f32_16x16x32_bf16 v[2:5], v[180:183], v[224:227], v[2:5]
	v_mfma_f32_16x16x32_bf16 v[6:9], v[172:175], v[224:227], v[6:9]
	v_mfma_f32_16x16x32_bf16 v[6:9], v[168:171], v[220:223], v[6:9]
	s_setprio 0
	s_barrier
	s_cbranch_scc0 .LBB0_530

.LBB0_538:
	v_mov_b32_e32 v2, v195
	s_andn2_b64 vcc, exec, s[0:1]
	s_cbranch_vccnz .LBB0_525
	s_branch .LBB0_525

.LBB0_767:
	s_and_b32 s54, s39, 0x2000
	s_add_u32 s22, s22, 0x80
	s_addc_u32 s23, s23, 0
	v_add_u32_e32 v130, s54, v199
	s_add_u32 s54, s24, 0x100
	s_waitcnt lgkmcnt(0)
	v_mov_b64_e32 v[8:9], v[4:5]
	v_mov_b64_e32 v[20:21], v[4:5]
	v_mov_b64_e32 v[24:25], v[4:5]
	v_mov_b64_e32 v[36:37], v[4:5]
	v_mov_b64_e32 v[40:41], v[4:5]
	v_mov_b64_e32 v[52:53], v[4:5]
	v_mov_b64_e32 v[56:57], v[4:5]
	v_mov_b64_e32 v[12:13], v[4:5]
	v_mov_b64_e32 v[16:17], v[4:5]
	v_mov_b64_e32 v[28:29], v[4:5]
	v_mov_b64_e32 v[32:33], v[4:5]
	v_mov_b64_e32 v[44:45], v[4:5]
	v_mov_b64_e32 v[48:49], v[4:5]
	v_mov_b64_e32 v[60:61], v[4:5]
	v_mov_b64_e32 v[64:65], v[4:5]
	v_mov_b64_e32 v[68:69], v[4:5]
	v_mov_b64_e32 v[72:73], v[4:5]
	v_mov_b64_e32 v[84:85], v[4:5]
	v_mov_b64_e32 v[88:89], v[4:5]
	v_mov_b64_e32 v[100:101], v[4:5]
	v_mov_b64_e32 v[104:105], v[4:5]
	v_mov_b64_e32 v[116:117], v[4:5]
	v_mov_b64_e32 v[120:121], v[4:5]
	v_mov_b64_e32 v[76:77], v[4:5]
	v_mov_b64_e32 v[80:81], v[4:5]
	v_mov_b64_e32 v[92:93], v[4:5]
	v_mov_b64_e32 v[96:97], v[4:5]
	v_mov_b64_e32 v[108:109], v[4:5]
	v_mov_b64_e32 v[112:113], v[4:5]
	v_mov_b64_e32 v[124:125], v[4:5]
	v_mov_b64_e32 v[128:129], v[4:5]
	s_addc_u32 s55, s25, 0
	s_mov_b32 s56, 2
	v_mov_b64_e32 v[6:7], v[2:3]
	v_mov_b64_e32 v[18:19], v[2:3]
	v_mov_b64_e32 v[22:23], v[2:3]
	v_mov_b64_e32 v[34:35], v[2:3]
	v_mov_b64_e32 v[38:39], v[2:3]
	v_mov_b64_e32 v[50:51], v[2:3]
	v_mov_b64_e32 v[54:55], v[2:3]
	v_mov_b64_e32 v[10:11], v[2:3]
	v_mov_b64_e32 v[14:15], v[2:3]
	v_mov_b64_e32 v[26:27], v[2:3]
	v_mov_b64_e32 v[30:31], v[2:3]
	v_mov_b64_e32 v[42:43], v[2:3]
	v_mov_b64_e32 v[46:47], v[2:3]
	v_mov_b64_e32 v[58:59], v[2:3]
	v_mov_b64_e32 v[62:63], v[2:3]
	v_mov_b64_e32 v[66:67], v[2:3]
	v_mov_b64_e32 v[70:71], v[2:3]
	v_mov_b64_e32 v[82:83], v[2:3]
	v_mov_b64_e32 v[86:87], v[2:3]
	v_mov_b64_e32 v[98:99], v[2:3]
	v_mov_b64_e32 v[102:103], v[2:3]
	v_mov_b64_e32 v[114:115], v[2:3]
	v_mov_b64_e32 v[118:119], v[2:3]
	v_mov_b64_e32 v[74:75], v[2:3]
	v_mov_b64_e32 v[78:79], v[2:3]
	v_mov_b64_e32 v[90:91], v[2:3]
	v_mov_b64_e32 v[94:95], v[2:3]
	v_mov_b64_e32 v[106:107], v[2:3]
	v_mov_b64_e32 v[110:111], v[2:3]
	v_mov_b64_e32 v[122:123], v[2:3]
	v_mov_b64_e32 v[126:127], v[2:3]
	s_cmp_eq_u32 s21, 0
	s_cbranch_scc1 .Lrealign_3
	s_andn2_b64 vcc, exec, s[6:7]
	s_cbranch_vccnz .Lrealign_3
	s_barrier
.Lrealign_3:
	s_branch .LBB0_769

.LBB0_775:
	s_or_b64 exec, exec, s[20:21]
	s_and_b64 vcc, exec, s[4:5]
	s_mov_b64 s[4:5], -1
	v_mov_b64_e32 v[244:245], v[202:203]
	s_cbranch_vccnz .LBB0_760
	v_mov_b32_e32 v2, v195
	v_mov_b32_e32 v3, v0
	v_readlane_b32 s4, v254, 9
	v_ashrrev_i32_e32 v4, 1, v3
	v_lshlrev_b32_e32 v3, 2, v3
	v_and_b32_e32 v3, 4, v3
	v_mul_u32_u24_e32 v5, 0x8900, v3
	v_lshlrev_b32_e32 v194, 3, v5
	v_readlane_b32 s5, v254, 10
	s_ashr_i32 s17, s16, 31
	v_ashrrev_i32_e32 v5, 31, v4
	v_lshl_add_u64 v[6:7], s[4:5], 0, v[194:195]
	s_lshl_b64 s[4:5], s[16:17], 11
	v_lshl_add_u64 v[6:7], v[6:7], 0, s[4:5]
	v_lshl_add_u64 v[6:7], v[4:5], 3, v[6:7]
	s_mov_b32 s4, 0x44000
	s_waitcnt lgkmcnt(6)
	v_add_co_u32_e32 v10, vcc, s4, v6
	s_mov_b32 s4, 0x89000
	s_nop 0
	v_addc_co_u32_e32 v11, vcc, 0, v7, vcc
	s_waitcnt lgkmcnt(5)
	v_add_co_u32_e32 v12, vcc, s4, v6
	s_mov_b32 s4, 0xcd000
	s_waitcnt lgkmcnt(4)
	v_addc_co_u32_e32 v13, vcc, 0, v7, vcc
	global_load_dwordx2 v[8:9], v[6:7], off
	s_waitcnt lgkmcnt(3)
	v_lshlrev_b32_e32 v14, 5, v4
	global_load_dwordx2 v[10:11], v[10:11], off offset:2048
	v_add_co_u32_e32 v6, vcc, s4, v6
	global_load_dwordx2 v[12:13], v[12:13], off
	s_nop 0
	v_addc_co_u32_e32 v7, vcc, 0, v7, vcc
	global_load_dwordx2 v[6:7], v[6:7], off offset:2048
	s_lshl_b32 s4, s50, 13
	s_and_b32 s4, s4, 0x2000
	s_add_i32 s4, s4, 0
	s_add_i32 s4, s4, 0x20000
	v_lshlrev_b32_e32 v3, 2, v3
	v_add3_u32 v3, s4, v14, v3
	s_andn2_b64 vcc, exec, s[6:7]
	s_waitcnt vmcnt(3)
	v_ffbh_u32_e32 v4, v9
	s_waitcnt lgkmcnt(2)
	v_min_u32_e32 v15, 32, v4
	v_lshlrev_b64 v[4:5], v15, v[8:9]
	s_waitcnt vmcnt(2)
	v_ffbh_u32_e32 v8, v11
	v_min_u32_e32 v4, 1, v4
	s_waitcnt vmcnt(1)
	v_ffbh_u32_e32 v9, v13
	v_min_u32_e32 v8, 32, v8
	s_waitcnt lgkmcnt(0)
	v_min_u32_e32 v17, 32, v9
	s_waitcnt vmcnt(0)
	v_ffbh_u32_e32 v16, v7
	v_min_u32_e32 v16, 32, v16
	v_or_b32_e32 v18, v5, v4
	v_lshlrev_b64 v[4:5], v8, v[10:11]
	v_sub_u32_e32 v10, 32, v8
	v_lshlrev_b64 v[8:9], v17, v[12:13]
	v_lshlrev_b64 v[6:7], v16, v[6:7]
	v_min_u32_e32 v4, 1, v4
	v_min_u32_e32 v8, 1, v8
	v_min_u32_e32 v6, 1, v6
	v_or_b32_e32 v4, v5, v4
	v_or_b32_e32 v5, v9, v8
	v_or_b32_e32 v6, v7, v6
	v_cvt_f32_u32_e32 v13, v18
	v_cvt_f32_u32_e32 v7, v4
	v_cvt_f32_u32_e32 v5, v5
	v_cvt_f32_u32_e32 v6, v6
	v_sub_u32_e32 v15, 32, v15
	v_sub_u32_e32 v11, 32, v17
	v_sub_u32_e32 v12, 32, v16
	v_ldexp_f32 v4, v13, v15
	v_ldexp_f32 v7, v7, v10
	v_ldexp_f32 v5, v5, v11
	v_ldexp_f32 v6, v6, v12
	v_fmamk_f32 v4, v4, 0x31000000, v1
	v_fmamk_f32 v7, v7, 0x31000000, v1
	v_fmamk_f32 v8, v5, 0x31000000, v1
	v_fmamk_f32 v9, v6, 0x31000000, v1
	v_rsq_f32_e32 v4, v4
	v_rsq_f32_e32 v5, v7
	v_rsq_f32_e32 v6, v8
	v_rsq_f32_e32 v7, v9
	ds_write_b128 v3, v[4:7]
	s_cbranch_vccnz .LBB0_759
	s_branch .LBB0_759

.LBB0_795:
	s_andn2_b64 vcc, exec, s[38:39]
	s_cbranch_vccnz .LBB0_800
	s_add_u32 s23, s36, s12
	s_addc_u32 s27, s37, 0
	s_lshl_b32 s19, s29, 13
	s_and_b32 s19, s19, 0x2000
	s_waitcnt lgkmcnt(0)
	v_mov_b64_e32 v[8:9], v[4:5]
	v_mov_b64_e32 v[20:21], v[4:5]
	v_mov_b64_e32 v[24:25], v[4:5]
	v_mov_b64_e32 v[36:37], v[4:5]
	v_mov_b64_e32 v[40:41], v[4:5]
	v_mov_b64_e32 v[52:53], v[4:5]
	v_mov_b64_e32 v[56:57], v[4:5]
	v_mov_b64_e32 v[12:13], v[4:5]
	v_mov_b64_e32 v[16:17], v[4:5]
	v_mov_b64_e32 v[28:29], v[4:5]
	v_mov_b64_e32 v[32:33], v[4:5]
	v_mov_b64_e32 v[44:45], v[4:5]
	v_mov_b64_e32 v[48:49], v[4:5]
	v_mov_b64_e32 v[60:61], v[4:5]
	v_mov_b64_e32 v[64:65], v[4:5]
	v_mov_b64_e32 v[68:69], v[4:5]
	v_mov_b64_e32 v[72:73], v[4:5]
	v_mov_b64_e32 v[84:85], v[4:5]
	v_mov_b64_e32 v[88:89], v[4:5]
	v_mov_b64_e32 v[100:101], v[4:5]
	v_mov_b64_e32 v[104:105], v[4:5]
	v_mov_b64_e32 v[116:117], v[4:5]
	v_mov_b64_e32 v[120:121], v[4:5]
	v_mov_b64_e32 v[76:77], v[4:5]
	v_mov_b64_e32 v[80:81], v[4:5]
	v_mov_b64_e32 v[92:93], v[4:5]
	v_mov_b64_e32 v[96:97], v[4:5]
	v_mov_b64_e32 v[108:109], v[4:5]
	v_mov_b64_e32 v[112:113], v[4:5]
	v_mov_b64_e32 v[124:125], v[4:5]
	v_mov_b64_e32 v[128:129], v[4:5]
	v_add_u32_e32 v130, s19, v236
	s_mov_b32 s84, 2
	v_mov_b64_e32 v[6:7], v[2:3]
	v_mov_b64_e32 v[18:19], v[2:3]
	v_mov_b64_e32 v[22:23], v[2:3]
	v_mov_b64_e32 v[34:35], v[2:3]
	v_mov_b64_e32 v[38:39], v[2:3]
	v_mov_b64_e32 v[50:51], v[2:3]
	v_mov_b64_e32 v[54:55], v[2:3]
	v_mov_b64_e32 v[10:11], v[2:3]
	v_mov_b64_e32 v[14:15], v[2:3]
	v_mov_b64_e32 v[26:27], v[2:3]
	v_mov_b64_e32 v[30:31], v[2:3]
	v_mov_b64_e32 v[42:43], v[2:3]
	v_mov_b64_e32 v[46:47], v[2:3]
	v_mov_b64_e32 v[58:59], v[2:3]
	v_mov_b64_e32 v[62:63], v[2:3]
	v_mov_b64_e32 v[66:67], v[2:3]
	v_mov_b64_e32 v[70:71], v[2:3]
	v_mov_b64_e32 v[82:83], v[2:3]
	v_mov_b64_e32 v[86:87], v[2:3]
	v_mov_b64_e32 v[98:99], v[2:3]
	v_mov_b64_e32 v[102:103], v[2:3]
	v_mov_b64_e32 v[114:115], v[2:3]
	v_mov_b64_e32 v[118:119], v[2:3]
	v_mov_b64_e32 v[74:75], v[2:3]
	v_mov_b64_e32 v[78:79], v[2:3]
	v_mov_b64_e32 v[90:91], v[2:3]
	v_mov_b64_e32 v[94:95], v[2:3]
	v_mov_b64_e32 v[106:107], v[2:3]
	v_mov_b64_e32 v[110:111], v[2:3]
	v_mov_b64_e32 v[122:123], v[2:3]
	v_mov_b64_e32 v[126:127], v[2:3]
	s_cmp_eq_u32 s29, 0
	s_cbranch_scc1 .Lrealign_4
	s_andn2_b64 vcc, exec, s[0:1]
	s_cbranch_vccnz .Lrealign_4
	s_barrier

.LBB0_830:
	v_mov_b32_e32 v2, v195
	v_mov_b32_e32 v3, v0
	v_readlane_b32 s4, v254, 9
	v_ashrrev_i32_e32 v4, 1, v3
	v_lshlrev_b32_e32 v3, 2, v3
	v_and_b32_e32 v3, 4, v3
	v_mul_u32_u24_e32 v5, 0x8900, v3
	v_lshlrev_b32_e32 v194, 3, v5
	v_readlane_b32 s5, v254, 10
	s_ashr_i32 s17, s16, 31
	v_ashrrev_i32_e32 v5, 31, v4
	v_lshl_add_u64 v[6:7], s[4:5], 0, v[194:195]
	s_lshl_b64 s[4:5], s[16:17], 11
	v_lshl_add_u64 v[6:7], v[6:7], 0, s[4:5]
	v_lshl_add_u64 v[6:7], v[4:5], 3, v[6:7]
	s_mov_b32 s4, 0x44000
	s_waitcnt lgkmcnt(0)
	v_add_co_u32_e32 v10, vcc, s4, v6
	s_mov_b32 s4, 0x89000
	s_nop 0
	v_addc_co_u32_e32 v11, vcc, 0, v7, vcc
	v_add_co_u32_e32 v12, vcc, s4, v6
	s_mov_b32 s4, 0xcd000
	s_nop 0
	v_addc_co_u32_e32 v13, vcc, 0, v7, vcc
	global_load_dwordx2 v[8:9], v[6:7], off
	v_add_co_u32_e32 v6, vcc, s4, v6
	v_lshlrev_b32_e32 v14, 5, v4
	s_nop 0
	v_addc_co_u32_e32 v7, vcc, 0, v7, vcc
	global_load_dwordx2 v[10:11], v[10:11], off offset:2048
	s_nop 0
	global_load_dwordx2 v[12:13], v[12:13], off
	s_nop 0
	global_load_dwordx2 v[6:7], v[6:7], off offset:2048
	s_lshl_b32 s4, s65, 13
	s_and_b32 s4, s4, 0x2000
	s_add_i32 s4, s4, 0
	s_add_i32 s4, s4, 0x20000
	v_lshlrev_b32_e32 v3, 2, v3
	v_add3_u32 v3, s4, v14, v3
	s_andn2_b64 vcc, exec, s[0:1]
	s_waitcnt vmcnt(0)
	v_ffbh_u32_e32 v4, v9
	v_min_u32_e32 v15, 32, v4
	v_lshlrev_b64 v[4:5], v15, v[8:9]
	v_min_u32_e32 v4, 1, v4
	v_ffbh_u32_e32 v16, v11
	v_ffbh_u32_e32 v17, v13
	v_ffbh_u32_e32 v18, v7
	v_min_u32_e32 v16, 32, v16
	v_min_u32_e32 v17, 32, v17
	v_min_u32_e32 v18, 32, v18
	v_lshlrev_b64 v[8:9], v16, v[10:11]
	v_lshlrev_b64 v[10:11], v17, v[12:13]
	v_lshlrev_b64 v[6:7], v18, v[6:7]
	v_or_b32_e32 v4, v5, v4
	v_min_u32_e32 v5, 1, v8
	v_min_u32_e32 v8, 1, v10
	v_min_u32_e32 v6, 1, v6
	v_or_b32_e32 v5, v9, v5
	v_or_b32_e32 v8, v11, v8
	v_or_b32_e32 v6, v7, v6
	v_cvt_f32_u32_e32 v4, v4
	v_cvt_f32_u32_e32 v5, v5
	v_cvt_f32_u32_e32 v7, v8
	v_cvt_f32_u32_e32 v6, v6
	v_sub_u32_e32 v15, 32, v15
	v_sub_u32_e32 v16, 32, v16
	v_sub_u32_e32 v12, 32, v17
	v_sub_u32_e32 v13, 32, v18
	v_ldexp_f32 v4, v4, v15
	v_ldexp_f32 v5, v5, v16
	v_ldexp_f32 v7, v7, v12
	v_ldexp_f32 v6, v6, v13
	v_fmamk_f32 v4, v4, 0x31000000, v1
	v_fmamk_f32 v5, v5, 0x31000000, v1
	v_fmamk_f32 v7, v7, 0x31000000, v1
	v_fmamk_f32 v8, v6, 0x31000000, v1
	v_rsq_f32_e32 v4, v4
	v_rsq_f32_e32 v5, v5
	v_rsq_f32_e32 v6, v7
	v_rsq_f32_e32 v7, v8
	ds_write_b128 v3, v[4:7]
	s_cbranch_vccnz .LBB0_785
	s_branch .LBB0_785

.LBB0_849:
	s_add_u32 s18, s18, 0x80
	s_addc_u32 s19, s19, 0
	s_add_u32 s51, s20, 0x100
	s_waitcnt lgkmcnt(0)
	v_mov_b64_e32 v[8:9], v[4:5]
	v_mov_b64_e32 v[20:21], v[4:5]
	v_mov_b64_e32 v[24:25], v[4:5]
	v_mov_b64_e32 v[36:37], v[4:5]
	v_mov_b64_e32 v[40:41], v[4:5]
	v_mov_b64_e32 v[52:53], v[4:5]
	v_mov_b64_e32 v[56:57], v[4:5]
	v_mov_b64_e32 v[12:13], v[4:5]
	v_mov_b64_e32 v[16:17], v[4:5]
	v_mov_b64_e32 v[28:29], v[4:5]
	v_mov_b64_e32 v[32:33], v[4:5]
	v_mov_b64_e32 v[44:45], v[4:5]
	v_mov_b64_e32 v[48:49], v[4:5]
	v_mov_b64_e32 v[60:61], v[4:5]
	v_mov_b64_e32 v[64:65], v[4:5]
	v_mov_b64_e32 v[72:73], v[4:5]
	v_mov_b64_e32 v[76:77], v[4:5]
	v_mov_b64_e32 v[96:97], v[4:5]
	v_mov_b64_e32 v[104:105], v[4:5]
	s_waitcnt vmcnt(0)
	v_mov_b64_e32 v[124:125], v[4:5]
	v_mov_b64_e32 v[128:129], v[4:5]
	v_mov_b64_e32 v[148:149], v[4:5]
	v_mov_b64_e32 v[168:169], v[4:5]
	v_mov_b64_e32 v[88:89], v[4:5]
	v_mov_b64_e32 v[92:93], v[4:5]
	v_mov_b64_e32 v[112:113], v[4:5]
	v_mov_b64_e32 v[116:117], v[4:5]
	v_mov_b64_e32 v[136:137], v[4:5]
	v_mov_b64_e32 v[140:141], v[4:5]
	v_mov_b64_e32 v[184:185], v[4:5]
	v_mov_b64_e32 v[188:189], v[4:5]
	s_addc_u32 s54, s21, 0
	s_mov_b32 s20, 0
	v_mov_b64_e32 v[6:7], v[2:3]
	v_mov_b64_e32 v[18:19], v[2:3]
	v_mov_b64_e32 v[22:23], v[2:3]
	v_mov_b64_e32 v[34:35], v[2:3]
	v_mov_b64_e32 v[38:39], v[2:3]
	v_mov_b64_e32 v[50:51], v[2:3]
	v_mov_b64_e32 v[54:55], v[2:3]
	v_mov_b64_e32 v[10:11], v[2:3]
	v_mov_b64_e32 v[14:15], v[2:3]
	v_mov_b64_e32 v[26:27], v[2:3]
	v_mov_b64_e32 v[30:31], v[2:3]
	v_mov_b64_e32 v[42:43], v[2:3]
	v_mov_b64_e32 v[46:47], v[2:3]
	v_mov_b64_e32 v[58:59], v[2:3]
	v_mov_b64_e32 v[62:63], v[2:3]
	v_mov_b64_e32 v[70:71], v[2:3]
	v_mov_b64_e32 v[74:75], v[2:3]
	v_mov_b64_e32 v[94:95], v[2:3]
	v_mov_b64_e32 v[102:103], v[2:3]
	v_mov_b64_e32 v[122:123], v[2:3]
	v_mov_b64_e32 v[126:127], v[2:3]
	v_mov_b64_e32 v[146:147], v[2:3]
	v_mov_b64_e32 v[166:167], v[2:3]
	v_mov_b64_e32 v[86:87], v[2:3]
	v_mov_b64_e32 v[90:91], v[2:3]
	v_mov_b64_e32 v[110:111], v[2:3]
	v_mov_b64_e32 v[114:115], v[2:3]
	v_mov_b64_e32 v[134:135], v[2:3]
	v_mov_b64_e32 v[138:139], v[2:3]
	v_mov_b64_e32 v[182:183], v[2:3]
	v_mov_b64_e32 v[186:187], v[2:3]
	s_cmp_eq_u32 s36, 1
	s_cbranch_scc1 .Lrealign_5
	s_andn2_b64 vcc, exec, s[6:7]
	s_cbranch_vccnz .Lrealign_5
	s_barrier
.Lrealign_5:
.LBB0_850:
	s_sub_u32 vcc_lo, s18, s12
	s_subb_u32 vcc_hi, s19, 0
	s_mov_b32 m0, s33
	s_nop 0
	global_load_lds_dwordx4 v210, vcc
	s_mov_b32 m0, s34
	s_nop 0
	global_load_lds_dwordx4 v212, vcc
	ds_read_b128 v[66:69], v198
	ds_read_b128 v[78:81], v198 offset:1024
	ds_read_b128 v[82:85], v198 offset:2048
	ds_read_b128 v[98:101], v198 offset:3072
	ds_read_b128 v[106:109], v198 offset:16384
	ds_read_b128 v[118:121], v198 offset:17408
	ds_read_b128 v[130:133], v198 offset:18432
	ds_read_b128 v[142:145], v198 offset:19456
	ds_read_b128 v[150:153], v234
	ds_read_b128 v[154:157], v234 offset:1024
	ds_read_b128 v[158:161], v234 offset:2048
	ds_read_b128 v[162:165], v234 offset:3072
	ds_read_b128 v[170:173], v234 offset:4096
	ds_read_b128 v[174:177], v234 offset:5120
	ds_read_b128 v[178:181], v234 offset:6144
	ds_read_b128 v[190:193], v234 offset:7168
	s_add_i32 s55, s20, 2
	s_add_u32 s56, s18, 0x80
	s_addc_u32 s21, s19, 0
	s_add_i32 s58, 0, 0x10000
	s_cmp_eq_u32 s35, s20
	s_cselect_b32 s21, s1, s21
	s_cselect_b32 s20, s0, s56
	s_cselect_b32 s57, s17, s54
	s_cselect_b32 s56, s16, s51
	s_add_i32 s59, 0, 0x14000
	s_add_i32 m0, s26, 0xc000
	s_nop 0
	global_load_lds_dwordx4 v210, s[18:19]
	s_add_i32 m0, s26, 0xe000
	s_nop 0
	global_load_lds_dwordx4 v212, s[18:19]
	s_waitcnt vmcnt(8)
	s_waitcnt lgkmcnt(0)
	v_mfma_f32_16x16x32_bf16 v[186:189], v[66:69], v[150:153], v[186:189]
	v_mfma_f32_16x16x32_bf16 v[186:189], v[78:81], v[154:157], v[186:189]
	s_barrier
	s_setprio 1
	v_mfma_f32_16x16x32_bf16 v[182:185], v[98:101], v[154:157], v[182:185]
	v_mfma_f32_16x16x32_bf16 v[182:185], v[82:85], v[150:153], v[182:185]
	v_mfma_f32_16x16x32_bf16 v[134:137], v[82:85], v[158:161], v[134:137]
	v_mfma_f32_16x16x32_bf16 v[134:137], v[98:101], v[162:165], v[134:137]
	v_mfma_f32_16x16x32_bf16 v[138:141], v[78:81], v[162:165], v[138:141]
	v_mfma_f32_16x16x32_bf16 v[138:141], v[66:69], v[158:161], v[138:141]
	v_mfma_f32_16x16x32_bf16 v[114:117], v[66:69], v[170:173], v[114:117]
	v_mfma_f32_16x16x32_bf16 v[114:117], v[78:81], v[174:177], v[114:117]
	v_mfma_f32_16x16x32_bf16 v[110:113], v[98:101], v[174:177], v[110:113]
	v_mfma_f32_16x16x32_bf16 v[110:113], v[82:85], v[170:173], v[110:113]
	v_mfma_f32_16x16x32_bf16 v[86:89], v[82:85], v[178:181], v[86:89]
	v_mfma_f32_16x16x32_bf16 v[86:89], v[98:101], v[190:193], v[86:89]
	v_mfma_f32_16x16x32_bf16 v[90:93], v[78:81], v[190:193], v[90:93]
	v_mfma_f32_16x16x32_bf16 v[90:93], v[66:69], v[178:181], v[90:93]
	v_mfma_f32_16x16x32_bf16 v[166:169], v[106:109], v[150:153], v[166:169]
	v_mfma_f32_16x16x32_bf16 v[166:169], v[118:121], v[154:157], v[166:169]
	v_mfma_f32_16x16x32_bf16 v[146:149], v[142:145], v[154:157], v[146:149]
	v_mfma_f32_16x16x32_bf16 v[146:149], v[130:133], v[150:153], v[146:149]
	v_mfma_f32_16x16x32_bf16 v[122:125], v[130:133], v[158:161], v[122:125]
	v_mfma_f32_16x16x32_bf16 v[122:125], v[142:145], v[162:165], v[122:125]
	v_mfma_f32_16x16x32_bf16 v[126:129], v[118:121], v[162:165], v[126:129]
	v_mfma_f32_16x16x32_bf16 v[126:129], v[106:109], v[158:161], v[126:129]
	v_mfma_f32_16x16x32_bf16 v[102:105], v[106:109], v[170:173], v[102:105]
	v_mfma_f32_16x16x32_bf16 v[102:105], v[118:121], v[174:177], v[102:105]
	v_mfma_f32_16x16x32_bf16 v[94:97], v[142:145], v[174:177], v[94:97]
	v_mfma_f32_16x16x32_bf16 v[94:97], v[130:133], v[170:173], v[94:97]
	v_mfma_f32_16x16x32_bf16 v[70:73], v[130:133], v[178:181], v[70:73]
	v_mfma_f32_16x16x32_bf16 v[70:73], v[142:145], v[190:193], v[70:73]
	v_mfma_f32_16x16x32_bf16 v[74:77], v[118:121], v[190:193], v[74:77]
	v_mfma_f32_16x16x32_bf16 v[74:77], v[106:109], v[178:181], v[74:77]
	s_setprio 0
	s_barrier
	ds_read_b128 v[150:153], v234 offset:16384
	ds_read_b128 v[154:157], v234 offset:17408
	ds_read_b128 v[158:161], v234 offset:18432
	ds_read_b128 v[162:165], v234 offset:19456
	ds_read_b128 v[170:173], v234 offset:20480
	ds_read_b128 v[174:177], v234 offset:21504
	ds_read_b128 v[178:181], v234 offset:22528
	ds_read_b128 v[190:193], v234 offset:23552
	s_add_i32 s58, s58, s24
	v_lshl_add_u64 v[214:215], s[56:57], 0, v[194:195]
	s_mov_b32 m0, s58
	s_nop 0
	global_load_lds_dwordx4 v194, s[56:57]
	s_add_i32 m0, s58, 0x2000
	v_lshl_add_u64 v[216:217], s[56:57], 0, v[204:205]
	s_add_u32 s56, s56, s12
	s_addc_u32 s57, s57, 0
	s_add_i32 s58, s59, s24
	global_load_lds_dwordx4 v[216:217], off
	v_lshl_add_u64 v[218:219], s[56:57], 0, v[194:195]
	s_mov_b32 m0, s58
	v_lshl_add_u64 v[220:221], s[56:57], 0, v[204:205]
	global_load_lds_dwordx4 v194, s[56:57]
	s_add_i32 m0, s58, 0x2000
	s_nop 0
	global_load_lds_dwordx4 v204, s[56:57]
	s_waitcnt vmcnt(6)
	s_waitcnt lgkmcnt(0)
	v_mfma_f32_16x16x32_bf16 v[62:65], v[66:69], v[150:153], v[62:65]
	v_mfma_f32_16x16x32_bf16 v[62:65], v[78:81], v[154:157], v[62:65]
	s_barrier
	s_setprio 1
	v_mfma_f32_16x16x32_bf16 v[58:61], v[98:101], v[154:157], v[58:61]
	v_mfma_f32_16x16x32_bf16 v[58:61], v[82:85], v[150:153], v[58:61]
	v_mfma_f32_16x16x32_bf16 v[42:45], v[82:85], v[158:161], v[42:45]
	v_mfma_f32_16x16x32_bf16 v[42:45], v[98:101], v[162:165], v[42:45]
	v_mfma_f32_16x16x32_bf16 v[46:49], v[78:81], v[162:165], v[46:49]
	v_mfma_f32_16x16x32_bf16 v[46:49], v[66:69], v[158:161], v[46:49]
	v_mfma_f32_16x16x32_bf16 v[30:33], v[66:69], v[170:173], v[30:33]
	v_mfma_f32_16x16x32_bf16 v[30:33], v[78:81], v[174:177], v[30:33]
	v_mfma_f32_16x16x32_bf16 v[26:29], v[98:101], v[174:177], v[26:29]
	v_mfma_f32_16x16x32_bf16 v[26:29], v[82:85], v[170:173], v[26:29]
	v_mfma_f32_16x16x32_bf16 v[10:13], v[82:85], v[178:181], v[10:13]
	v_mfma_f32_16x16x32_bf16 v[10:13], v[98:101], v[190:193], v[10:13]
	v_mfma_f32_16x16x32_bf16 v[14:17], v[78:81], v[190:193], v[14:17]
	v_mfma_f32_16x16x32_bf16 v[14:17], v[66:69], v[178:181], v[14:17]
	v_mfma_f32_16x16x32_bf16 v[54:57], v[106:109], v[150:153], v[54:57]
	v_mfma_f32_16x16x32_bf16 v[54:57], v[118:121], v[154:157], v[54:57]
	v_mfma_f32_16x16x32_bf16 v[50:53], v[142:145], v[154:157], v[50:53]
	v_mfma_f32_16x16x32_bf16 v[50:53], v[130:133], v[150:153], v[50:53]
	v_mfma_f32_16x16x32_bf16 v[34:37], v[130:133], v[158:161], v[34:37]
	v_mfma_f32_16x16x32_bf16 v[34:37], v[142:145], v[162:165], v[34:37]
	v_mfma_f32_16x16x32_bf16 v[38:41], v[118:121], v[162:165], v[38:41]
	v_mfma_f32_16x16x32_bf16 v[38:41], v[106:109], v[158:161], v[38:41]
	v_mfma_f32_16x16x32_bf16 v[22:25], v[106:109], v[170:173], v[22:25]
	v_mfma_f32_16x16x32_bf16 v[22:25], v[118:121], v[174:177], v[22:25]
	v_mfma_f32_16x16x32_bf16 v[18:21], v[142:145], v[174:177], v[18:21]
	v_mfma_f32_16x16x32_bf16 v[18:21], v[130:133], v[170:173], v[18:21]
	v_mfma_f32_16x16x32_bf16 v[2:5], v[130:133], v[178:181], v[2:5]
	v_mfma_f32_16x16x32_bf16 v[2:5], v[142:145], v[190:193], v[2:5]
	v_mfma_f32_16x16x32_bf16 v[6:9], v[118:121], v[190:193], v[6:9]
	v_mfma_f32_16x16x32_bf16 v[6:9], v[106:109], v[178:181], v[6:9]
	s_setprio 0
	s_barrier
	s_mov_b32 m0, s26
	s_nop 0
	global_load_lds_dwordx4 v208, s[20:21]
	s_mov_b32 m0, s27
	s_nop 0
	global_load_lds_dwordx4 v206, s[20:21]
	ds_read_b128 v[66:69], v198 offset:32768
	ds_read_b128 v[78:81], v198 offset:33792
	ds_read_b128 v[82:85], v198 offset:34816
	ds_read_b128 v[98:101], v198 offset:35840
	ds_read_b128 v[106:109], v198 offset:49152
	ds_read_b128 v[118:121], v198 offset:50176
	ds_read_b128 v[130:133], v198 offset:51200
	ds_read_b128 v[142:145], v198 offset:52224
	ds_read_b128 v[150:153], v234 offset:32768
	ds_read_b128 v[154:157], v234 offset:33792
	ds_read_b128 v[158:161], v234 offset:34816
	ds_read_b128 v[162:165], v234 offset:35840
	ds_read_b128 v[170:173], v234 offset:36864
	ds_read_b128 v[174:177], v234 offset:37888
	ds_read_b128 v[178:181], v234 offset:38912
	ds_read_b128 v[190:193], v234 offset:39936
	s_add_i32 s56, 0, 0x18000
	s_add_i32 s57, 0, 0x1c000
	s_add_u32 s20, s20, s12
	s_addc_u32 s21, s21, 0
	s_mov_b32 m0, s28
	s_nop 0
	global_load_lds_dwordx4 v208, s[20:21]
	s_mov_b32 m0, s29
	s_nop 0
	global_load_lds_dwordx4 v206, s[20:21]
	s_waitcnt vmcnt(8)
	s_waitcnt lgkmcnt(0)
	v_mfma_f32_16x16x32_bf16 v[186:189], v[66:69], v[150:153], v[186:189]
	v_mfma_f32_16x16x32_bf16 v[186:189], v[78:81], v[154:157], v[186:189]
	s_barrier
	s_setprio 1
	v_mfma_f32_16x16x32_bf16 v[182:185], v[98:101], v[154:157], v[182:185]
	v_mfma_f32_16x16x32_bf16 v[182:185], v[82:85], v[150:153], v[182:185]
	v_mfma_f32_16x16x32_bf16 v[134:137], v[82:85], v[158:161], v[134:137]
	v_mfma_f32_16x16x32_bf16 v[134:137], v[98:101], v[162:165], v[134:137]
	v_mfma_f32_16x16x32_bf16 v[138:141], v[78:81], v[162:165], v[138:141]
	v_mfma_f32_16x16x32_bf16 v[138:141], v[66:69], v[158:161], v[138:141]
	v_mfma_f32_16x16x32_bf16 v[114:117], v[66:69], v[170:173], v[114:117]
	v_mfma_f32_16x16x32_bf16 v[114:117], v[78:81], v[174:177], v[114:117]
	v_mfma_f32_16x16x32_bf16 v[110:113], v[98:101], v[174:177], v[110:113]
	v_mfma_f32_16x16x32_bf16 v[110:113], v[82:85], v[170:173], v[110:113]
	v_mfma_f32_16x16x32_bf16 v[86:89], v[82:85], v[178:181], v[86:89]
	v_mfma_f32_16x16x32_bf16 v[86:89], v[98:101], v[190:193], v[86:89]
	v_mfma_f32_16x16x32_bf16 v[90:93], v[78:81], v[190:193], v[90:93]
	v_mfma_f32_16x16x32_bf16 v[90:93], v[66:69], v[178:181], v[90:93]
	v_mfma_f32_16x16x32_bf16 v[166:169], v[106:109], v[150:153], v[166:169]
	v_mfma_f32_16x16x32_bf16 v[166:169], v[118:121], v[154:157], v[166:169]
	v_mfma_f32_16x16x32_bf16 v[146:149], v[142:145], v[154:157], v[146:149]
	v_mfma_f32_16x16x32_bf16 v[146:149], v[130:133], v[150:153], v[146:149]
	v_mfma_f32_16x16x32_bf16 v[122:125], v[130:133], v[158:161], v[122:125]
	v_mfma_f32_16x16x32_bf16 v[122:125], v[142:145], v[162:165], v[122:125]
	v_mfma_f32_16x16x32_bf16 v[126:129], v[118:121], v[162:165], v[126:129]
	v_mfma_f32_16x16x32_bf16 v[126:129], v[106:109], v[158:161], v[126:129]
	v_mfma_f32_16x16x32_bf16 v[102:105], v[106:109], v[170:173], v[102:105]
	v_mfma_f32_16x16x32_bf16 v[102:105], v[118:121], v[174:177], v[102:105]
	v_mfma_f32_16x16x32_bf16 v[94:97], v[142:145], v[174:177], v[94:97]
	v_mfma_f32_16x16x32_bf16 v[94:97], v[130:133], v[170:173], v[94:97]
	v_mfma_f32_16x16x32_bf16 v[70:73], v[130:133], v[178:181], v[70:73]
	v_mfma_f32_16x16x32_bf16 v[70:73], v[142:145], v[190:193], v[70:73]
	v_mfma_f32_16x16x32_bf16 v[74:77], v[118:121], v[190:193], v[74:77]
	v_mfma_f32_16x16x32_bf16 v[74:77], v[106:109], v[178:181], v[74:77]
	s_setprio 0
	s_barrier
	ds_read_b128 v[150:153], v234 offset:49152
	ds_read_b128 v[154:157], v234 offset:50176
	ds_read_b128 v[158:161], v234 offset:51200
	ds_read_b128 v[162:165], v234 offset:52224
	ds_read_b128 v[170:173], v234 offset:53248
	ds_read_b128 v[174:177], v234 offset:54272
	ds_read_b128 v[178:181], v234 offset:55296
	ds_read_b128 v[190:193], v234 offset:56320
	s_add_i32 s20, s56, s24
	v_lshl_add_u64 v[214:215], v[214:215], 0, s[94:95]
	s_mov_b32 m0, s20
	s_nop 0
	global_load_lds_dwordx4 v[214:215], off
	v_lshl_add_u64 v[214:215], v[216:217], 0, s[94:95]
	s_add_i32 m0, s20, 0x2000
	s_add_i32 s20, s57, s24
	global_load_lds_dwordx4 v[214:215], off
	v_lshl_add_u64 v[214:215], v[218:219], 0, s[94:95]
	s_mov_b32 m0, s20
	s_nop 0
	global_load_lds_dwordx4 v[214:215], off
	v_lshl_add_u64 v[214:215], v[220:221], 0, s[94:95]
	s_add_i32 m0, s20, 0x2000
	s_nop 0
	global_load_lds_dwordx4 v[214:215], off
	s_waitcnt vmcnt(6)
	s_waitcnt lgkmcnt(0)
	v_mfma_f32_16x16x32_bf16 v[62:65], v[66:69], v[150:153], v[62:65]
	v_mfma_f32_16x16x32_bf16 v[62:65], v[78:81], v[154:157], v[62:65]
	s_barrier
	s_setprio 1
	v_mfma_f32_16x16x32_bf16 v[58:61], v[98:101], v[154:157], v[58:61]
	v_mfma_f32_16x16x32_bf16 v[58:61], v[82:85], v[150:153], v[58:61]
	v_mfma_f32_16x16x32_bf16 v[42:45], v[82:85], v[158:161], v[42:45]
	v_mfma_f32_16x16x32_bf16 v[42:45], v[98:101], v[162:165], v[42:45]
	v_mfma_f32_16x16x32_bf16 v[46:49], v[78:81], v[162:165], v[46:49]
	v_mfma_f32_16x16x32_bf16 v[46:49], v[66:69], v[158:161], v[46:49]
	v_mfma_f32_16x16x32_bf16 v[30:33], v[66:69], v[170:173], v[30:33]
	v_mfma_f32_16x16x32_bf16 v[30:33], v[78:81], v[174:177], v[30:33]
	v_mfma_f32_16x16x32_bf16 v[26:29], v[98:101], v[174:177], v[26:29]
	v_mfma_f32_16x16x32_bf16 v[26:29], v[82:85], v[170:173], v[26:29]
	v_mfma_f32_16x16x32_bf16 v[10:13], v[82:85], v[178:181], v[10:13]
	v_mfma_f32_16x16x32_bf16 v[10:13], v[98:101], v[190:193], v[10:13]
	s_add_u32 s18, s18, 0x100
	v_mfma_f32_16x16x32_bf16 v[14:17], v[78:81], v[190:193], v[14:17]
	v_mfma_f32_16x16x32_bf16 v[14:17], v[66:69], v[178:181], v[14:17]
	s_addc_u32 s19, s19, 0
	v_mfma_f32_16x16x32_bf16 v[54:57], v[106:109], v[150:153], v[54:57]
	v_mfma_f32_16x16x32_bf16 v[54:57], v[118:121], v[154:157], v[54:57]
	s_add_u32 s51, s51, 0x100
	v_mfma_f32_16x16x32_bf16 v[50:53], v[142:145], v[154:157], v[50:53]
	v_mfma_f32_16x16x32_bf16 v[50:53], v[130:133], v[150:153], v[50:53]
	s_addc_u32 s54, s54, 0
	v_mfma_f32_16x16x32_bf16 v[34:37], v[130:133], v[158:161], v[34:37]
	v_mfma_f32_16x16x32_bf16 v[34:37], v[142:145], v[162:165], v[34:37]
	s_cmp_ge_u32 s55, s53
	v_mfma_f32_16x16x32_bf16 v[38:41], v[118:121], v[162:165], v[38:41]
	v_mfma_f32_16x16x32_bf16 v[38:41], v[106:109], v[158:161], v[38:41]
	s_mov_b32 s20, s55
	v_mfma_f32_16x16x32_bf16 v[22:25], v[106:109], v[170:173], v[22:25]
	v_mfma_f32_16x16x32_bf16 v[22:25], v[118:121], v[174:177], v[22:25]
	v_mfma_f32_16x16x32_bf16 v[18:21], v[142:145], v[174:177], v[18:21]
	v_mfma_f32_16x16x32_bf16 v[18:21], v[130:133], v[170:173], v[18:21]
	v_mfma_f32_16x16x32_bf16 v[2:5], v[130:133], v[178:181], v[2:5]
	v_mfma_f32_16x16x32_bf16 v[2:5], v[142:145], v[190:193], v[2:5]
	v_mfma_f32_16x16x32_bf16 v[6:9], v[118:121], v[190:193], v[6:9]
	v_mfma_f32_16x16x32_bf16 v[6:9], v[106:109], v[178:181], v[6:9]
	s_setprio 0
	s_barrier
	s_cbranch_scc0 .LBB0_850

.LBB0_855:
	s_or_b64 exec, exec, s[18:19]
	s_and_b64 vcc, exec, s[4:5]
	s_mov_b64 s[4:5], -1
	s_cbranch_vccnz .LBB0_842
	v_mov_b32_e32 v2, v195
	s_andn2_b64 vcc, exec, s[6:7]
	s_cbranch_vccnz .LBB0_841
	s_branch .LBB0_841

.LBB0_873:
	s_ashr_i32 s17, s16, 31
	s_lshl_b64 s[62:63], s[16:17], 7
	s_and_b64 s[6:7], s[6:7], exec
	s_cselect_b32 s23, s62, 0
	s_cselect_b32 s17, s63, 0
	s_add_u32 s6, s18, s23
	s_addc_u32 s7, s19, s17
	s_add_u32 s18, s28, s23
	s_addc_u32 s19, s29, s17
	s_cmp_lt_i32 s25, 1
	s_cbranch_scc1 .LBB0_877
	s_add_i32 s17, s25, -2
	s_add_u32 s20, s20, 0x80
	s_addc_u32 s21, s21, 0
	s_add_u32 s23, s26, 0x100
	s_waitcnt lgkmcnt(0)
	v_mov_b64_e32 v[8:9], v[4:5]
	v_mov_b64_e32 v[20:21], v[4:5]
	v_mov_b64_e32 v[24:25], v[4:5]
	v_mov_b64_e32 v[36:37], v[4:5]
	v_mov_b64_e32 v[40:41], v[4:5]
	v_mov_b64_e32 v[52:53], v[4:5]
	v_mov_b64_e32 v[56:57], v[4:5]
	v_mov_b64_e32 v[12:13], v[4:5]
	v_mov_b64_e32 v[16:17], v[4:5]
	v_mov_b64_e32 v[28:29], v[4:5]
	v_mov_b64_e32 v[32:33], v[4:5]
	v_mov_b64_e32 v[44:45], v[4:5]
	v_mov_b64_e32 v[48:49], v[4:5]
	v_mov_b64_e32 v[60:61], v[4:5]
	v_mov_b64_e32 v[64:65], v[4:5]
	v_mov_b64_e32 v[68:69], v[4:5]
	v_mov_b64_e32 v[72:73], v[4:5]
	v_mov_b64_e32 v[84:85], v[4:5]
	v_mov_b64_e32 v[88:89], v[4:5]
	v_mov_b64_e32 v[100:101], v[4:5]
	v_mov_b64_e32 v[104:105], v[4:5]
	s_waitcnt vmcnt(0)
	v_mov_b64_e32 v[116:117], v[4:5]
	v_mov_b64_e32 v[120:121], v[4:5]
	v_mov_b64_e32 v[76:77], v[4:5]
	v_mov_b64_e32 v[80:81], v[4:5]
	v_mov_b64_e32 v[92:93], v[4:5]
	v_mov_b64_e32 v[96:97], v[4:5]
	v_mov_b64_e32 v[108:109], v[4:5]
	v_mov_b64_e32 v[112:113], v[4:5]
	v_mov_b64_e32 v[124:125], v[4:5]
	v_mov_b64_e32 v[128:129], v[4:5]
	s_addc_u32 s28, s27, 0
	s_mov_b32 s26, 0
	v_mov_b64_e32 v[6:7], v[2:3]
	v_mov_b64_e32 v[18:19], v[2:3]
	v_mov_b64_e32 v[22:23], v[2:3]
	v_mov_b64_e32 v[34:35], v[2:3]
	v_mov_b64_e32 v[38:39], v[2:3]
	v_mov_b64_e32 v[50:51], v[2:3]
	v_mov_b64_e32 v[54:55], v[2:3]
	v_mov_b64_e32 v[10:11], v[2:3]
	v_mov_b64_e32 v[14:15], v[2:3]
	v_mov_b64_e32 v[26:27], v[2:3]
	v_mov_b64_e32 v[30:31], v[2:3]
	v_mov_b64_e32 v[42:43], v[2:3]
	v_mov_b64_e32 v[46:47], v[2:3]
	v_mov_b64_e32 v[58:59], v[2:3]
	v_mov_b64_e32 v[62:63], v[2:3]
	v_mov_b64_e32 v[66:67], v[2:3]
	v_mov_b64_e32 v[70:71], v[2:3]
	v_mov_b64_e32 v[82:83], v[2:3]
	v_mov_b64_e32 v[86:87], v[2:3]
	v_mov_b64_e32 v[98:99], v[2:3]
	v_mov_b64_e32 v[102:103], v[2:3]
	v_mov_b64_e32 v[114:115], v[2:3]
	v_mov_b64_e32 v[118:119], v[2:3]
	v_mov_b64_e32 v[74:75], v[2:3]
	v_mov_b64_e32 v[78:79], v[2:3]
	v_mov_b64_e32 v[90:91], v[2:3]
	v_mov_b64_e32 v[94:95], v[2:3]
	v_mov_b64_e32 v[106:107], v[2:3]
	v_mov_b64_e32 v[110:111], v[2:3]
	v_mov_b64_e32 v[122:123], v[2:3]
	v_mov_b64_e32 v[126:127], v[2:3]
	s_cmp_eq_u32 s54, 1
	s_cbranch_scc1 .Lrealign_6
	s_andn2_b64 vcc, exec, s[0:1]
	s_cbranch_vccnz .Lrealign_6
	s_barrier
.Lrealign_6:
.LBB0_875:
	s_sub_u32 vcc_lo, s20, s12
	s_subb_u32 vcc_hi, s21, 0
	s_mov_b32 m0, s51
	s_nop 0
	global_load_lds_dwordx4 v210, vcc
	s_mov_b32 m0, s53
	s_nop 0
	global_load_lds_dwordx4 v212, vcc
	ds_read_b128 v[130:133], v235
	ds_read_b128 v[134:137], v235 offset:1024
	ds_read_b128 v[138:141], v235 offset:2048
	ds_read_b128 v[142:145], v235 offset:3072
	ds_read_b128 v[146:149], v235 offset:16384
	ds_read_b128 v[150:153], v235 offset:17408
	ds_read_b128 v[154:157], v235 offset:18432
	ds_read_b128 v[158:161], v235 offset:19456
	ds_read_b128 v[162:165], v237
	ds_read_b128 v[166:169], v237 offset:1024
	ds_read_b128 v[170:173], v237 offset:2048
	ds_read_b128 v[174:177], v237 offset:3072
	ds_read_b128 v[178:181], v237 offset:4096
	ds_read_b128 v[182:185], v237 offset:5120
	ds_read_b128 v[186:189], v237 offset:6144
	ds_read_b128 v[190:193], v237 offset:7168
	s_add_i32 s29, s26, 2
	s_add_u32 s62, s20, 0x80
	s_addc_u32 s27, s21, 0
	s_add_i32 s64, 0, 0x10000
	s_cmp_eq_u32 s17, s26
	s_cselect_b32 s27, s7, s27
	s_cselect_b32 s26, s6, s62
	s_cselect_b32 s63, s19, s28
	s_cselect_b32 s62, s18, s23
	s_add_i32 s65, 0, 0x14000
	s_add_i32 m0, s37, 0xc000
	s_nop 0
	global_load_lds_dwordx4 v210, s[20:21]
	s_add_i32 m0, s37, 0xe000
	s_nop 0
	global_load_lds_dwordx4 v212, s[20:21]
	s_waitcnt vmcnt(8)
	s_waitcnt lgkmcnt(0)
	v_mfma_f32_16x16x32_bf16 v[126:129], v[130:133], v[162:165], v[126:129]
	v_mfma_f32_16x16x32_bf16 v[126:129], v[134:137], v[166:169], v[126:129]
	s_barrier
	s_setprio 1
	v_mfma_f32_16x16x32_bf16 v[122:125], v[142:145], v[166:169], v[122:125]
	v_mfma_f32_16x16x32_bf16 v[122:125], v[138:141], v[162:165], v[122:125]
	v_mfma_f32_16x16x32_bf16 v[106:109], v[138:141], v[170:173], v[106:109]
	v_mfma_f32_16x16x32_bf16 v[106:109], v[142:145], v[174:177], v[106:109]
	v_mfma_f32_16x16x32_bf16 v[110:113], v[134:137], v[174:177], v[110:113]
	v_mfma_f32_16x16x32_bf16 v[110:113], v[130:133], v[170:173], v[110:113]
	v_mfma_f32_16x16x32_bf16 v[94:97], v[130:133], v[178:181], v[94:97]
	v_mfma_f32_16x16x32_bf16 v[94:97], v[134:137], v[182:185], v[94:97]
	v_mfma_f32_16x16x32_bf16 v[90:93], v[142:145], v[182:185], v[90:93]
	v_mfma_f32_16x16x32_bf16 v[90:93], v[138:141], v[178:181], v[90:93]
	v_mfma_f32_16x16x32_bf16 v[74:77], v[138:141], v[186:189], v[74:77]
	v_mfma_f32_16x16x32_bf16 v[74:77], v[142:145], v[190:193], v[74:77]
	v_mfma_f32_16x16x32_bf16 v[78:81], v[134:137], v[190:193], v[78:81]
	v_mfma_f32_16x16x32_bf16 v[78:81], v[130:133], v[186:189], v[78:81]
	v_mfma_f32_16x16x32_bf16 v[118:121], v[146:149], v[162:165], v[118:121]
	v_mfma_f32_16x16x32_bf16 v[118:121], v[150:153], v[166:169], v[118:121]
	v_mfma_f32_16x16x32_bf16 v[114:117], v[158:161], v[166:169], v[114:117]
	v_mfma_f32_16x16x32_bf16 v[114:117], v[154:157], v[162:165], v[114:117]
	v_mfma_f32_16x16x32_bf16 v[98:101], v[154:157], v[170:173], v[98:101]
	v_mfma_f32_16x16x32_bf16 v[98:101], v[158:161], v[174:177], v[98:101]
	v_mfma_f32_16x16x32_bf16 v[102:105], v[150:153], v[174:177], v[102:105]
	v_mfma_f32_16x16x32_bf16 v[102:105], v[146:149], v[170:173], v[102:105]
	v_mfma_f32_16x16x32_bf16 v[86:89], v[146:149], v[178:181], v[86:89]
	v_mfma_f32_16x16x32_bf16 v[86:89], v[150:153], v[182:185], v[86:89]
	v_mfma_f32_16x16x32_bf16 v[82:85], v[158:161], v[182:185], v[82:85]
	v_mfma_f32_16x16x32_bf16 v[82:85], v[154:157], v[178:181], v[82:85]
	v_mfma_f32_16x16x32_bf16 v[66:69], v[154:157], v[186:189], v[66:69]
	v_mfma_f32_16x16x32_bf16 v[66:69], v[158:161], v[190:193], v[66:69]
	v_mfma_f32_16x16x32_bf16 v[70:73], v[150:153], v[190:193], v[70:73]
	v_mfma_f32_16x16x32_bf16 v[70:73], v[146:149], v[186:189], v[70:73]
	s_setprio 0
	s_barrier
	ds_read_b128 v[162:165], v237 offset:16384
	ds_read_b128 v[166:169], v237 offset:17408
	ds_read_b128 v[170:173], v237 offset:18432
	ds_read_b128 v[174:177], v237 offset:19456
	ds_read_b128 v[178:181], v237 offset:20480
	ds_read_b128 v[182:185], v237 offset:21504
	ds_read_b128 v[186:189], v237 offset:22528
	ds_read_b128 v[190:193], v237 offset:23552
	s_add_i32 s64, s64, s36
	v_lshl_add_u64 v[198:199], s[62:63], 0, v[194:195]
	s_mov_b32 m0, s64
	s_nop 0
	global_load_lds_dwordx4 v194, s[62:63]
	s_add_i32 m0, s64, 0x2000
	v_lshl_add_u64 v[214:215], s[62:63], 0, v[208:209]
	s_add_u32 s62, s62, s12
	s_addc_u32 s63, s63, 0
	s_add_i32 s64, s65, s36
	global_load_lds_dwordx4 v[214:215], off
	v_lshl_add_u64 v[216:217], s[62:63], 0, v[194:195]
	s_mov_b32 m0, s64
	v_lshl_add_u64 v[218:219], s[62:63], 0, v[208:209]
	global_load_lds_dwordx4 v194, s[62:63]
	s_add_i32 m0, s64, 0x2000
	s_nop 0
	global_load_lds_dwordx4 v208, s[62:63]
	s_waitcnt vmcnt(6)
	s_waitcnt lgkmcnt(0)
	v_mfma_f32_16x16x32_bf16 v[62:65], v[130:133], v[162:165], v[62:65]
	v_mfma_f32_16x16x32_bf16 v[62:65], v[134:137], v[166:169], v[62:65]
	s_barrier
	s_setprio 1
	v_mfma_f32_16x16x32_bf16 v[58:61], v[142:145], v[166:169], v[58:61]
	v_mfma_f32_16x16x32_bf16 v[58:61], v[138:141], v[162:165], v[58:61]
	v_mfma_f32_16x16x32_bf16 v[42:45], v[138:141], v[170:173], v[42:45]
	v_mfma_f32_16x16x32_bf16 v[42:45], v[142:145], v[174:177], v[42:45]
	v_mfma_f32_16x16x32_bf16 v[46:49], v[134:137], v[174:177], v[46:49]
	v_mfma_f32_16x16x32_bf16 v[46:49], v[130:133], v[170:173], v[46:49]
	v_mfma_f32_16x16x32_bf16 v[30:33], v[130:133], v[178:181], v[30:33]
	v_mfma_f32_16x16x32_bf16 v[30:33], v[134:137], v[182:185], v[30:33]
	v_mfma_f32_16x16x32_bf16 v[26:29], v[142:145], v[182:185], v[26:29]
	v_mfma_f32_16x16x32_bf16 v[26:29], v[138:141], v[178:181], v[26:29]
	v_mfma_f32_16x16x32_bf16 v[10:13], v[138:141], v[186:189], v[10:13]
	v_mfma_f32_16x16x32_bf16 v[10:13], v[142:145], v[190:193], v[10:13]
	v_mfma_f32_16x16x32_bf16 v[14:17], v[134:137], v[190:193], v[14:17]
	v_mfma_f32_16x16x32_bf16 v[14:17], v[130:133], v[186:189], v[14:17]
	v_mfma_f32_16x16x32_bf16 v[54:57], v[146:149], v[162:165], v[54:57]
	v_mfma_f32_16x16x32_bf16 v[54:57], v[150:153], v[166:169], v[54:57]
	v_mfma_f32_16x16x32_bf16 v[50:53], v[158:161], v[166:169], v[50:53]
	v_mfma_f32_16x16x32_bf16 v[50:53], v[154:157], v[162:165], v[50:53]
	v_mfma_f32_16x16x32_bf16 v[34:37], v[154:157], v[170:173], v[34:37]
	v_mfma_f32_16x16x32_bf16 v[34:37], v[158:161], v[174:177], v[34:37]
	v_mfma_f32_16x16x32_bf16 v[38:41], v[150:153], v[174:177], v[38:41]
	v_mfma_f32_16x16x32_bf16 v[38:41], v[146:149], v[170:173], v[38:41]
	v_mfma_f32_16x16x32_bf16 v[22:25], v[146:149], v[178:181], v[22:25]
	v_mfma_f32_16x16x32_bf16 v[22:25], v[150:153], v[182:185], v[22:25]
	v_mfma_f32_16x16x32_bf16 v[18:21], v[158:161], v[182:185], v[18:21]
	v_mfma_f32_16x16x32_bf16 v[18:21], v[154:157], v[178:181], v[18:21]
	v_mfma_f32_16x16x32_bf16 v[2:5], v[154:157], v[186:189], v[2:5]
	v_mfma_f32_16x16x32_bf16 v[2:5], v[158:161], v[190:193], v[2:5]
	v_mfma_f32_16x16x32_bf16 v[6:9], v[150:153], v[190:193], v[6:9]
	v_mfma_f32_16x16x32_bf16 v[6:9], v[146:149], v[186:189], v[6:9]
	s_setprio 0
	s_barrier
	s_mov_b32 m0, s37
	s_nop 0
	global_load_lds_dwordx4 v204, s[26:27]
	s_mov_b32 m0, s38
	s_nop 0
	global_load_lds_dwordx4 v206, s[26:27]
	ds_read_b128 v[130:133], v235 offset:32768
	ds_read_b128 v[134:137], v235 offset:33792
	ds_read_b128 v[138:141], v235 offset:34816
	ds_read_b128 v[142:145], v235 offset:35840
	ds_read_b128 v[146:149], v235 offset:49152
	ds_read_b128 v[150:153], v235 offset:50176
	ds_read_b128 v[154:157], v235 offset:51200
	ds_read_b128 v[158:161], v235 offset:52224
	ds_read_b128 v[162:165], v237 offset:32768
	ds_read_b128 v[166:169], v237 offset:33792
	ds_read_b128 v[170:173], v237 offset:34816
	ds_read_b128 v[174:177], v237 offset:35840
	ds_read_b128 v[178:181], v237 offset:36864
	ds_read_b128 v[182:185], v237 offset:37888
	ds_read_b128 v[186:189], v237 offset:38912
	ds_read_b128 v[190:193], v237 offset:39936
	s_add_i32 s62, 0, 0x18000
	s_add_i32 s63, 0, 0x1c000
	s_add_u32 s26, s26, s12
	s_addc_u32 s27, s27, 0
	s_mov_b32 m0, s39
	s_nop 0
	global_load_lds_dwordx4 v204, s[26:27]
	s_mov_b32 m0, s50
	s_nop 0
	global_load_lds_dwordx4 v206, s[26:27]
	s_waitcnt vmcnt(8)
	s_waitcnt lgkmcnt(0)
	v_mfma_f32_16x16x32_bf16 v[126:129], v[130:133], v[162:165], v[126:129]
	v_mfma_f32_16x16x32_bf16 v[126:129], v[134:137], v[166:169], v[126:129]
	s_barrier
	s_setprio 1
	v_mfma_f32_16x16x32_bf16 v[122:125], v[142:145], v[166:169], v[122:125]
	v_mfma_f32_16x16x32_bf16 v[122:125], v[138:141], v[162:165], v[122:125]
	v_mfma_f32_16x16x32_bf16 v[106:109], v[138:141], v[170:173], v[106:109]
	v_mfma_f32_16x16x32_bf16 v[106:109], v[142:145], v[174:177], v[106:109]
	v_mfma_f32_16x16x32_bf16 v[110:113], v[134:137], v[174:177], v[110:113]
	v_mfma_f32_16x16x32_bf16 v[110:113], v[130:133], v[170:173], v[110:113]
	v_mfma_f32_16x16x32_bf16 v[94:97], v[130:133], v[178:181], v[94:97]
	v_mfma_f32_16x16x32_bf16 v[94:97], v[134:137], v[182:185], v[94:97]
	v_mfma_f32_16x16x32_bf16 v[90:93], v[142:145], v[182:185], v[90:93]
	v_mfma_f32_16x16x32_bf16 v[90:93], v[138:141], v[178:181], v[90:93]
	v_mfma_f32_16x16x32_bf16 v[74:77], v[138:141], v[186:189], v[74:77]
	v_mfma_f32_16x16x32_bf16 v[74:77], v[142:145], v[190:193], v[74:77]
	v_mfma_f32_16x16x32_bf16 v[78:81], v[134:137], v[190:193], v[78:81]
	v_mfma_f32_16x16x32_bf16 v[78:81], v[130:133], v[186:189], v[78:81]
	v_mfma_f32_16x16x32_bf16 v[118:121], v[146:149], v[162:165], v[118:121]
	v_mfma_f32_16x16x32_bf16 v[118:121], v[150:153], v[166:169], v[118:121]
	v_mfma_f32_16x16x32_bf16 v[114:117], v[158:161], v[166:169], v[114:117]
	v_mfma_f32_16x16x32_bf16 v[114:117], v[154:157], v[162:165], v[114:117]
	v_mfma_f32_16x16x32_bf16 v[98:101], v[154:157], v[170:173], v[98:101]
	v_mfma_f32_16x16x32_bf16 v[98:101], v[158:161], v[174:177], v[98:101]
	v_mfma_f32_16x16x32_bf16 v[102:105], v[150:153], v[174:177], v[102:105]
	v_mfma_f32_16x16x32_bf16 v[102:105], v[146:149], v[170:173], v[102:105]
	v_mfma_f32_16x16x32_bf16 v[86:89], v[146:149], v[178:181], v[86:89]
	v_mfma_f32_16x16x32_bf16 v[86:89], v[150:153], v[182:185], v[86:89]
	v_mfma_f32_16x16x32_bf16 v[82:85], v[158:161], v[182:185], v[82:85]
	v_mfma_f32_16x16x32_bf16 v[82:85], v[154:157], v[178:181], v[82:85]
	v_mfma_f32_16x16x32_bf16 v[66:69], v[154:157], v[186:189], v[66:69]
	v_mfma_f32_16x16x32_bf16 v[66:69], v[158:161], v[190:193], v[66:69]
	v_mfma_f32_16x16x32_bf16 v[70:73], v[150:153], v[190:193], v[70:73]
	v_mfma_f32_16x16x32_bf16 v[70:73], v[146:149], v[186:189], v[70:73]
	s_setprio 0
	s_barrier
	ds_read_b128 v[162:165], v237 offset:49152
	ds_read_b128 v[166:169], v237 offset:50176
	ds_read_b128 v[170:173], v237 offset:51200
	ds_read_b128 v[174:177], v237 offset:52224
	ds_read_b128 v[178:181], v237 offset:53248
	ds_read_b128 v[182:185], v237 offset:54272
	ds_read_b128 v[186:189], v237 offset:55296
	ds_read_b128 v[190:193], v237 offset:56320
	s_add_i32 s26, s62, s36
	v_lshl_add_u64 v[198:199], v[198:199], 0, s[94:95]
	s_mov_b32 m0, s26
	s_nop 0
	global_load_lds_dwordx4 v[198:199], off
	v_lshl_add_u64 v[198:199], v[214:215], 0, s[94:95]
	s_add_i32 m0, s26, 0x2000
	s_add_i32 s26, s63, s36
	global_load_lds_dwordx4 v[198:199], off
	v_lshl_add_u64 v[198:199], v[216:217], 0, s[94:95]
	s_mov_b32 m0, s26
	s_nop 0
	global_load_lds_dwordx4 v[198:199], off
	v_lshl_add_u64 v[198:199], v[218:219], 0, s[94:95]
	s_add_i32 m0, s26, 0x2000
	s_nop 0
	global_load_lds_dwordx4 v[198:199], off
	s_waitcnt vmcnt(6)
	s_waitcnt lgkmcnt(0)
	v_mfma_f32_16x16x32_bf16 v[62:65], v[130:133], v[162:165], v[62:65]
	v_mfma_f32_16x16x32_bf16 v[62:65], v[134:137], v[166:169], v[62:65]
	s_barrier
	s_setprio 1
	v_mfma_f32_16x16x32_bf16 v[58:61], v[142:145], v[166:169], v[58:61]
	v_mfma_f32_16x16x32_bf16 v[58:61], v[138:141], v[162:165], v[58:61]
	v_mfma_f32_16x16x32_bf16 v[42:45], v[138:141], v[170:173], v[42:45]
	v_mfma_f32_16x16x32_bf16 v[42:45], v[142:145], v[174:177], v[42:45]
	v_mfma_f32_16x16x32_bf16 v[46:49], v[134:137], v[174:177], v[46:49]
	v_mfma_f32_16x16x32_bf16 v[46:49], v[130:133], v[170:173], v[46:49]
	v_mfma_f32_16x16x32_bf16 v[30:33], v[130:133], v[178:181], v[30:33]
	v_mfma_f32_16x16x32_bf16 v[30:33], v[134:137], v[182:185], v[30:33]
	v_mfma_f32_16x16x32_bf16 v[26:29], v[142:145], v[182:185], v[26:29]
	v_mfma_f32_16x16x32_bf16 v[26:29], v[138:141], v[178:181], v[26:29]
	v_mfma_f32_16x16x32_bf16 v[10:13], v[138:141], v[186:189], v[10:13]
	v_mfma_f32_16x16x32_bf16 v[10:13], v[142:145], v[190:193], v[10:13]
	s_add_u32 s20, s20, 0x100
	v_mfma_f32_16x16x32_bf16 v[14:17], v[134:137], v[190:193], v[14:17]
	v_mfma_f32_16x16x32_bf16 v[14:17], v[130:133], v[186:189], v[14:17]
	s_addc_u32 s21, s21, 0
	v_mfma_f32_16x16x32_bf16 v[54:57], v[146:149], v[162:165], v[54:57]
	v_mfma_f32_16x16x32_bf16 v[54:57], v[150:153], v[166:169], v[54:57]
	s_add_u32 s23, s23, 0x100
	v_mfma_f32_16x16x32_bf16 v[50:53], v[158:161], v[166:169], v[50:53]
	v_mfma_f32_16x16x32_bf16 v[50:53], v[154:157], v[162:165], v[50:53]
	s_addc_u32 s28, s28, 0
	v_mfma_f32_16x16x32_bf16 v[34:37], v[154:157], v[170:173], v[34:37]
	v_mfma_f32_16x16x32_bf16 v[34:37], v[158:161], v[174:177], v[34:37]
	s_cmp_ge_i32 s29, s25
	v_mfma_f32_16x16x32_bf16 v[38:41], v[150:153], v[174:177], v[38:41]
	v_mfma_f32_16x16x32_bf16 v[38:41], v[146:149], v[170:173], v[38:41]
	s_mov_b32 s26, s29
	v_mfma_f32_16x16x32_bf16 v[22:25], v[146:149], v[178:181], v[22:25]
	v_mfma_f32_16x16x32_bf16 v[22:25], v[150:153], v[182:185], v[22:25]
	v_mfma_f32_16x16x32_bf16 v[18:21], v[158:161], v[182:185], v[18:21]
	v_mfma_f32_16x16x32_bf16 v[18:21], v[154:157], v[178:181], v[18:21]
	v_mfma_f32_16x16x32_bf16 v[2:5], v[154:157], v[186:189], v[2:5]
	v_mfma_f32_16x16x32_bf16 v[2:5], v[158:161], v[190:193], v[2:5]
	v_mfma_f32_16x16x32_bf16 v[6:9], v[150:153], v[190:193], v[6:9]
	v_mfma_f32_16x16x32_bf16 v[6:9], v[146:149], v[186:189], v[6:9]
	s_setprio 0
	s_barrier
	s_cbranch_scc0 .LBB0_875
	v_readlane_b32 s64, v254, 51
	v_readlane_b32 s65, v254, 52
	s_branch .LBB0_878

.LBB0_972:
	s_ashr_i32 s29, s28, 31
	s_lshl_b64 s[10:11], s[28:29], 20
	s_add_u32 s36, s46, s10
	s_addc_u32 s37, s47, s11
	s_and_b64 s[4:5], s[4:5], exec
	s_cselect_b32 s13, s37, s7
	s_cselect_b32 s29, s36, s6
	s_add_u32 s33, s6, 0x100
	v_mov_b64_e32 v[68:69], v[4:5]
	v_mov_b64_e32 v[8:9], v[4:5]
	v_mov_b64_e32 v[72:73], v[4:5]
	v_mov_b64_e32 v[16:17], v[4:5]
	v_mov_b64_e32 v[80:81], v[4:5]
	v_mov_b64_e32 v[24:25], v[4:5]
	v_mov_b64_e32 v[88:89], v[4:5]
	v_mov_b64_e32 v[12:13], v[4:5]
	v_mov_b64_e32 v[76:77], v[4:5]
	v_mov_b64_e32 v[20:21], v[4:5]
	v_mov_b64_e32 v[84:85], v[4:5]
	v_mov_b64_e32 v[28:29], v[4:5]
	v_mov_b64_e32 v[92:93], v[4:5]
	v_mov_b64_e32 v[32:33], v[4:5]
	v_mov_b64_e32 v[96:97], v[4:5]
	v_mov_b64_e32 v[36:37], v[4:5]
	v_mov_b64_e32 v[100:101], v[4:5]
	v_mov_b64_e32 v[40:41], v[4:5]
	v_mov_b64_e32 v[104:105], v[4:5]
	v_mov_b64_e32 v[48:49], v[4:5]
	v_mov_b64_e32 v[112:113], v[4:5]
	v_mov_b64_e32 v[56:57], v[4:5]
	v_mov_b64_e32 v[120:121], v[4:5]
	v_mov_b64_e32 v[44:45], v[4:5]
	v_mov_b64_e32 v[108:109], v[4:5]
	v_mov_b64_e32 v[52:53], v[4:5]
	v_mov_b64_e32 v[116:117], v[4:5]
	v_mov_b64_e32 v[60:61], v[4:5]
	v_mov_b64_e32 v[124:125], v[4:5]
	v_mov_b64_e32 v[64:65], v[4:5]
	v_mov_b64_e32 v[128:129], v[4:5]
	s_addc_u32 s38, s7, 0
	s_mov_b32 s39, -2
	v_mov_b64_e32 v[66:67], v[2:3]
	v_mov_b64_e32 v[6:7], v[2:3]
	v_mov_b64_e32 v[70:71], v[2:3]
	v_mov_b64_e32 v[14:15], v[2:3]
	v_mov_b64_e32 v[78:79], v[2:3]
	v_mov_b64_e32 v[22:23], v[2:3]
	v_mov_b64_e32 v[86:87], v[2:3]
	v_mov_b64_e32 v[10:11], v[2:3]
	v_mov_b64_e32 v[74:75], v[2:3]
	v_mov_b64_e32 v[18:19], v[2:3]
	v_mov_b64_e32 v[82:83], v[2:3]
	v_mov_b64_e32 v[26:27], v[2:3]
	v_mov_b64_e32 v[90:91], v[2:3]
	v_mov_b64_e32 v[30:31], v[2:3]
	v_mov_b64_e32 v[94:95], v[2:3]
	v_mov_b64_e32 v[34:35], v[2:3]
	v_mov_b64_e32 v[98:99], v[2:3]
	v_mov_b64_e32 v[38:39], v[2:3]
	v_mov_b64_e32 v[102:103], v[2:3]
	v_mov_b64_e32 v[46:47], v[2:3]
	v_mov_b64_e32 v[110:111], v[2:3]
	v_mov_b64_e32 v[54:55], v[2:3]
	v_mov_b64_e32 v[118:119], v[2:3]
	v_mov_b64_e32 v[42:43], v[2:3]
	v_mov_b64_e32 v[106:107], v[2:3]
	v_mov_b64_e32 v[50:51], v[2:3]
	v_mov_b64_e32 v[114:115], v[2:3]
	v_mov_b64_e32 v[58:59], v[2:3]
	v_mov_b64_e32 v[122:123], v[2:3]
	v_mov_b64_e32 v[62:63], v[2:3]
	v_mov_b64_e32 v[126:127], v[2:3]
	s_cmp_eq_u32 s9, 0
	s_cbranch_scc1 .Lrealign_7
	s_andn2_b64 vcc, exec, s[22:23]
	s_cbranch_vccnz .Lrealign_7
	s_barrier
.Lrealign_7:
.LBB0_973:
	s_add_u32 vcc_lo, s0, 0xffffc000
	s_addc_u32 vcc_hi, s1, -1
	s_mov_b32 m0, s59
	s_nop 0
	global_load_lds_dwordx4 v146, vcc
	s_mov_b32 m0, s60
	s_nop 0
	global_load_lds_dwordx4 v148, vcc
	ds_read_b128 v[130:133], v246
	ds_read_b128 v[134:137], v246 offset:1024
	ds_read_b128 v[150:153], v246 offset:2048
	ds_read_b128 v[154:157], v246 offset:3072
	ds_read_b128 v[158:161], v246 offset:16384
	ds_read_b128 v[162:165], v246 offset:17408
	ds_read_b128 v[166:169], v246 offset:18432
	ds_read_b128 v[170:173], v246 offset:19456
	ds_read_b128 v[174:177], v247
	ds_read_b128 v[178:181], v247 offset:1024
	ds_read_b128 v[182:185], v247 offset:2048
	ds_read_b128 v[186:189], v247 offset:3072
	ds_read_b128 v[190:193], v247 offset:4096
	ds_read_b128 v[204:207], v247 offset:5120
	ds_read_b128 v[208:211], v247 offset:6144
	ds_read_b128 v[212:215], v247 offset:7168
	s_add_u32 s4, s0, 0x100
	s_addc_u32 s5, s1, 0
	s_add_i32 s40, 0, 0x10000
	s_cmp_eq_u32 s39, 28
	s_cselect_b32 s11, s35, s5
	s_cselect_b32 s10, s34, s4
	s_cselect_b32 s7, s13, s38
	s_cselect_b32 s6, s29, s33
	s_add_i32 s41, 0, 0x14000
	s_add_i32 m0, s49, 0xc000
	s_nop 0
	global_load_lds_dwordx4 v146, s[0:1]
	s_add_i32 m0, s49, 0xe000
	s_nop 0
	global_load_lds_dwordx4 v148, s[0:1]
	s_waitcnt vmcnt(8)
	s_waitcnt lgkmcnt(0)
	v_mfma_f32_16x16x32_bf16 v[126:129], v[130:133], v[174:177], v[126:129]
	v_mfma_f32_16x16x32_bf16 v[126:129], v[134:137], v[178:181], v[126:129]
	s_barrier
	s_setprio 1
	v_mfma_f32_16x16x32_bf16 v[62:65], v[154:157], v[178:181], v[62:65]
	v_mfma_f32_16x16x32_bf16 v[62:65], v[150:153], v[174:177], v[62:65]
	v_mfma_f32_16x16x32_bf16 v[58:61], v[150:153], v[182:185], v[58:61]
	v_mfma_f32_16x16x32_bf16 v[58:61], v[154:157], v[186:189], v[58:61]
	v_mfma_f32_16x16x32_bf16 v[122:125], v[134:137], v[186:189], v[122:125]
	v_mfma_f32_16x16x32_bf16 v[122:125], v[130:133], v[182:185], v[122:125]
	v_mfma_f32_16x16x32_bf16 v[114:117], v[130:133], v[190:193], v[114:117]
	v_mfma_f32_16x16x32_bf16 v[114:117], v[134:137], v[204:207], v[114:117]
	v_mfma_f32_16x16x32_bf16 v[50:53], v[154:157], v[204:207], v[50:53]
	v_mfma_f32_16x16x32_bf16 v[50:53], v[150:153], v[190:193], v[50:53]
	v_mfma_f32_16x16x32_bf16 v[42:45], v[150:153], v[208:211], v[42:45]
	v_mfma_f32_16x16x32_bf16 v[42:45], v[154:157], v[212:215], v[42:45]
	v_mfma_f32_16x16x32_bf16 v[106:109], v[134:137], v[212:215], v[106:109]
	v_mfma_f32_16x16x32_bf16 v[106:109], v[130:133], v[208:211], v[106:109]
	v_mfma_f32_16x16x32_bf16 v[118:121], v[158:161], v[174:177], v[118:121]
	v_mfma_f32_16x16x32_bf16 v[118:121], v[162:165], v[178:181], v[118:121]
	v_mfma_f32_16x16x32_bf16 v[54:57], v[170:173], v[178:181], v[54:57]
	v_mfma_f32_16x16x32_bf16 v[54:57], v[166:169], v[174:177], v[54:57]
	v_mfma_f32_16x16x32_bf16 v[46:49], v[166:169], v[182:185], v[46:49]
	v_mfma_f32_16x16x32_bf16 v[46:49], v[170:173], v[186:189], v[46:49]
	v_mfma_f32_16x16x32_bf16 v[110:113], v[162:165], v[186:189], v[110:113]
	v_mfma_f32_16x16x32_bf16 v[110:113], v[158:161], v[182:185], v[110:113]
	v_mfma_f32_16x16x32_bf16 v[102:105], v[158:161], v[190:193], v[102:105]
	v_mfma_f32_16x16x32_bf16 v[102:105], v[162:165], v[204:207], v[102:105]
	v_mfma_f32_16x16x32_bf16 v[38:41], v[170:173], v[204:207], v[38:41]
	v_mfma_f32_16x16x32_bf16 v[38:41], v[166:169], v[190:193], v[38:41]
	v_mfma_f32_16x16x32_bf16 v[34:37], v[166:169], v[208:211], v[34:37]
	v_mfma_f32_16x16x32_bf16 v[34:37], v[170:173], v[212:215], v[34:37]
	v_mfma_f32_16x16x32_bf16 v[98:101], v[162:165], v[212:215], v[98:101]
	v_mfma_f32_16x16x32_bf16 v[98:101], v[158:161], v[208:211], v[98:101]
	s_setprio 0
	s_barrier
	ds_read_b128 v[174:177], v247 offset:16384
	ds_read_b128 v[178:181], v247 offset:17408
	ds_read_b128 v[182:185], v247 offset:18432
	ds_read_b128 v[186:189], v247 offset:19456
	ds_read_b128 v[190:193], v247 offset:20480
	ds_read_b128 v[204:207], v247 offset:21504
	ds_read_b128 v[208:211], v247 offset:22528
	ds_read_b128 v[212:215], v247 offset:23552
	s_add_i32 s0, s40, s48
	s_mov_b32 m0, s0
	s_nop 0
	global_load_lds_dwordx4 v140, s[6:7]
	s_add_i32 m0, s0, 0x2000
	s_add_u32 s0, s6, 0x80000
	s_addc_u32 s1, s7, 0
	s_add_i32 s40, s41, s48
	global_load_lds_dwordx4 v144, s[6:7]
	s_mov_b32 m0, s40
	s_nop 0
	global_load_lds_dwordx4 v140, s[0:1]
	s_add_i32 m0, s40, 0x2000
	s_nop 0
	global_load_lds_dwordx4 v144, s[0:1]
	s_waitcnt vmcnt(6)
	s_waitcnt lgkmcnt(0)
	v_mfma_f32_16x16x32_bf16 v[94:97], v[130:133], v[174:177], v[94:97]
	v_mfma_f32_16x16x32_bf16 v[94:97], v[134:137], v[178:181], v[94:97]
	s_barrier
	s_setprio 1
	v_mfma_f32_16x16x32_bf16 v[30:33], v[154:157], v[178:181], v[30:33]
	v_mfma_f32_16x16x32_bf16 v[30:33], v[150:153], v[174:177], v[30:33]
	v_mfma_f32_16x16x32_bf16 v[26:29], v[150:153], v[182:185], v[26:29]
	v_mfma_f32_16x16x32_bf16 v[26:29], v[154:157], v[186:189], v[26:29]
	v_mfma_f32_16x16x32_bf16 v[90:93], v[134:137], v[186:189], v[90:93]
	v_mfma_f32_16x16x32_bf16 v[90:93], v[130:133], v[182:185], v[90:93]
	v_mfma_f32_16x16x32_bf16 v[82:85], v[130:133], v[190:193], v[82:85]
	v_mfma_f32_16x16x32_bf16 v[82:85], v[134:137], v[204:207], v[82:85]
	v_mfma_f32_16x16x32_bf16 v[18:21], v[154:157], v[204:207], v[18:21]
	v_mfma_f32_16x16x32_bf16 v[18:21], v[150:153], v[190:193], v[18:21]
	v_mfma_f32_16x16x32_bf16 v[10:13], v[150:153], v[208:211], v[10:13]
	v_mfma_f32_16x16x32_bf16 v[10:13], v[154:157], v[212:215], v[10:13]
	v_mfma_f32_16x16x32_bf16 v[74:77], v[134:137], v[212:215], v[74:77]
	v_mfma_f32_16x16x32_bf16 v[74:77], v[130:133], v[208:211], v[74:77]
	v_mfma_f32_16x16x32_bf16 v[86:89], v[158:161], v[174:177], v[86:89]
	v_mfma_f32_16x16x32_bf16 v[86:89], v[162:165], v[178:181], v[86:89]
	v_mfma_f32_16x16x32_bf16 v[22:25], v[170:173], v[178:181], v[22:25]
	v_mfma_f32_16x16x32_bf16 v[22:25], v[166:169], v[174:177], v[22:25]
	v_mfma_f32_16x16x32_bf16 v[14:17], v[166:169], v[182:185], v[14:17]
	v_mfma_f32_16x16x32_bf16 v[14:17], v[170:173], v[186:189], v[14:17]
	v_mfma_f32_16x16x32_bf16 v[78:81], v[162:165], v[186:189], v[78:81]
	v_mfma_f32_16x16x32_bf16 v[78:81], v[158:161], v[182:185], v[78:81]
	v_mfma_f32_16x16x32_bf16 v[70:73], v[158:161], v[190:193], v[70:73]
	v_mfma_f32_16x16x32_bf16 v[70:73], v[162:165], v[204:207], v[70:73]
	v_mfma_f32_16x16x32_bf16 v[6:9], v[170:173], v[204:207], v[6:9]
	v_mfma_f32_16x16x32_bf16 v[6:9], v[166:169], v[190:193], v[6:9]
	v_mfma_f32_16x16x32_bf16 v[2:5], v[166:169], v[208:211], v[2:5]
	v_mfma_f32_16x16x32_bf16 v[2:5], v[170:173], v[212:215], v[2:5]
	v_mfma_f32_16x16x32_bf16 v[66:69], v[162:165], v[212:215], v[66:69]
	v_mfma_f32_16x16x32_bf16 v[66:69], v[158:161], v[208:211], v[66:69]
	s_setprio 0
	s_barrier
	s_mov_b32 m0, s49
	s_nop 0
	global_load_lds_dwordx4 v138, s[10:11]
	s_mov_b32 m0, s70
	s_nop 0
	global_load_lds_dwordx4 v142, s[10:11]
	ds_read_b128 v[130:133], v246 offset:32768
	ds_read_b128 v[134:137], v246 offset:33792
	ds_read_b128 v[150:153], v246 offset:34816
	ds_read_b128 v[154:157], v246 offset:35840
	ds_read_b128 v[158:161], v246 offset:49152
	ds_read_b128 v[162:165], v246 offset:50176
	ds_read_b128 v[166:169], v246 offset:51200
	ds_read_b128 v[170:173], v246 offset:52224
	ds_read_b128 v[174:177], v247 offset:32768
	ds_read_b128 v[178:181], v247 offset:33792
	ds_read_b128 v[182:185], v247 offset:34816
	ds_read_b128 v[186:189], v247 offset:35840
	ds_read_b128 v[190:193], v247 offset:36864
	ds_read_b128 v[204:207], v247 offset:37888
	ds_read_b128 v[208:211], v247 offset:38912
	ds_read_b128 v[212:215], v247 offset:39936
	s_add_i32 s40, 0, 0x18000
	s_add_i32 s41, 0, 0x1c000
	s_add_u32 s0, s10, 0x4000
	s_addc_u32 s1, s11, 0
	s_mov_b32 m0, s71
	s_nop 0
	global_load_lds_dwordx4 v138, s[0:1]
	s_mov_b32 m0, s73
	s_nop 0
	global_load_lds_dwordx4 v142, s[0:1]
	s_waitcnt vmcnt(8)
	s_waitcnt lgkmcnt(0)
	v_mfma_f32_16x16x32_bf16 v[126:129], v[130:133], v[174:177], v[126:129]
	v_mfma_f32_16x16x32_bf16 v[126:129], v[134:137], v[178:181], v[126:129]
	s_barrier
	s_setprio 1
	v_mfma_f32_16x16x32_bf16 v[62:65], v[154:157], v[178:181], v[62:65]
	v_mfma_f32_16x16x32_bf16 v[62:65], v[150:153], v[174:177], v[62:65]
	v_mfma_f32_16x16x32_bf16 v[58:61], v[150:153], v[182:185], v[58:61]
	v_mfma_f32_16x16x32_bf16 v[58:61], v[154:157], v[186:189], v[58:61]
	v_mfma_f32_16x16x32_bf16 v[122:125], v[134:137], v[186:189], v[122:125]
	v_mfma_f32_16x16x32_bf16 v[122:125], v[130:133], v[182:185], v[122:125]
	v_mfma_f32_16x16x32_bf16 v[114:117], v[130:133], v[190:193], v[114:117]
	v_mfma_f32_16x16x32_bf16 v[114:117], v[134:137], v[204:207], v[114:117]
	v_mfma_f32_16x16x32_bf16 v[50:53], v[154:157], v[204:207], v[50:53]
	v_mfma_f32_16x16x32_bf16 v[50:53], v[150:153], v[190:193], v[50:53]
	v_mfma_f32_16x16x32_bf16 v[42:45], v[150:153], v[208:211], v[42:45]
	v_mfma_f32_16x16x32_bf16 v[42:45], v[154:157], v[212:215], v[42:45]
	v_mfma_f32_16x16x32_bf16 v[106:109], v[134:137], v[212:215], v[106:109]
	v_mfma_f32_16x16x32_bf16 v[106:109], v[130:133], v[208:211], v[106:109]
	v_mfma_f32_16x16x32_bf16 v[118:121], v[158:161], v[174:177], v[118:121]
	v_mfma_f32_16x16x32_bf16 v[118:121], v[162:165], v[178:181], v[118:121]
	v_mfma_f32_16x16x32_bf16 v[54:57], v[170:173], v[178:181], v[54:57]
	v_mfma_f32_16x16x32_bf16 v[54:57], v[166:169], v[174:177], v[54:57]
	v_mfma_f32_16x16x32_bf16 v[46:49], v[166:169], v[182:185], v[46:49]
	v_mfma_f32_16x16x32_bf16 v[46:49], v[170:173], v[186:189], v[46:49]
	v_mfma_f32_16x16x32_bf16 v[110:113], v[162:165], v[186:189], v[110:113]
	v_mfma_f32_16x16x32_bf16 v[110:113], v[158:161], v[182:185], v[110:113]
	v_mfma_f32_16x16x32_bf16 v[102:105], v[158:161], v[190:193], v[102:105]
	v_mfma_f32_16x16x32_bf16 v[102:105], v[162:165], v[204:207], v[102:105]
	v_mfma_f32_16x16x32_bf16 v[38:41], v[170:173], v[204:207], v[38:41]
	v_mfma_f32_16x16x32_bf16 v[38:41], v[166:169], v[190:193], v[38:41]
	v_mfma_f32_16x16x32_bf16 v[34:37], v[166:169], v[208:211], v[34:37]
	v_mfma_f32_16x16x32_bf16 v[34:37], v[170:173], v[212:215], v[34:37]
	v_mfma_f32_16x16x32_bf16 v[98:101], v[162:165], v[212:215], v[98:101]
	v_mfma_f32_16x16x32_bf16 v[98:101], v[158:161], v[208:211], v[98:101]
	s_setprio 0
	s_barrier
	ds_read_b128 v[174:177], v247 offset:49152
	ds_read_b128 v[178:181], v247 offset:50176
	ds_read_b128 v[182:185], v247 offset:51200
	ds_read_b128 v[186:189], v247 offset:52224
	ds_read_b128 v[190:193], v247 offset:53248
	ds_read_b128 v[204:207], v247 offset:54272
	ds_read_b128 v[208:211], v247 offset:55296
	ds_read_b128 v[212:215], v247 offset:56320
	s_add_i32 s0, s40, s48
	s_add_u32 vcc_lo, s6, s94
	s_addc_u32 vcc_hi, s7, s95
	s_mov_b32 m0, s0
	s_nop 0
	global_load_lds_dwordx4 v140, vcc
	s_add_i32 m0, s0, 0x2000
	s_add_u32 s0, s6, 0x80080
	s_addc_u32 s1, s7, 0
	s_add_i32 s6, s41, s48
	global_load_lds_dwordx4 v144, vcc
	s_mov_b32 m0, s6
	s_nop 0
	global_load_lds_dwordx4 v140, s[0:1]
	s_add_i32 m0, s6, 0x2000
	s_nop 0
	global_load_lds_dwordx4 v144, s[0:1]
	s_waitcnt vmcnt(6)
	s_waitcnt lgkmcnt(0)
	v_mfma_f32_16x16x32_bf16 v[94:97], v[130:133], v[174:177], v[94:97]
	v_mfma_f32_16x16x32_bf16 v[94:97], v[134:137], v[178:181], v[94:97]
	s_barrier
	s_setprio 1
	v_mfma_f32_16x16x32_bf16 v[30:33], v[154:157], v[178:181], v[30:33]
	v_mfma_f32_16x16x32_bf16 v[30:33], v[150:153], v[174:177], v[30:33]
	v_mfma_f32_16x16x32_bf16 v[26:29], v[150:153], v[182:185], v[26:29]
	v_mfma_f32_16x16x32_bf16 v[26:29], v[154:157], v[186:189], v[26:29]
	v_mfma_f32_16x16x32_bf16 v[90:93], v[134:137], v[186:189], v[90:93]
	v_mfma_f32_16x16x32_bf16 v[90:93], v[130:133], v[182:185], v[90:93]
	v_mfma_f32_16x16x32_bf16 v[82:85], v[130:133], v[190:193], v[82:85]
	v_mfma_f32_16x16x32_bf16 v[82:85], v[134:137], v[204:207], v[82:85]
	v_mfma_f32_16x16x32_bf16 v[18:21], v[154:157], v[204:207], v[18:21]
	v_mfma_f32_16x16x32_bf16 v[18:21], v[150:153], v[190:193], v[18:21]
	v_mfma_f32_16x16x32_bf16 v[10:13], v[150:153], v[208:211], v[10:13]
	v_mfma_f32_16x16x32_bf16 v[10:13], v[154:157], v[212:215], v[10:13]
	s_add_i32 s39, s39, 2
	v_mfma_f32_16x16x32_bf16 v[74:77], v[134:137], v[212:215], v[74:77]
	v_mfma_f32_16x16x32_bf16 v[74:77], v[130:133], v[208:211], v[74:77]
	s_add_u32 s33, s33, 0x100
	v_mfma_f32_16x16x32_bf16 v[86:89], v[158:161], v[174:177], v[86:89]
	v_mfma_f32_16x16x32_bf16 v[86:89], v[162:165], v[178:181], v[86:89]
	s_addc_u32 s38, s38, 0
	v_mfma_f32_16x16x32_bf16 v[22:25], v[170:173], v[178:181], v[22:25]
	v_mfma_f32_16x16x32_bf16 v[22:25], v[166:169], v[174:177], v[22:25]
	s_cmp_gt_u32 s39, 29
	v_mfma_f32_16x16x32_bf16 v[14:17], v[166:169], v[182:185], v[14:17]
	v_mfma_f32_16x16x32_bf16 v[14:17], v[170:173], v[186:189], v[14:17]
	s_mov_b64 s[0:1], s[4:5]
	v_mfma_f32_16x16x32_bf16 v[78:81], v[162:165], v[186:189], v[78:81]
	v_mfma_f32_16x16x32_bf16 v[78:81], v[158:161], v[182:185], v[78:81]
	v_mfma_f32_16x16x32_bf16 v[70:73], v[158:161], v[190:193], v[70:73]
	v_mfma_f32_16x16x32_bf16 v[70:73], v[162:165], v[204:207], v[70:73]
	v_mfma_f32_16x16x32_bf16 v[6:9], v[170:173], v[204:207], v[6:9]
	v_mfma_f32_16x16x32_bf16 v[6:9], v[166:169], v[190:193], v[6:9]
	v_mfma_f32_16x16x32_bf16 v[2:5], v[166:169], v[208:211], v[2:5]
	v_mfma_f32_16x16x32_bf16 v[2:5], v[170:173], v[212:215], v[2:5]
	v_mfma_f32_16x16x32_bf16 v[66:69], v[162:165], v[212:215], v[66:69]
	v_mfma_f32_16x16x32_bf16 v[66:69], v[158:161], v[208:211], v[66:69]
	s_setprio 0
	s_barrier
	s_cbranch_scc0 .LBB0_973

.LBB0_1264:
	s_andn2_saveexec_b64 s[0:1], s[0:1]
	s_or_b64 exec, exec, s[0:1]
	s_mov_b32 s0, 0xbfb8aa3b
	v_pk_mul_f32 v[2:3], v[158:159], s[0:1] op_sel_hi:[1,0]
	v_pk_mul_f32 v[12:13], v[30:31], s[0:1] op_sel_hi:[1,0]
	v_exp_f32_e32 v2, v2
	v_exp_f32_e32 v3, v3
	v_exp_f32_e32 v18, v12
	v_exp_f32_e32 v19, v13
	v_cvt_pk_bf16_f32 v8, v6, v7
	v_pk_add_f32 v[2:3], v[2:3], 1.0 op_sel_hi:[1,0]
	v_cvt_pk_bf16_f32 v24, v26, v27
	v_rcp_f32_e32 v2, v2
	v_rcp_f32_e32 v3, v3
	v_pk_add_f32 v[18:19], v[18:19], 1.0 op_sel_hi:[1,0]
	v_cvt_pk_bf16_f32 v9, v156, v157
	v_rcp_f32_e32 v18, v18
	v_rcp_f32_e32 v19, v19
	v_pk_mul_f32 v[2:3], v[158:159], v[2:3]
	v_cvt_pk_bf16_f32 v13, v154, v155
	v_pk_mul_f32 v[2:3], v[160:161], v[2:3]
	v_cvt_pk_bf16_f32 v12, v10, v11
	v_cvt_pk_bf16_f32 v29, v2, v3
	v_pk_mul_f32 v[2:3], v[30:31], v[18:19]
	v_pk_mul_f32 v[18:19], v[104:105], s[0:1] op_sel_hi:[1,0]
	v_pk_mul_f32 v[2:3], v[34:35], v[2:3]
	v_exp_f32_e32 v18, v18
	v_exp_f32_e32 v19, v19
	v_cvt_pk_bf16_f32 v28, v2, v3
	v_cvt_pk_bf16_f32 v11, v84, v85
	v_cvt_pk_bf16_f32 v10, v82, v83
	v_pk_add_f32 v[6:7], v[18:19], 1.0 op_sel_hi:[1,0]
	v_cvt_pk_bf16_f32 v17, v164, v165
	v_rcp_f32_e32 v6, v6
	v_rcp_f32_e32 v7, v7
	v_cvt_pk_bf16_f32 v16, v14, v15
	v_cvt_pk_bf16_f32 v15, v88, v89
	v_cvt_pk_bf16_f32 v14, v90, v91
	v_pk_mul_f32 v[2:3], v[104:105], v[6:7]
	v_pk_mul_f32 v[6:7], v[106:107], s[0:1] op_sel_hi:[1,0]
	v_pk_mul_f32 v[2:3], v[108:109], v[2:3]
	v_exp_f32_e32 v18, v6
	v_exp_f32_e32 v19, v7
	v_cvt_pk_bf16_f32 v27, v2, v3
	v_cvt_pk_bf16_f32 v7, v76, v77
	v_cvt_pk_bf16_f32 v6, v78, v79
	v_pk_add_f32 v[18:19], v[18:19], 1.0 op_sel_hi:[1,0]
	v_cvt_pk_bf16_f32 v21, v168, v169
	v_rcp_f32_e32 v30, v18
	v_rcp_f32_e32 v31, v19
	v_cvt_pk_bf16_f32 v20, v22, v23
	v_cvt_pk_bf16_f32 v19, v92, v93
	v_cvt_pk_bf16_f32 v18, v94, v95
	v_pk_mul_f32 v[2:3], v[106:107], v[30:31]
	v_cvt_pk_bf16_f32 v25, v172, v173
	v_pk_mul_f32 v[2:3], v[110:111], v[2:3]
	v_cvt_pk_bf16_f32 v23, v100, v101
	v_cvt_pk_bf16_f32 v26, v2, v3
	v_add_lshl_u32 v2, v74, v4, 1
	v_add_u32_e32 v3, 0x5800, v2
	global_store_dwordx4 v3, v[6:9], s[92:93]
	v_add_u32_e32 v3, 0x8400, v2
	global_store_dwordx4 v3, v[10:13], s[92:93]
	v_add_u32_e32 v3, 0xb000, v2
	global_store_dwordx4 v3, v[14:17], s[92:93]
	v_add_u32_e32 v3, 0xdc00, v2
	v_cvt_pk_bf16_f32 v22, v102, v103
	global_store_dwordx4 v3, v[18:21], s[92:93]
	v_add_u32_e32 v3, 0x10800, v2
	v_add_u32_e32 v2, 0x13400, v2
	s_and_b64 vcc, exec, s[2:3]
	s_mov_b64 s[0:1], -1
	global_store_dwordx4 v3, v[22:25], s[92:93]
	global_store_dwordx4 v2, v[26:29], s[92:93]
	s_cbranch_vccnz .LBB0_963
	v_mov_b32_e32 v2, v195
	s_andn2_b64 vcc, exec, s[22:23]
	s_cbranch_vccnz .LBB0_962
	s_branch .LBB0_962

.LBB0_1440:
	s_add_u32 s46, s20, 0x100
	s_waitcnt lgkmcnt(0)
	v_mov_b64_e32 v[8:9], v[4:5]
	v_mov_b64_e32 v[20:21], v[4:5]
	v_mov_b64_e32 v[24:25], v[4:5]
	v_mov_b64_e32 v[36:37], v[4:5]
	v_mov_b64_e32 v[40:41], v[4:5]
	v_mov_b64_e32 v[52:53], v[4:5]
	v_mov_b64_e32 v[56:57], v[4:5]
	v_mov_b64_e32 v[12:13], v[4:5]
	v_mov_b64_e32 v[16:17], v[4:5]
	v_mov_b64_e32 v[28:29], v[4:5]
	v_mov_b64_e32 v[32:33], v[4:5]
	v_mov_b64_e32 v[44:45], v[4:5]
	v_mov_b64_e32 v[48:49], v[4:5]
	v_mov_b64_e32 v[60:61], v[4:5]
	v_mov_b64_e32 v[64:65], v[4:5]
	v_mov_b64_e32 v[72:73], v[4:5]
	v_mov_b64_e32 v[76:77], v[4:5]
	v_mov_b64_e32 v[96:97], v[4:5]
	v_mov_b64_e32 v[104:105], v[4:5]
	v_mov_b64_e32 v[124:125], v[4:5]
	v_mov_b64_e32 v[128:129], v[4:5]
	v_mov_b64_e32 v[148:149], v[4:5]
	v_mov_b64_e32 v[168:169], v[4:5]
	v_mov_b64_e32 v[84:85], v[4:5]
	v_mov_b64_e32 v[92:93], v[4:5]
	v_mov_b64_e32 v[112:113], v[4:5]
	v_mov_b64_e32 v[116:117], v[4:5]
	v_mov_b64_e32 v[136:137], v[4:5]
	v_mov_b64_e32 v[140:141], v[4:5]
	v_mov_b64_e32 v[184:185], v[4:5]
	v_mov_b64_e32 v[188:189], v[4:5]
	s_addc_u32 s47, s21, 0
	s_mov_b32 s48, -2
	v_mov_b64_e32 v[6:7], v[2:3]
	v_mov_b64_e32 v[18:19], v[2:3]
	v_mov_b64_e32 v[22:23], v[2:3]
	v_mov_b64_e32 v[34:35], v[2:3]
	v_mov_b64_e32 v[38:39], v[2:3]
	v_mov_b64_e32 v[50:51], v[2:3]
	v_mov_b64_e32 v[54:55], v[2:3]
	v_mov_b64_e32 v[10:11], v[2:3]
	v_mov_b64_e32 v[14:15], v[2:3]
	v_mov_b64_e32 v[26:27], v[2:3]
	v_mov_b64_e32 v[30:31], v[2:3]
	v_mov_b64_e32 v[42:43], v[2:3]
	v_mov_b64_e32 v[46:47], v[2:3]
	v_mov_b64_e32 v[58:59], v[2:3]
	v_mov_b64_e32 v[62:63], v[2:3]
	v_mov_b64_e32 v[70:71], v[2:3]
	v_mov_b64_e32 v[74:75], v[2:3]
	v_mov_b64_e32 v[94:95], v[2:3]
	v_mov_b64_e32 v[102:103], v[2:3]
	v_mov_b64_e32 v[122:123], v[2:3]
	v_mov_b64_e32 v[126:127], v[2:3]
	v_mov_b64_e32 v[146:147], v[2:3]
	v_mov_b64_e32 v[166:167], v[2:3]
	v_mov_b64_e32 v[82:83], v[2:3]
	v_mov_b64_e32 v[90:91], v[2:3]
	v_mov_b64_e32 v[110:111], v[2:3]
	v_mov_b64_e32 v[114:115], v[2:3]
	v_mov_b64_e32 v[134:135], v[2:3]
	v_mov_b64_e32 v[138:139], v[2:3]
	v_mov_b64_e32 v[182:183], v[2:3]
	v_mov_b64_e32 v[186:187], v[2:3]
	s_cmp_eq_u32 s41, 1
	s_cbranch_scc1 .Lrealign_8
	s_andn2_b64 vcc, exec, s[12:13]
	s_cbranch_vccnz .Lrealign_8
	s_barrier
.Lrealign_8:
.LBB0_1441:
	s_add_u32 vcc_lo, s18, 0xffea0000
	s_addc_u32 vcc_hi, s19, -1
	s_mov_b32 m0, s38
	s_nop 0
	global_load_lds_dwordx4 v210, vcc
	s_mov_b32 m0, s40
	s_nop 0
	global_load_lds_dwordx4 v212, vcc
	ds_read_b128 v[66:69], v198
	ds_read_b128 v[78:81], v198 offset:1024
	ds_read_b128 v[86:89], v198 offset:2048
	ds_read_b128 v[98:101], v198 offset:3072
	ds_read_b128 v[106:109], v198 offset:16384
	ds_read_b128 v[118:121], v198 offset:17408
	ds_read_b128 v[130:133], v198 offset:18432
	ds_read_b128 v[142:145], v198 offset:19456
	ds_read_b128 v[150:153], v234
	ds_read_b128 v[154:157], v234 offset:1024
	ds_read_b128 v[158:161], v234 offset:2048
	ds_read_b128 v[162:165], v234 offset:3072
	ds_read_b128 v[170:173], v234 offset:4096
	ds_read_b128 v[174:177], v234 offset:5120
	ds_read_b128 v[178:181], v234 offset:6144
	ds_read_b128 v[190:193], v234 offset:7168
	s_add_u32 s20, s18, 0x100
	s_addc_u32 s21, s19, 0
	s_add_i32 s49, 0, 0x10000
	s_cmpk_eq_i32 s48, 0x54
	s_cselect_b32 s25, s1, s21
	s_cselect_b32 s24, s0, s20
	s_cselect_b32 s23, s17, s47
	s_cselect_b32 s22, s16, s46
	s_add_i32 s50, 0, 0x14000
	s_add_i32 m0, s28, 0xc000
	s_nop 0
	global_load_lds_dwordx4 v210, s[18:19]
	s_add_i32 m0, s28, 0xe000
	s_nop 0
	global_load_lds_dwordx4 v212, s[18:19]
	s_waitcnt vmcnt(8)
	s_waitcnt lgkmcnt(0)
	v_mfma_f32_16x16x32_bf16 v[186:189], v[66:69], v[150:153], v[186:189]
	v_mfma_f32_16x16x32_bf16 v[186:189], v[78:81], v[154:157], v[186:189]
	s_barrier
	s_setprio 1
	v_mfma_f32_16x16x32_bf16 v[182:185], v[98:101], v[154:157], v[182:185]
	v_mfma_f32_16x16x32_bf16 v[182:185], v[86:89], v[150:153], v[182:185]
	v_mfma_f32_16x16x32_bf16 v[134:137], v[86:89], v[158:161], v[134:137]
	v_mfma_f32_16x16x32_bf16 v[134:137], v[98:101], v[162:165], v[134:137]
	v_mfma_f32_16x16x32_bf16 v[138:141], v[78:81], v[162:165], v[138:141]
	v_mfma_f32_16x16x32_bf16 v[138:141], v[66:69], v[158:161], v[138:141]
	v_mfma_f32_16x16x32_bf16 v[114:117], v[66:69], v[170:173], v[114:117]
	v_mfma_f32_16x16x32_bf16 v[114:117], v[78:81], v[174:177], v[114:117]
	v_mfma_f32_16x16x32_bf16 v[110:113], v[98:101], v[174:177], v[110:113]
	v_mfma_f32_16x16x32_bf16 v[110:113], v[86:89], v[170:173], v[110:113]
	v_mfma_f32_16x16x32_bf16 v[82:85], v[86:89], v[178:181], v[82:85]
	v_mfma_f32_16x16x32_bf16 v[82:85], v[98:101], v[190:193], v[82:85]
	v_mfma_f32_16x16x32_bf16 v[90:93], v[78:81], v[190:193], v[90:93]
	v_mfma_f32_16x16x32_bf16 v[90:93], v[66:69], v[178:181], v[90:93]
	v_mfma_f32_16x16x32_bf16 v[166:169], v[106:109], v[150:153], v[166:169]
	v_mfma_f32_16x16x32_bf16 v[166:169], v[118:121], v[154:157], v[166:169]
	v_mfma_f32_16x16x32_bf16 v[146:149], v[142:145], v[154:157], v[146:149]
	v_mfma_f32_16x16x32_bf16 v[146:149], v[130:133], v[150:153], v[146:149]
	v_mfma_f32_16x16x32_bf16 v[122:125], v[130:133], v[158:161], v[122:125]
	v_mfma_f32_16x16x32_bf16 v[122:125], v[142:145], v[162:165], v[122:125]
	v_mfma_f32_16x16x32_bf16 v[126:129], v[118:121], v[162:165], v[126:129]
	v_mfma_f32_16x16x32_bf16 v[126:129], v[106:109], v[158:161], v[126:129]
	v_mfma_f32_16x16x32_bf16 v[102:105], v[106:109], v[170:173], v[102:105]
	v_mfma_f32_16x16x32_bf16 v[102:105], v[118:121], v[174:177], v[102:105]
	v_mfma_f32_16x16x32_bf16 v[94:97], v[142:145], v[174:177], v[94:97]
	v_mfma_f32_16x16x32_bf16 v[94:97], v[130:133], v[170:173], v[94:97]
	v_mfma_f32_16x16x32_bf16 v[70:73], v[130:133], v[178:181], v[70:73]
	v_mfma_f32_16x16x32_bf16 v[70:73], v[142:145], v[190:193], v[70:73]
	v_mfma_f32_16x16x32_bf16 v[74:77], v[118:121], v[190:193], v[74:77]
	v_mfma_f32_16x16x32_bf16 v[74:77], v[106:109], v[178:181], v[74:77]
	s_setprio 0
	s_barrier
	ds_read_b128 v[150:153], v234 offset:16384
	ds_read_b128 v[154:157], v234 offset:17408
	ds_read_b128 v[158:161], v234 offset:18432
	ds_read_b128 v[162:165], v234 offset:19456
	ds_read_b128 v[170:173], v234 offset:20480
	ds_read_b128 v[174:177], v234 offset:21504
	ds_read_b128 v[178:181], v234 offset:22528
	ds_read_b128 v[190:193], v234 offset:23552
	s_add_i32 s18, s49, s26
	s_mov_b32 m0, s18
	s_nop 0
	global_load_lds_dwordx4 v194, s[22:23]
	s_add_i32 m0, s18, 0x2000
	s_add_u32 s18, s22, 0x160000
	s_addc_u32 s19, s23, 0
	s_add_i32 s49, s50, s26
	global_load_lds_dwordx4 v204, s[22:23]
	s_mov_b32 m0, s49
	s_nop 0
	global_load_lds_dwordx4 v194, s[18:19]
	s_add_i32 m0, s49, 0x2000
	s_nop 0
	global_load_lds_dwordx4 v204, s[18:19]
	s_waitcnt vmcnt(6)
	s_waitcnt lgkmcnt(0)
	v_mfma_f32_16x16x32_bf16 v[62:65], v[66:69], v[150:153], v[62:65]
	v_mfma_f32_16x16x32_bf16 v[62:65], v[78:81], v[154:157], v[62:65]
	s_barrier
	s_setprio 1
	v_mfma_f32_16x16x32_bf16 v[58:61], v[98:101], v[154:157], v[58:61]
	v_mfma_f32_16x16x32_bf16 v[58:61], v[86:89], v[150:153], v[58:61]
	v_mfma_f32_16x16x32_bf16 v[42:45], v[86:89], v[158:161], v[42:45]
	v_mfma_f32_16x16x32_bf16 v[42:45], v[98:101], v[162:165], v[42:45]
	v_mfma_f32_16x16x32_bf16 v[46:49], v[78:81], v[162:165], v[46:49]
	v_mfma_f32_16x16x32_bf16 v[46:49], v[66:69], v[158:161], v[46:49]
	v_mfma_f32_16x16x32_bf16 v[30:33], v[66:69], v[170:173], v[30:33]
	v_mfma_f32_16x16x32_bf16 v[30:33], v[78:81], v[174:177], v[30:33]
	v_mfma_f32_16x16x32_bf16 v[26:29], v[98:101], v[174:177], v[26:29]
	v_mfma_f32_16x16x32_bf16 v[26:29], v[86:89], v[170:173], v[26:29]
	v_mfma_f32_16x16x32_bf16 v[10:13], v[86:89], v[178:181], v[10:13]
	v_mfma_f32_16x16x32_bf16 v[10:13], v[98:101], v[190:193], v[10:13]
	v_mfma_f32_16x16x32_bf16 v[14:17], v[78:81], v[190:193], v[14:17]
	v_mfma_f32_16x16x32_bf16 v[14:17], v[66:69], v[178:181], v[14:17]
	v_mfma_f32_16x16x32_bf16 v[54:57], v[106:109], v[150:153], v[54:57]
	v_mfma_f32_16x16x32_bf16 v[54:57], v[118:121], v[154:157], v[54:57]
	v_mfma_f32_16x16x32_bf16 v[50:53], v[142:145], v[154:157], v[50:53]
	v_mfma_f32_16x16x32_bf16 v[50:53], v[130:133], v[150:153], v[50:53]
	v_mfma_f32_16x16x32_bf16 v[34:37], v[130:133], v[158:161], v[34:37]
	v_mfma_f32_16x16x32_bf16 v[34:37], v[142:145], v[162:165], v[34:37]
	v_mfma_f32_16x16x32_bf16 v[38:41], v[118:121], v[162:165], v[38:41]
	v_mfma_f32_16x16x32_bf16 v[38:41], v[106:109], v[158:161], v[38:41]
	v_mfma_f32_16x16x32_bf16 v[22:25], v[106:109], v[170:173], v[22:25]
	v_mfma_f32_16x16x32_bf16 v[22:25], v[118:121], v[174:177], v[22:25]
	v_mfma_f32_16x16x32_bf16 v[18:21], v[142:145], v[174:177], v[18:21]
	v_mfma_f32_16x16x32_bf16 v[18:21], v[130:133], v[170:173], v[18:21]
	v_mfma_f32_16x16x32_bf16 v[2:5], v[130:133], v[178:181], v[2:5]
	v_mfma_f32_16x16x32_bf16 v[2:5], v[142:145], v[190:193], v[2:5]
	v_mfma_f32_16x16x32_bf16 v[6:9], v[118:121], v[190:193], v[6:9]
	v_mfma_f32_16x16x32_bf16 v[6:9], v[106:109], v[178:181], v[6:9]
	s_setprio 0
	s_barrier
	s_mov_b32 m0, s28
	s_nop 0
	global_load_lds_dwordx4 v208, s[24:25]
	s_mov_b32 m0, s29
	s_nop 0
	global_load_lds_dwordx4 v206, s[24:25]
	ds_read_b128 v[66:69], v198 offset:32768
	ds_read_b128 v[78:81], v198 offset:33792
	ds_read_b128 v[86:89], v198 offset:34816
	ds_read_b128 v[98:101], v198 offset:35840
	ds_read_b128 v[106:109], v198 offset:49152
	ds_read_b128 v[118:121], v198 offset:50176
	ds_read_b128 v[130:133], v198 offset:51200
	ds_read_b128 v[142:145], v198 offset:52224
	ds_read_b128 v[150:153], v234 offset:32768
	ds_read_b128 v[154:157], v234 offset:33792
	ds_read_b128 v[158:161], v234 offset:34816
	ds_read_b128 v[162:165], v234 offset:35840
	ds_read_b128 v[170:173], v234 offset:36864
	ds_read_b128 v[174:177], v234 offset:37888
	ds_read_b128 v[178:181], v234 offset:38912
	ds_read_b128 v[190:193], v234 offset:39936
	s_add_i32 s49, 0, 0x18000
	s_add_i32 s50, 0, 0x1c000
	s_add_u32 s18, s24, 0x160000
	s_addc_u32 s19, s25, 0
	s_mov_b32 m0, s33
	s_nop 0
	global_load_lds_dwordx4 v208, s[18:19]
	s_mov_b32 m0, s37
	s_nop 0
	global_load_lds_dwordx4 v206, s[18:19]
	s_waitcnt vmcnt(8)
	s_waitcnt lgkmcnt(0)
	v_mfma_f32_16x16x32_bf16 v[186:189], v[66:69], v[150:153], v[186:189]
	v_mfma_f32_16x16x32_bf16 v[186:189], v[78:81], v[154:157], v[186:189]
	s_barrier
	s_setprio 1
	v_mfma_f32_16x16x32_bf16 v[182:185], v[98:101], v[154:157], v[182:185]
	v_mfma_f32_16x16x32_bf16 v[182:185], v[86:89], v[150:153], v[182:185]
	v_mfma_f32_16x16x32_bf16 v[134:137], v[86:89], v[158:161], v[134:137]
	v_mfma_f32_16x16x32_bf16 v[134:137], v[98:101], v[162:165], v[134:137]
	v_mfma_f32_16x16x32_bf16 v[138:141], v[78:81], v[162:165], v[138:141]
	v_mfma_f32_16x16x32_bf16 v[138:141], v[66:69], v[158:161], v[138:141]
	v_mfma_f32_16x16x32_bf16 v[114:117], v[66:69], v[170:173], v[114:117]
	v_mfma_f32_16x16x32_bf16 v[114:117], v[78:81], v[174:177], v[114:117]
	v_mfma_f32_16x16x32_bf16 v[110:113], v[98:101], v[174:177], v[110:113]
	v_mfma_f32_16x16x32_bf16 v[110:113], v[86:89], v[170:173], v[110:113]
	v_mfma_f32_16x16x32_bf16 v[82:85], v[86:89], v[178:181], v[82:85]
	v_mfma_f32_16x16x32_bf16 v[82:85], v[98:101], v[190:193], v[82:85]
	v_mfma_f32_16x16x32_bf16 v[90:93], v[78:81], v[190:193], v[90:93]
	v_mfma_f32_16x16x32_bf16 v[90:93], v[66:69], v[178:181], v[90:93]
	v_mfma_f32_16x16x32_bf16 v[166:169], v[106:109], v[150:153], v[166:169]
	v_mfma_f32_16x16x32_bf16 v[166:169], v[118:121], v[154:157], v[166:169]
	v_mfma_f32_16x16x32_bf16 v[146:149], v[142:145], v[154:157], v[146:149]
	v_mfma_f32_16x16x32_bf16 v[146:149], v[130:133], v[150:153], v[146:149]
	v_mfma_f32_16x16x32_bf16 v[122:125], v[130:133], v[158:161], v[122:125]
	v_mfma_f32_16x16x32_bf16 v[122:125], v[142:145], v[162:165], v[122:125]
	v_mfma_f32_16x16x32_bf16 v[126:129], v[118:121], v[162:165], v[126:129]
	v_mfma_f32_16x16x32_bf16 v[126:129], v[106:109], v[158:161], v[126:129]
	v_mfma_f32_16x16x32_bf16 v[102:105], v[106:109], v[170:173], v[102:105]
	v_mfma_f32_16x16x32_bf16 v[102:105], v[118:121], v[174:177], v[102:105]
	v_mfma_f32_16x16x32_bf16 v[94:97], v[142:145], v[174:177], v[94:97]
	v_mfma_f32_16x16x32_bf16 v[94:97], v[130:133], v[170:173], v[94:97]
	v_mfma_f32_16x16x32_bf16 v[70:73], v[130:133], v[178:181], v[70:73]
	v_mfma_f32_16x16x32_bf16 v[70:73], v[142:145], v[190:193], v[70:73]
	v_mfma_f32_16x16x32_bf16 v[74:77], v[118:121], v[190:193], v[74:77]
	v_mfma_f32_16x16x32_bf16 v[74:77], v[106:109], v[178:181], v[74:77]
	s_setprio 0
	s_barrier
	ds_read_b128 v[150:153], v234 offset:49152
	ds_read_b128 v[154:157], v234 offset:50176
	ds_read_b128 v[158:161], v234 offset:51200
	ds_read_b128 v[162:165], v234 offset:52224
	ds_read_b128 v[170:173], v234 offset:53248
	ds_read_b128 v[174:177], v234 offset:54272
	ds_read_b128 v[178:181], v234 offset:55296
	ds_read_b128 v[190:193], v234 offset:56320
	s_add_i32 s18, s49, s26
	s_add_u32 vcc_lo, s22, s94
	s_addc_u32 vcc_hi, s23, s95
	s_mov_b32 m0, s18
	s_nop 0
	global_load_lds_dwordx4 v194, vcc
	s_add_i32 m0, s18, 0x2000
	s_add_u32 s18, s22, 0x160080
	s_addc_u32 s19, s23, 0
	s_add_i32 s22, s50, s26
	global_load_lds_dwordx4 v204, vcc
	s_mov_b32 m0, s22
	s_nop 0
	global_load_lds_dwordx4 v194, s[18:19]
	s_add_i32 m0, s22, 0x2000
	s_nop 0
	global_load_lds_dwordx4 v204, s[18:19]
	s_waitcnt vmcnt(6)
	s_waitcnt lgkmcnt(0)
	v_mfma_f32_16x16x32_bf16 v[62:65], v[66:69], v[150:153], v[62:65]
	v_mfma_f32_16x16x32_bf16 v[62:65], v[78:81], v[154:157], v[62:65]
	s_barrier
	s_setprio 1
	v_mfma_f32_16x16x32_bf16 v[58:61], v[98:101], v[154:157], v[58:61]
	v_mfma_f32_16x16x32_bf16 v[58:61], v[86:89], v[150:153], v[58:61]
	v_mfma_f32_16x16x32_bf16 v[42:45], v[86:89], v[158:161], v[42:45]
	v_mfma_f32_16x16x32_bf16 v[42:45], v[98:101], v[162:165], v[42:45]
	v_mfma_f32_16x16x32_bf16 v[46:49], v[78:81], v[162:165], v[46:49]
	v_mfma_f32_16x16x32_bf16 v[46:49], v[66:69], v[158:161], v[46:49]
	v_mfma_f32_16x16x32_bf16 v[30:33], v[66:69], v[170:173], v[30:33]
	v_mfma_f32_16x16x32_bf16 v[30:33], v[78:81], v[174:177], v[30:33]
	v_mfma_f32_16x16x32_bf16 v[26:29], v[98:101], v[174:177], v[26:29]
	v_mfma_f32_16x16x32_bf16 v[26:29], v[86:89], v[170:173], v[26:29]
	v_mfma_f32_16x16x32_bf16 v[10:13], v[86:89], v[178:181], v[10:13]
	v_mfma_f32_16x16x32_bf16 v[10:13], v[98:101], v[190:193], v[10:13]
	s_add_i32 s48, s48, 2
	v_mfma_f32_16x16x32_bf16 v[14:17], v[78:81], v[190:193], v[14:17]
	v_mfma_f32_16x16x32_bf16 v[14:17], v[66:69], v[178:181], v[14:17]
	s_add_u32 s46, s46, 0x100
	v_mfma_f32_16x16x32_bf16 v[54:57], v[106:109], v[150:153], v[54:57]
	v_mfma_f32_16x16x32_bf16 v[54:57], v[118:121], v[154:157], v[54:57]
	s_addc_u32 s47, s47, 0
	v_mfma_f32_16x16x32_bf16 v[50:53], v[142:145], v[154:157], v[50:53]
	v_mfma_f32_16x16x32_bf16 v[50:53], v[130:133], v[150:153], v[50:53]
	s_cmpk_gt_u32 s48, 0x55
	v_mfma_f32_16x16x32_bf16 v[34:37], v[130:133], v[158:161], v[34:37]
	v_mfma_f32_16x16x32_bf16 v[34:37], v[142:145], v[162:165], v[34:37]
	s_mov_b64 s[18:19], s[20:21]
	v_mfma_f32_16x16x32_bf16 v[38:41], v[118:121], v[162:165], v[38:41]
	v_mfma_f32_16x16x32_bf16 v[38:41], v[106:109], v[158:161], v[38:41]
	v_mfma_f32_16x16x32_bf16 v[22:25], v[106:109], v[170:173], v[22:25]
	v_mfma_f32_16x16x32_bf16 v[22:25], v[118:121], v[174:177], v[22:25]
	v_mfma_f32_16x16x32_bf16 v[18:21], v[142:145], v[174:177], v[18:21]
	v_mfma_f32_16x16x32_bf16 v[18:21], v[130:133], v[170:173], v[18:21]
	v_mfma_f32_16x16x32_bf16 v[2:5], v[130:133], v[178:181], v[2:5]
	v_mfma_f32_16x16x32_bf16 v[2:5], v[142:145], v[190:193], v[2:5]
	v_mfma_f32_16x16x32_bf16 v[6:9], v[118:121], v[190:193], v[6:9]
	v_mfma_f32_16x16x32_bf16 v[6:9], v[106:109], v[178:181], v[6:9]
	s_setprio 0
	s_barrier
	s_cbranch_scc0 .LBB0_1441

.LBB0_1446:
	s_or_b64 exec, exec, s[18:19]
	s_and_b64 vcc, exec, s[4:5]
	s_mov_b64 s[4:5], -1
	s_cbranch_vccnz .LBB0_1433
	v_mov_b32_e32 v2, v195
	s_andn2_b64 vcc, exec, s[12:13]
	s_cbranch_vccnz .LBB0_1432
	s_branch .LBB0_1432

.LBB0_1509:
	s_ashr_i32 s15, s14, 31
	s_lshl_b64 s[28:29], s[14:15], 7
	s_and_b64 s[6:7], s[6:7], exec
	s_cselect_b32 s23, s28, 0
	s_cselect_b32 s15, s29, 0
	s_add_u32 s6, s16, s23
	s_addc_u32 s7, s17, s15
	s_add_u32 s16, s26, s23
	s_addc_u32 s17, s27, s15
	s_cmp_lt_i32 s21, 1
	s_cbranch_scc1 .LBB0_1532
	s_add_i32 s15, s21, -2
	s_add_u32 s23, s24, 0x100
	s_waitcnt lgkmcnt(0)
	v_mov_b64_e32 v[8:9], v[4:5]
	v_mov_b64_e32 v[20:21], v[4:5]
	v_mov_b64_e32 v[24:25], v[4:5]
	v_mov_b64_e32 v[36:37], v[4:5]
	v_mov_b64_e32 v[40:41], v[4:5]
	v_mov_b64_e32 v[52:53], v[4:5]
	v_mov_b64_e32 v[56:57], v[4:5]
	v_mov_b64_e32 v[12:13], v[4:5]
	v_mov_b64_e32 v[16:17], v[4:5]
	v_mov_b64_e32 v[28:29], v[4:5]
	v_mov_b64_e32 v[32:33], v[4:5]
	v_mov_b64_e32 v[44:45], v[4:5]
	v_mov_b64_e32 v[48:49], v[4:5]
	v_mov_b64_e32 v[60:61], v[4:5]
	v_mov_b64_e32 v[64:65], v[4:5]
	v_mov_b64_e32 v[68:69], v[4:5]
	v_mov_b64_e32 v[72:73], v[4:5]
	v_mov_b64_e32 v[84:85], v[4:5]
	v_mov_b64_e32 v[88:89], v[4:5]
	v_mov_b64_e32 v[100:101], v[4:5]
	v_mov_b64_e32 v[104:105], v[4:5]
	v_mov_b64_e32 v[116:117], v[4:5]
	v_mov_b64_e32 v[120:121], v[4:5]
	v_mov_b64_e32 v[76:77], v[4:5]
	v_mov_b64_e32 v[80:81], v[4:5]
	v_mov_b64_e32 v[92:93], v[4:5]
	v_mov_b64_e32 v[96:97], v[4:5]
	v_mov_b64_e32 v[108:109], v[4:5]
	v_mov_b64_e32 v[112:113], v[4:5]
	v_mov_b64_e32 v[124:125], v[4:5]
	v_mov_b64_e32 v[128:129], v[4:5]
	s_addc_u32 s54, s25, 0
	s_mov_b32 s26, 0
	v_mov_b64_e32 v[6:7], v[2:3]
	v_mov_b64_e32 v[18:19], v[2:3]
	v_mov_b64_e32 v[22:23], v[2:3]
	v_mov_b64_e32 v[34:35], v[2:3]
	v_mov_b64_e32 v[38:39], v[2:3]
	v_mov_b64_e32 v[50:51], v[2:3]
	v_mov_b64_e32 v[54:55], v[2:3]
	v_mov_b64_e32 v[10:11], v[2:3]
	v_mov_b64_e32 v[14:15], v[2:3]
	v_mov_b64_e32 v[26:27], v[2:3]
	v_mov_b64_e32 v[30:31], v[2:3]
	v_mov_b64_e32 v[42:43], v[2:3]
	v_mov_b64_e32 v[46:47], v[2:3]
	v_mov_b64_e32 v[58:59], v[2:3]
	v_mov_b64_e32 v[62:63], v[2:3]
	v_mov_b64_e32 v[66:67], v[2:3]
	v_mov_b64_e32 v[70:71], v[2:3]
	v_mov_b64_e32 v[82:83], v[2:3]
	v_mov_b64_e32 v[86:87], v[2:3]
	v_mov_b64_e32 v[98:99], v[2:3]
	v_mov_b64_e32 v[102:103], v[2:3]
	v_mov_b64_e32 v[114:115], v[2:3]
	v_mov_b64_e32 v[118:119], v[2:3]
	v_mov_b64_e32 v[74:75], v[2:3]
	v_mov_b64_e32 v[78:79], v[2:3]
	v_mov_b64_e32 v[90:91], v[2:3]
	v_mov_b64_e32 v[94:95], v[2:3]
	v_mov_b64_e32 v[106:107], v[2:3]
	v_mov_b64_e32 v[110:111], v[2:3]
	v_mov_b64_e32 v[122:123], v[2:3]
	v_mov_b64_e32 v[126:127], v[2:3]
	s_cmp_eq_u32 s46, 1
	s_cbranch_scc1 .Lrealign_9
	s_andn2_b64 vcc, exec, s[0:1]
	s_cbranch_vccnz .Lrealign_9
	s_barrier
.Lrealign_9:
.LBB0_1511:
	s_add_u32 vcc_lo, s18, 0xffea0000
	s_addc_u32 vcc_hi, s19, -1
	s_mov_b32 m0, s44
	s_nop 0
	global_load_lds_dwordx4 v210, vcc
	s_mov_b32 m0, s45
	s_nop 0
	global_load_lds_dwordx4 v212, vcc
	ds_read_b128 v[130:133], v235
	ds_read_b128 v[134:137], v235 offset:1024
	ds_read_b128 v[138:141], v235 offset:2048
	ds_read_b128 v[142:145], v235 offset:3072
	ds_read_b128 v[146:149], v235 offset:16384
	ds_read_b128 v[150:153], v235 offset:17408
	ds_read_b128 v[154:157], v235 offset:18432
	ds_read_b128 v[158:161], v235 offset:19456
	ds_read_b128 v[162:165], v237
	ds_read_b128 v[166:169], v237 offset:1024
	ds_read_b128 v[170:173], v237 offset:2048
	ds_read_b128 v[174:177], v237 offset:3072
	ds_read_b128 v[178:181], v237 offset:4096
	ds_read_b128 v[182:185], v237 offset:5120
	ds_read_b128 v[186:189], v237 offset:6144
	ds_read_b128 v[190:193], v237 offset:7168
	s_add_i32 s55, s26, 2
	s_add_u32 s24, s18, 0x100
	s_addc_u32 s25, s19, 0
	s_add_i32 s56, 0, 0x10000
	s_cmp_eq_u32 s15, s26
	s_cselect_b32 s29, s7, s25
	s_cselect_b32 s28, s6, s24
	s_cselect_b32 s27, s17, s54
	s_cselect_b32 s26, s16, s23
	s_add_i32 s57, 0, 0x14000
	s_add_i32 m0, s40, 0xc000
	s_nop 0
	global_load_lds_dwordx4 v210, s[18:19]
	s_add_i32 m0, s40, 0xe000
	s_nop 0
	global_load_lds_dwordx4 v212, s[18:19]
	s_waitcnt vmcnt(8)
	s_waitcnt lgkmcnt(0)
	v_mfma_f32_16x16x32_bf16 v[126:129], v[130:133], v[162:165], v[126:129]
	v_mfma_f32_16x16x32_bf16 v[126:129], v[134:137], v[166:169], v[126:129]
	s_barrier
	s_setprio 1
	v_mfma_f32_16x16x32_bf16 v[122:125], v[142:145], v[166:169], v[122:125]
	v_mfma_f32_16x16x32_bf16 v[122:125], v[138:141], v[162:165], v[122:125]
	v_mfma_f32_16x16x32_bf16 v[106:109], v[138:141], v[170:173], v[106:109]
	v_mfma_f32_16x16x32_bf16 v[106:109], v[142:145], v[174:177], v[106:109]
	v_mfma_f32_16x16x32_bf16 v[110:113], v[134:137], v[174:177], v[110:113]
	v_mfma_f32_16x16x32_bf16 v[110:113], v[130:133], v[170:173], v[110:113]
	v_mfma_f32_16x16x32_bf16 v[94:97], v[130:133], v[178:181], v[94:97]
	v_mfma_f32_16x16x32_bf16 v[94:97], v[134:137], v[182:185], v[94:97]
	v_mfma_f32_16x16x32_bf16 v[90:93], v[142:145], v[182:185], v[90:93]
	v_mfma_f32_16x16x32_bf16 v[90:93], v[138:141], v[178:181], v[90:93]
	v_mfma_f32_16x16x32_bf16 v[74:77], v[138:141], v[186:189], v[74:77]
	v_mfma_f32_16x16x32_bf16 v[74:77], v[142:145], v[190:193], v[74:77]
	v_mfma_f32_16x16x32_bf16 v[78:81], v[134:137], v[190:193], v[78:81]
	v_mfma_f32_16x16x32_bf16 v[78:81], v[130:133], v[186:189], v[78:81]
	v_mfma_f32_16x16x32_bf16 v[118:121], v[146:149], v[162:165], v[118:121]
	v_mfma_f32_16x16x32_bf16 v[118:121], v[150:153], v[166:169], v[118:121]
	v_mfma_f32_16x16x32_bf16 v[114:117], v[158:161], v[166:169], v[114:117]
	v_mfma_f32_16x16x32_bf16 v[114:117], v[154:157], v[162:165], v[114:117]
	v_mfma_f32_16x16x32_bf16 v[98:101], v[154:157], v[170:173], v[98:101]
	v_mfma_f32_16x16x32_bf16 v[98:101], v[158:161], v[174:177], v[98:101]
	v_mfma_f32_16x16x32_bf16 v[102:105], v[150:153], v[174:177], v[102:105]
	v_mfma_f32_16x16x32_bf16 v[102:105], v[146:149], v[170:173], v[102:105]
	v_mfma_f32_16x16x32_bf16 v[86:89], v[146:149], v[178:181], v[86:89]
	v_mfma_f32_16x16x32_bf16 v[86:89], v[150:153], v[182:185], v[86:89]
	v_mfma_f32_16x16x32_bf16 v[82:85], v[158:161], v[182:185], v[82:85]
	v_mfma_f32_16x16x32_bf16 v[82:85], v[154:157], v[178:181], v[82:85]
	v_mfma_f32_16x16x32_bf16 v[66:69], v[154:157], v[186:189], v[66:69]
	v_mfma_f32_16x16x32_bf16 v[66:69], v[158:161], v[190:193], v[66:69]
	v_mfma_f32_16x16x32_bf16 v[70:73], v[150:153], v[190:193], v[70:73]
	v_mfma_f32_16x16x32_bf16 v[70:73], v[146:149], v[186:189], v[70:73]
	s_setprio 0
	s_barrier
	ds_read_b128 v[162:165], v237 offset:16384
	ds_read_b128 v[166:169], v237 offset:17408
	ds_read_b128 v[170:173], v237 offset:18432
	ds_read_b128 v[174:177], v237 offset:19456
	ds_read_b128 v[178:181], v237 offset:20480
	ds_read_b128 v[182:185], v237 offset:21504
	ds_read_b128 v[186:189], v237 offset:22528
	ds_read_b128 v[190:193], v237 offset:23552
	s_add_i32 s18, s56, s39
	s_mov_b32 m0, s18
	s_nop 0
	global_load_lds_dwordx4 v194, s[26:27]
	s_add_i32 m0, s18, 0x2000
	s_add_u32 s18, s26, 0x160000
	s_addc_u32 s19, s27, 0
	s_add_i32 s56, s57, s39
	global_load_lds_dwordx4 v208, s[26:27]
	s_mov_b32 m0, s56
	s_nop 0
	global_load_lds_dwordx4 v194, s[18:19]
	s_add_i32 m0, s56, 0x2000
	s_nop 0
	global_load_lds_dwordx4 v208, s[18:19]
	s_waitcnt vmcnt(6)
	s_waitcnt lgkmcnt(0)
	v_mfma_f32_16x16x32_bf16 v[62:65], v[130:133], v[162:165], v[62:65]
	v_mfma_f32_16x16x32_bf16 v[62:65], v[134:137], v[166:169], v[62:65]
	s_barrier
	s_setprio 1
	v_mfma_f32_16x16x32_bf16 v[58:61], v[142:145], v[166:169], v[58:61]
	v_mfma_f32_16x16x32_bf16 v[58:61], v[138:141], v[162:165], v[58:61]
	v_mfma_f32_16x16x32_bf16 v[42:45], v[138:141], v[170:173], v[42:45]
	v_mfma_f32_16x16x32_bf16 v[42:45], v[142:145], v[174:177], v[42:45]
	v_mfma_f32_16x16x32_bf16 v[46:49], v[134:137], v[174:177], v[46:49]
	v_mfma_f32_16x16x32_bf16 v[46:49], v[130:133], v[170:173], v[46:49]
	v_mfma_f32_16x16x32_bf16 v[30:33], v[130:133], v[178:181], v[30:33]
	v_mfma_f32_16x16x32_bf16 v[30:33], v[134:137], v[182:185], v[30:33]
	v_mfma_f32_16x16x32_bf16 v[26:29], v[142:145], v[182:185], v[26:29]
	v_mfma_f32_16x16x32_bf16 v[26:29], v[138:141], v[178:181], v[26:29]
	v_mfma_f32_16x16x32_bf16 v[10:13], v[138:141], v[186:189], v[10:13]
	v_mfma_f32_16x16x32_bf16 v[10:13], v[142:145], v[190:193], v[10:13]
	v_mfma_f32_16x16x32_bf16 v[14:17], v[134:137], v[190:193], v[14:17]
	v_mfma_f32_16x16x32_bf16 v[14:17], v[130:133], v[186:189], v[14:17]
	v_mfma_f32_16x16x32_bf16 v[54:57], v[146:149], v[162:165], v[54:57]
	v_mfma_f32_16x16x32_bf16 v[54:57], v[150:153], v[166:169], v[54:57]
	v_mfma_f32_16x16x32_bf16 v[50:53], v[158:161], v[166:169], v[50:53]
	v_mfma_f32_16x16x32_bf16 v[50:53], v[154:157], v[162:165], v[50:53]
	v_mfma_f32_16x16x32_bf16 v[34:37], v[154:157], v[170:173], v[34:37]
	v_mfma_f32_16x16x32_bf16 v[34:37], v[158:161], v[174:177], v[34:37]
	v_mfma_f32_16x16x32_bf16 v[38:41], v[150:153], v[174:177], v[38:41]
	v_mfma_f32_16x16x32_bf16 v[38:41], v[146:149], v[170:173], v[38:41]
	v_mfma_f32_16x16x32_bf16 v[22:25], v[146:149], v[178:181], v[22:25]
	v_mfma_f32_16x16x32_bf16 v[22:25], v[150:153], v[182:185], v[22:25]
	v_mfma_f32_16x16x32_bf16 v[18:21], v[158:161], v[182:185], v[18:21]
	v_mfma_f32_16x16x32_bf16 v[18:21], v[154:157], v[178:181], v[18:21]
	v_mfma_f32_16x16x32_bf16 v[2:5], v[154:157], v[186:189], v[2:5]
	v_mfma_f32_16x16x32_bf16 v[2:5], v[158:161], v[190:193], v[2:5]
	v_mfma_f32_16x16x32_bf16 v[6:9], v[150:153], v[190:193], v[6:9]
	v_mfma_f32_16x16x32_bf16 v[6:9], v[146:149], v[186:189], v[6:9]
	s_setprio 0
	s_barrier
	s_mov_b32 m0, s40
	s_nop 0
	global_load_lds_dwordx4 v204, s[28:29]
	s_mov_b32 m0, s41
	s_nop 0
	global_load_lds_dwordx4 v206, s[28:29]
	ds_read_b128 v[130:133], v235 offset:32768
	ds_read_b128 v[134:137], v235 offset:33792
	ds_read_b128 v[138:141], v235 offset:34816
	ds_read_b128 v[142:145], v235 offset:35840
	ds_read_b128 v[146:149], v235 offset:49152
	ds_read_b128 v[150:153], v235 offset:50176
	ds_read_b128 v[154:157], v235 offset:51200
	ds_read_b128 v[158:161], v235 offset:52224
	ds_read_b128 v[162:165], v237 offset:32768
	ds_read_b128 v[166:169], v237 offset:33792
	ds_read_b128 v[170:173], v237 offset:34816
	ds_read_b128 v[174:177], v237 offset:35840
	ds_read_b128 v[178:181], v237 offset:36864
	ds_read_b128 v[182:185], v237 offset:37888
	ds_read_b128 v[186:189], v237 offset:38912
	ds_read_b128 v[190:193], v237 offset:39936
	s_add_i32 s56, 0, 0x18000
	s_add_i32 s57, 0, 0x1c000
	s_add_u32 s18, s28, 0x160000
	s_addc_u32 s19, s29, 0
	s_mov_b32 m0, s42
	s_nop 0
	global_load_lds_dwordx4 v204, s[18:19]
	s_mov_b32 m0, s43
	s_nop 0
	global_load_lds_dwordx4 v206, s[18:19]
	s_waitcnt vmcnt(8)
	s_waitcnt lgkmcnt(0)
	v_mfma_f32_16x16x32_bf16 v[126:129], v[130:133], v[162:165], v[126:129]
	v_mfma_f32_16x16x32_bf16 v[126:129], v[134:137], v[166:169], v[126:129]
	s_barrier
	s_setprio 1
	v_mfma_f32_16x16x32_bf16 v[122:125], v[142:145], v[166:169], v[122:125]
	v_mfma_f32_16x16x32_bf16 v[122:125], v[138:141], v[162:165], v[122:125]
	v_mfma_f32_16x16x32_bf16 v[106:109], v[138:141], v[170:173], v[106:109]
	v_mfma_f32_16x16x32_bf16 v[106:109], v[142:145], v[174:177], v[106:109]
	v_mfma_f32_16x16x32_bf16 v[110:113], v[134:137], v[174:177], v[110:113]
	v_mfma_f32_16x16x32_bf16 v[110:113], v[130:133], v[170:173], v[110:113]
	v_mfma_f32_16x16x32_bf16 v[94:97], v[130:133], v[178:181], v[94:97]
	v_mfma_f32_16x16x32_bf16 v[94:97], v[134:137], v[182:185], v[94:97]
	v_mfma_f32_16x16x32_bf16 v[90:93], v[142:145], v[182:185], v[90:93]
	v_mfma_f32_16x16x32_bf16 v[90:93], v[138:141], v[178:181], v[90:93]
	v_mfma_f32_16x16x32_bf16 v[74:77], v[138:141], v[186:189], v[74:77]
	v_mfma_f32_16x16x32_bf16 v[74:77], v[142:145], v[190:193], v[74:77]
	v_mfma_f32_16x16x32_bf16 v[78:81], v[134:137], v[190:193], v[78:81]
	v_mfma_f32_16x16x32_bf16 v[78:81], v[130:133], v[186:189], v[78:81]
	v_mfma_f32_16x16x32_bf16 v[118:121], v[146:149], v[162:165], v[118:121]
	v_mfma_f32_16x16x32_bf16 v[118:121], v[150:153], v[166:169], v[118:121]
	v_mfma_f32_16x16x32_bf16 v[114:117], v[158:161], v[166:169], v[114:117]
	v_mfma_f32_16x16x32_bf16 v[114:117], v[154:157], v[162:165], v[114:117]
	v_mfma_f32_16x16x32_bf16 v[98:101], v[154:157], v[170:173], v[98:101]
	v_mfma_f32_16x16x32_bf16 v[98:101], v[158:161], v[174:177], v[98:101]
	v_mfma_f32_16x16x32_bf16 v[102:105], v[150:153], v[174:177], v[102:105]
	v_mfma_f32_16x16x32_bf16 v[102:105], v[146:149], v[170:173], v[102:105]
	v_mfma_f32_16x16x32_bf16 v[86:89], v[146:149], v[178:181], v[86:89]
	v_mfma_f32_16x16x32_bf16 v[86:89], v[150:153], v[182:185], v[86:89]
	v_mfma_f32_16x16x32_bf16 v[82:85], v[158:161], v[182:185], v[82:85]
	v_mfma_f32_16x16x32_bf16 v[82:85], v[154:157], v[178:181], v[82:85]
	v_mfma_f32_16x16x32_bf16 v[66:69], v[154:157], v[186:189], v[66:69]
	v_mfma_f32_16x16x32_bf16 v[66:69], v[158:161], v[190:193], v[66:69]
	v_mfma_f32_16x16x32_bf16 v[70:73], v[150:153], v[190:193], v[70:73]
	v_mfma_f32_16x16x32_bf16 v[70:73], v[146:149], v[186:189], v[70:73]
	s_setprio 0
	s_barrier
	ds_read_b128 v[162:165], v237 offset:49152
	ds_read_b128 v[166:169], v237 offset:50176
	ds_read_b128 v[170:173], v237 offset:51200
	ds_read_b128 v[174:177], v237 offset:52224
	ds_read_b128 v[178:181], v237 offset:53248
	ds_read_b128 v[182:185], v237 offset:54272
	ds_read_b128 v[186:189], v237 offset:55296
	ds_read_b128 v[190:193], v237 offset:56320
	s_add_i32 s18, s56, s39
	s_add_u32 vcc_lo, s26, s94
	s_addc_u32 vcc_hi, s27, s95
	s_mov_b32 m0, s18
	s_nop 0
	global_load_lds_dwordx4 v194, vcc
	s_add_i32 m0, s18, 0x2000
	s_add_u32 s18, s26, 0x160080
	s_addc_u32 s19, s27, 0
	s_add_i32 s26, s57, s39
	global_load_lds_dwordx4 v208, vcc
	s_mov_b32 m0, s26
	s_nop 0
	global_load_lds_dwordx4 v194, s[18:19]
	s_add_i32 m0, s26, 0x2000
	s_nop 0
	global_load_lds_dwordx4 v208, s[18:19]
	s_waitcnt vmcnt(6)
	s_waitcnt lgkmcnt(0)
	v_mfma_f32_16x16x32_bf16 v[62:65], v[130:133], v[162:165], v[62:65]
	v_mfma_f32_16x16x32_bf16 v[62:65], v[134:137], v[166:169], v[62:65]
	s_barrier
	s_setprio 1
	v_mfma_f32_16x16x32_bf16 v[58:61], v[142:145], v[166:169], v[58:61]
	v_mfma_f32_16x16x32_bf16 v[58:61], v[138:141], v[162:165], v[58:61]
	v_mfma_f32_16x16x32_bf16 v[42:45], v[138:141], v[170:173], v[42:45]
	v_mfma_f32_16x16x32_bf16 v[42:45], v[142:145], v[174:177], v[42:45]
	v_mfma_f32_16x16x32_bf16 v[46:49], v[134:137], v[174:177], v[46:49]
	v_mfma_f32_16x16x32_bf16 v[46:49], v[130:133], v[170:173], v[46:49]
	v_mfma_f32_16x16x32_bf16 v[30:33], v[130:133], v[178:181], v[30:33]
	v_mfma_f32_16x16x32_bf16 v[30:33], v[134:137], v[182:185], v[30:33]
	v_mfma_f32_16x16x32_bf16 v[26:29], v[142:145], v[182:185], v[26:29]
	v_mfma_f32_16x16x32_bf16 v[26:29], v[138:141], v[178:181], v[26:29]
	v_mfma_f32_16x16x32_bf16 v[10:13], v[138:141], v[186:189], v[10:13]
	v_mfma_f32_16x16x32_bf16 v[10:13], v[142:145], v[190:193], v[10:13]
	s_add_u32 s23, s23, 0x100
	v_mfma_f32_16x16x32_bf16 v[14:17], v[134:137], v[190:193], v[14:17]
	v_mfma_f32_16x16x32_bf16 v[14:17], v[130:133], v[186:189], v[14:17]
	s_addc_u32 s54, s54, 0
	v_mfma_f32_16x16x32_bf16 v[54:57], v[146:149], v[162:165], v[54:57]
	v_mfma_f32_16x16x32_bf16 v[54:57], v[150:153], v[166:169], v[54:57]
	s_cmp_ge_i32 s55, s21
	v_mfma_f32_16x16x32_bf16 v[50:53], v[158:161], v[166:169], v[50:53]
	v_mfma_f32_16x16x32_bf16 v[50:53], v[154:157], v[162:165], v[50:53]
	s_mov_b64 s[18:19], s[24:25]
	v_mfma_f32_16x16x32_bf16 v[34:37], v[154:157], v[170:173], v[34:37]
	v_mfma_f32_16x16x32_bf16 v[34:37], v[158:161], v[174:177], v[34:37]
	s_mov_b32 s26, s55
	v_mfma_f32_16x16x32_bf16 v[38:41], v[150:153], v[174:177], v[38:41]
	v_mfma_f32_16x16x32_bf16 v[38:41], v[146:149], v[170:173], v[38:41]
	v_mfma_f32_16x16x32_bf16 v[22:25], v[146:149], v[178:181], v[22:25]
	v_mfma_f32_16x16x32_bf16 v[22:25], v[150:153], v[182:185], v[22:25]
	v_mfma_f32_16x16x32_bf16 v[18:21], v[158:161], v[182:185], v[18:21]
	v_mfma_f32_16x16x32_bf16 v[18:21], v[154:157], v[178:181], v[18:21]
	v_mfma_f32_16x16x32_bf16 v[2:5], v[154:157], v[186:189], v[2:5]
	v_mfma_f32_16x16x32_bf16 v[2:5], v[158:161], v[190:193], v[2:5]
	v_mfma_f32_16x16x32_bf16 v[6:9], v[150:153], v[190:193], v[6:9]
	v_mfma_f32_16x16x32_bf16 v[6:9], v[146:149], v[186:189], v[6:9]
	s_setprio 0
	s_barrier
	s_cbranch_scc0 .LBB0_1511
	s_and_b64 vcc, exec, s[12:13]
	s_cbranch_vccz .LBB0_1514
